# plus sample-attention P.V stage rewritten by hand (lane owns 2 value columns x 16 queries, rolling ds_read_b64 score pipeline, 16-row-deep value prefetch, no per-read LDS waits)
# speedup vs baseline: 1.0118x; 1.0118x over previous
; __device__ __forceinline__ float bflo(unsigned w) { return __uint_as_float(w << 16); }
; __device__ __forceinline__ float bfhi(unsigned w) { return __uint_as_float(w & 0xffff0000u); }
; template <int BR>
; __device__ __forceinline__ void sample_unit(const SampP& P, int bs, int h, char* lds, float lam) {
;     ...
;   { const int hf = lane >> 5, l31 = lane & 31;
;     f32x4 acc[16];
; #pragma unroll
;     for (int q = 0; q < 16; ++q) acc[q] = (f32x4){0.f, 0.f, 0.f, 0.f};
; #pragma unroll 1
;     for (int k5 = 0; k5 < 13; ++k5) { const int keyb = 130 * wid + 10 * k5 + hf;
;       f32x4 v[5];
; #pragma unroll
;       for (int e = 0; e < 5; ++e) { const int key = keyb + 2 * e;
;         if (key < PAST) v[e] = *(const f32x4*)(Vc + (size_t)key * 1024 + 4 * l31);
;         else { const u32x2 w = *(const u32x2*)(Vn + (size_t)(key - PAST) * 1024 + 4 * l31); v[e] = (f32x4){bflo(w.x), bfhi(w.x), bflo(w.y), bfhi(w.y)}; } }
; #pragma unroll
;       for (int e = 0; e < 5; ++e) { const float* sp = S1 + keyb + 2 * e;
; #pragma unroll
;         for (int q = 0; q < 16; ++q) acc[q] += sp[q * SST] * v[e];
;         asm volatile("" ::: "memory"); }
;     }
.LBB0_613:
	s_or_b64 exec, exec, s[0:1]
	s_mov_b64 exec, -1
	v_and_b32_e32 v141, 63, v1
	v_lshlrev_b32_e32 v132, 3, v141
	v_lshlrev_b32_e32 v142, 2, v141
	v_readlane_b32 s14, v251, 21
	v_readlane_b32 s0, v251, 13
	v_readlane_b32 s1, v251, 14
	s_nop 3
	s_lshl_b32 s2, s91, 22
	s_add_u32 s0, s0, s2
	s_addc_u32 s1, s1, 0
	s_lshl_b32 s2, s92, 9
	s_add_u32 s0, s0, s2
	s_addc_u32 s1, s1, 0
	s_lshl_b32 s2, s14, 19
	s_add_u32 s0, s0, s2
	s_addc_u32 s1, s1, 0
	s_add_u32 s0, s0, 0x800
	s_addc_u32 s1, s1, 0
	v_mov_b32_e32 v134, s0
	v_mov_b32_e32 v135, s1
	v_add_co_u32_e32 v134, vcc, v134, v132
	s_nop 1
	v_addc_co_u32_e32 v135, vcc, 0, v135, vcc
	v_readlane_b32 s0, v251, 26
	v_readlane_b32 s1, v251, 27
	s_nop 3
	s_add_u32 s0, s0, 0x1a000000
	s_addc_u32 s1, s1, 0
	s_lshl_b32 s2, s91, 15
	s_add_u32 s0, s0, s2
	s_addc_u32 s1, s1, 0
	s_lshl_b32 s2, s14, 12
	s_add_u32 s0, s0, s2
	s_addc_u32 s1, s1, 0
	s_lshl_b32 s2, s92, 8
	s_add_u32 s0, s0, s2
	s_addc_u32 s1, s1, 0
	v_mov_b32_e32 v136, s0
	v_mov_b32_e32 v137, s1
	v_add_co_u32_e32 v136, vcc, v136, v142
	s_nop 1
	v_addc_co_u32_e32 v137, vcc, 0, v137, vcc
	v_mov_b32_e32 v141, s14
	v_lshlrev_b32_e32 v138, 9, v141
	v_lshlrev_b32_e32 v139, 3, v141
	v_add_u32_e32 v139, 0x1000, v139
	v_lshlrev_b32_e32 v140, 13, v141
	v_add_u32_e32 v140, 0x10800, v140
	v_add_u32_e32 v140, v140, v132
	s_mov_b64 s[0:1], 0x2000
	global_load_dwordx2 v[100:101], v[134:135], off offset:-2048
	global_load_dwordx2 v[102:103], v[134:135], off offset:2048
	v_lshl_add_u64 v[134:135], v[134:135], 0, s[0:1]
	global_load_dwordx2 v[104:105], v[134:135], off offset:-2048
	global_load_dwordx2 v[106:107], v[134:135], off offset:2048
	v_lshl_add_u64 v[134:135], v[134:135], 0, s[0:1]
	global_load_dwordx2 v[108:109], v[134:135], off offset:-2048
	global_load_dwordx2 v[110:111], v[134:135], off offset:2048
	v_lshl_add_u64 v[134:135], v[134:135], 0, s[0:1]
	global_load_dwordx2 v[112:113], v[134:135], off offset:-2048
	global_load_dwordx2 v[114:115], v[134:135], off offset:2048
	v_lshl_add_u64 v[134:135], v[134:135], 0, s[0:1]
	global_load_dwordx2 v[116:117], v[134:135], off offset:-2048
	global_load_dwordx2 v[118:119], v[134:135], off offset:2048
	v_lshl_add_u64 v[134:135], v[134:135], 0, s[0:1]
	global_load_dwordx2 v[120:121], v[134:135], off offset:-2048
	global_load_dwordx2 v[122:123], v[134:135], off offset:2048
	v_lshl_add_u64 v[134:135], v[134:135], 0, s[0:1]
	global_load_dwordx2 v[124:125], v[134:135], off offset:-2048
	global_load_dwordx2 v[126:127], v[134:135], off offset:2048
	v_lshl_add_u64 v[134:135], v[134:135], 0, s[0:1]
	global_load_dwordx2 v[128:129], v[134:135], off offset:-2048
	global_load_dwordx2 v[130:131], v[134:135], off offset:2048
	v_lshl_add_u64 v[134:135], v[134:135], 0, s[0:1]
	v_mov_b32_e32 v2, 0
	v_mov_b32_e32 v3, 0
	v_mov_b32_e32 v4, 0
	v_mov_b32_e32 v5, 0
	v_mov_b32_e32 v6, 0
	v_mov_b32_e32 v7, 0
	v_mov_b32_e32 v8, 0
	v_mov_b32_e32 v9, 0
	v_mov_b32_e32 v10, 0
	v_mov_b32_e32 v11, 0
	v_mov_b32_e32 v12, 0
	v_mov_b32_e32 v13, 0
	v_mov_b32_e32 v14, 0
	v_mov_b32_e32 v15, 0
	v_mov_b32_e32 v16, 0
	v_mov_b32_e32 v17, 0
	v_mov_b32_e32 v18, 0
	v_mov_b32_e32 v19, 0
	v_mov_b32_e32 v20, 0
	v_mov_b32_e32 v21, 0
	v_mov_b32_e32 v22, 0
	v_mov_b32_e32 v23, 0
	v_mov_b32_e32 v24, 0
	v_mov_b32_e32 v25, 0
	v_mov_b32_e32 v26, 0
	v_mov_b32_e32 v27, 0
	v_mov_b32_e32 v28, 0
	v_mov_b32_e32 v29, 0
	v_mov_b32_e32 v30, 0
	v_mov_b32_e32 v31, 0
	v_mov_b32_e32 v32, 0
	v_mov_b32_e32 v33, 0
	s_waitcnt lgkmcnt(0)
	s_barrier
	ds_read_b64 v[34:35], v138 offset:0
	ds_read_b64 v[36:37], v138 offset:4224
	ds_read_b64 v[38:39], v138 offset:8448
	ds_read_b64 v[40:41], v138 offset:12672
	ds_read_b64 v[42:43], v138 offset:16896
	ds_read_b64 v[44:45], v138 offset:21120
	ds_read_b64 v[46:47], v138 offset:25344
	ds_read_b64 v[48:49], v138 offset:29568
	ds_read_b64 v[84:85], v138 offset:33792
	ds_read_b64 v[86:87], v138 offset:38016
	ds_read_b64 v[88:89], v138 offset:42240
	ds_read_b64 v[90:91], v138 offset:46464
	ds_read_b64 v[92:93], v138 offset:50688
	ds_read_b64 v[94:95], v138 offset:54912
	ds_read_b64 v[96:97], v138 offset:59136
	ds_read_b64 v[98:99], v138 offset:63360
	s_mov_b32 s2, 0
.Lpvf_loop:
	s_waitcnt vmcnt(14)
	s_waitcnt lgkmcnt(15)
	v_pk_fma_f32 v[2:3], v[34:35], v[100:101], v[2:3] op_sel_hi:[0,1,1]
	v_pk_fma_f32 v[2:3], v[34:35], v[102:103], v[2:3] op_sel:[1,0,0] op_sel_hi:[1,1,1]
	ds_read_b64 v[34:35], v138 offset:8
	s_waitcnt lgkmcnt(15)
	v_pk_fma_f32 v[4:5], v[36:37], v[100:101], v[4:5] op_sel_hi:[0,1,1]
	v_pk_fma_f32 v[4:5], v[36:37], v[102:103], v[4:5] op_sel:[1,0,0] op_sel_hi:[1,1,1]
	ds_read_b64 v[36:37], v138 offset:4232
	s_waitcnt lgkmcnt(15)
	v_pk_fma_f32 v[6:7], v[38:39], v[100:101], v[6:7] op_sel_hi:[0,1,1]
	v_pk_fma_f32 v[6:7], v[38:39], v[102:103], v[6:7] op_sel:[1,0,0] op_sel_hi:[1,1,1]
	ds_read_b64 v[38:39], v138 offset:8456
	s_waitcnt lgkmcnt(15)
	v_pk_fma_f32 v[8:9], v[40:41], v[100:101], v[8:9] op_sel_hi:[0,1,1]
	v_pk_fma_f32 v[8:9], v[40:41], v[102:103], v[8:9] op_sel:[1,0,0] op_sel_hi:[1,1,1]
	ds_read_b64 v[40:41], v138 offset:12680
	s_waitcnt lgkmcnt(15)
	v_pk_fma_f32 v[10:11], v[42:43], v[100:101], v[10:11] op_sel_hi:[0,1,1]
	v_pk_fma_f32 v[10:11], v[42:43], v[102:103], v[10:11] op_sel:[1,0,0] op_sel_hi:[1,1,1]
	ds_read_b64 v[42:43], v138 offset:16904
	s_waitcnt lgkmcnt(15)
	v_pk_fma_f32 v[12:13], v[44:45], v[100:101], v[12:13] op_sel_hi:[0,1,1]
	v_pk_fma_f32 v[12:13], v[44:45], v[102:103], v[12:13] op_sel:[1,0,0] op_sel_hi:[1,1,1]
	ds_read_b64 v[44:45], v138 offset:21128
	s_waitcnt lgkmcnt(15)
	v_pk_fma_f32 v[14:15], v[46:47], v[100:101], v[14:15] op_sel_hi:[0,1,1]
	v_pk_fma_f32 v[14:15], v[46:47], v[102:103], v[14:15] op_sel:[1,0,0] op_sel_hi:[1,1,1]
	ds_read_b64 v[46:47], v138 offset:25352
	s_waitcnt lgkmcnt(15)
; __device__ __forceinline__ float bflo(unsigned w) { return __uint_as_float(w << 16); }
; __device__ __forceinline__ float bfhi(unsigned w) { return __uint_as_float(w & 0xffff0000u); }
; template <int BR>
; __device__ __forceinline__ void sample_unit(const SampP& P, int bs, int h, char* lds, float lam) {
;     ...
; #pragma unroll 1
;     for (int k5 = 0; k5 < 13; ++k5) { const int keyb = 130 * wid + 10 * k5 + hf;
;       f32x4 v[5];
; #pragma unroll
;       for (int e = 0; e < 5; ++e) { const int key = keyb + 2 * e;
;         if (key < PAST) v[e] = *(const f32x4*)(Vc + (size_t)key * 1024 + 4 * l31);
;         else { const u32x2 w = *(const u32x2*)(Vn + (size_t)(key - PAST) * 1024 + 4 * l31); v[e] = (f32x4){bflo(w.x), bfhi(w.x), bflo(w.y), bfhi(w.y)}; } }
; #pragma unroll
;       for (int e = 0; e < 5; ++e) { const float* sp = S1 + keyb + 2 * e;
; #pragma unroll
;         for (int q = 0; q < 16; ++q) acc[q] += sp[q * SST] * v[e];
;         asm volatile("" ::: "memory"); }
	v_pk_fma_f32 v[16:17], v[48:49], v[100:101], v[16:17] op_sel_hi:[0,1,1]
	v_pk_fma_f32 v[16:17], v[48:49], v[102:103], v[16:17] op_sel:[1,0,0] op_sel_hi:[1,1,1]
	ds_read_b64 v[48:49], v138 offset:29576
	s_waitcnt lgkmcnt(15)
	v_pk_fma_f32 v[18:19], v[84:85], v[100:101], v[18:19] op_sel_hi:[0,1,1]
	v_pk_fma_f32 v[18:19], v[84:85], v[102:103], v[18:19] op_sel:[1,0,0] op_sel_hi:[1,1,1]
	ds_read_b64 v[84:85], v138 offset:33800
	s_waitcnt lgkmcnt(15)
	v_pk_fma_f32 v[20:21], v[86:87], v[100:101], v[20:21] op_sel_hi:[0,1,1]
	v_pk_fma_f32 v[20:21], v[86:87], v[102:103], v[20:21] op_sel:[1,0,0] op_sel_hi:[1,1,1]
	ds_read_b64 v[86:87], v138 offset:38024
	s_waitcnt lgkmcnt(15)
	v_pk_fma_f32 v[22:23], v[88:89], v[100:101], v[22:23] op_sel_hi:[0,1,1]
	v_pk_fma_f32 v[22:23], v[88:89], v[102:103], v[22:23] op_sel:[1,0,0] op_sel_hi:[1,1,1]
	ds_read_b64 v[88:89], v138 offset:42248
	s_waitcnt lgkmcnt(15)
	v_pk_fma_f32 v[24:25], v[90:91], v[100:101], v[24:25] op_sel_hi:[0,1,1]
	v_pk_fma_f32 v[24:25], v[90:91], v[102:103], v[24:25] op_sel:[1,0,0] op_sel_hi:[1,1,1]
	ds_read_b64 v[90:91], v138 offset:46472
	s_waitcnt lgkmcnt(15)
	v_pk_fma_f32 v[26:27], v[92:93], v[100:101], v[26:27] op_sel_hi:[0,1,1]
	v_pk_fma_f32 v[26:27], v[92:93], v[102:103], v[26:27] op_sel:[1,0,0] op_sel_hi:[1,1,1]
	ds_read_b64 v[92:93], v138 offset:50696
	s_waitcnt lgkmcnt(15)
	v_pk_fma_f32 v[28:29], v[94:95], v[100:101], v[28:29] op_sel_hi:[0,1,1]
	v_pk_fma_f32 v[28:29], v[94:95], v[102:103], v[28:29] op_sel:[1,0,0] op_sel_hi:[1,1,1]
	ds_read_b64 v[94:95], v138 offset:54920
	s_waitcnt lgkmcnt(15)
	v_pk_fma_f32 v[30:31], v[96:97], v[100:101], v[30:31] op_sel_hi:[0,1,1]
	v_pk_fma_f32 v[30:31], v[96:97], v[102:103], v[30:31] op_sel:[1,0,0] op_sel_hi:[1,1,1]
	ds_read_b64 v[96:97], v138 offset:59144
	s_waitcnt lgkmcnt(15)
	v_pk_fma_f32 v[32:33], v[98:99], v[100:101], v[32:33] op_sel_hi:[0,1,1]
	v_pk_fma_f32 v[32:33], v[98:99], v[102:103], v[32:33] op_sel:[1,0,0] op_sel_hi:[1,1,1]
	ds_read_b64 v[98:99], v138 offset:63368
	global_load_dwordx2 v[100:101], v[134:135], off offset:-2048
	global_load_dwordx2 v[102:103], v[134:135], off offset:2048
	v_lshl_add_u64 v[134:135], v[134:135], 0, s[0:1]
	s_waitcnt vmcnt(14)
	s_waitcnt lgkmcnt(15)
	v_pk_fma_f32 v[2:3], v[34:35], v[104:105], v[2:3] op_sel_hi:[0,1,1]
	v_pk_fma_f32 v[2:3], v[34:35], v[106:107], v[2:3] op_sel:[1,0,0] op_sel_hi:[1,1,1]
	ds_read_b64 v[34:35], v138 offset:16
	s_waitcnt lgkmcnt(15)
	v_pk_fma_f32 v[4:5], v[36:37], v[104:105], v[4:5] op_sel_hi:[0,1,1]
	v_pk_fma_f32 v[4:5], v[36:37], v[106:107], v[4:5] op_sel:[1,0,0] op_sel_hi:[1,1,1]
	ds_read_b64 v[36:37], v138 offset:4240
	s_waitcnt lgkmcnt(15)
	v_pk_fma_f32 v[6:7], v[38:39], v[104:105], v[6:7] op_sel_hi:[0,1,1]
	v_pk_fma_f32 v[6:7], v[38:39], v[106:107], v[6:7] op_sel:[1,0,0] op_sel_hi:[1,1,1]
	ds_read_b64 v[38:39], v138 offset:8464
	s_waitcnt lgkmcnt(15)
	v_pk_fma_f32 v[8:9], v[40:41], v[104:105], v[8:9] op_sel_hi:[0,1,1]
	v_pk_fma_f32 v[8:9], v[40:41], v[106:107], v[8:9] op_sel:[1,0,0] op_sel_hi:[1,1,1]
	ds_read_b64 v[40:41], v138 offset:12688
	s_waitcnt lgkmcnt(15)
	v_pk_fma_f32 v[10:11], v[42:43], v[104:105], v[10:11] op_sel_hi:[0,1,1]
	v_pk_fma_f32 v[10:11], v[42:43], v[106:107], v[10:11] op_sel:[1,0,0] op_sel_hi:[1,1,1]
	ds_read_b64 v[42:43], v138 offset:16912
	s_waitcnt lgkmcnt(15)
	v_pk_fma_f32 v[12:13], v[44:45], v[104:105], v[12:13] op_sel_hi:[0,1,1]
	v_pk_fma_f32 v[12:13], v[44:45], v[106:107], v[12:13] op_sel:[1,0,0] op_sel_hi:[1,1,1]
	ds_read_b64 v[44:45], v138 offset:21136
	s_waitcnt lgkmcnt(15)
	v_pk_fma_f32 v[14:15], v[46:47], v[104:105], v[14:15] op_sel_hi:[0,1,1]
	v_pk_fma_f32 v[14:15], v[46:47], v[106:107], v[14:15] op_sel:[1,0,0] op_sel_hi:[1,1,1]
	ds_read_b64 v[46:47], v138 offset:25360
	s_waitcnt lgkmcnt(15)
	v_pk_fma_f32 v[16:17], v[48:49], v[104:105], v[16:17] op_sel_hi:[0,1,1]
	v_pk_fma_f32 v[16:17], v[48:49], v[106:107], v[16:17] op_sel:[1,0,0] op_sel_hi:[1,1,1]
	ds_read_b64 v[48:49], v138 offset:29584
	s_waitcnt lgkmcnt(15)
	v_pk_fma_f32 v[18:19], v[84:85], v[104:105], v[18:19] op_sel_hi:[0,1,1]
	v_pk_fma_f32 v[18:19], v[84:85], v[106:107], v[18:19] op_sel:[1,0,0] op_sel_hi:[1,1,1]
	ds_read_b64 v[84:85], v138 offset:33808
	s_waitcnt lgkmcnt(15)
	v_pk_fma_f32 v[20:21], v[86:87], v[104:105], v[20:21] op_sel_hi:[0,1,1]
	v_pk_fma_f32 v[20:21], v[86:87], v[106:107], v[20:21] op_sel:[1,0,0] op_sel_hi:[1,1,1]
	ds_read_b64 v[86:87], v138 offset:38032
	s_waitcnt lgkmcnt(15)
	v_pk_fma_f32 v[22:23], v[88:89], v[104:105], v[22:23] op_sel_hi:[0,1,1]
	v_pk_fma_f32 v[22:23], v[88:89], v[106:107], v[22:23] op_sel:[1,0,0] op_sel_hi:[1,1,1]
	ds_read_b64 v[88:89], v138 offset:42256
	s_waitcnt lgkmcnt(15)
	v_pk_fma_f32 v[24:25], v[90:91], v[104:105], v[24:25] op_sel_hi:[0,1,1]
	v_pk_fma_f32 v[24:25], v[90:91], v[106:107], v[24:25] op_sel:[1,0,0] op_sel_hi:[1,1,1]
	ds_read_b64 v[90:91], v138 offset:46480
	s_waitcnt lgkmcnt(15)
	v_pk_fma_f32 v[26:27], v[92:93], v[104:105], v[26:27] op_sel_hi:[0,1,1]
	v_pk_fma_f32 v[26:27], v[92:93], v[106:107], v[26:27] op_sel:[1,0,0] op_sel_hi:[1,1,1]
	ds_read_b64 v[92:93], v138 offset:50704
	s_waitcnt lgkmcnt(15)
	v_pk_fma_f32 v[28:29], v[94:95], v[104:105], v[28:29] op_sel_hi:[0,1,1]
	v_pk_fma_f32 v[28:29], v[94:95], v[106:107], v[28:29] op_sel:[1,0,0] op_sel_hi:[1,1,1]
	ds_read_b64 v[94:95], v138 offset:54928
	s_waitcnt lgkmcnt(15)
	v_pk_fma_f32 v[30:31], v[96:97], v[104:105], v[30:31] op_sel_hi:[0,1,1]
	v_pk_fma_f32 v[30:31], v[96:97], v[106:107], v[30:31] op_sel:[1,0,0] op_sel_hi:[1,1,1]
	ds_read_b64 v[96:97], v138 offset:59152
	s_waitcnt lgkmcnt(15)
; __device__ __forceinline__ float bflo(unsigned w) { return __uint_as_float(w << 16); }
; __device__ __forceinline__ float bfhi(unsigned w) { return __uint_as_float(w & 0xffff0000u); }
; template <int BR>
; __device__ __forceinline__ void sample_unit(const SampP& P, int bs, int h, char* lds, float lam) {
;     ...
; #pragma unroll 1
;     for (int k5 = 0; k5 < 13; ++k5) { const int keyb = 130 * wid + 10 * k5 + hf;
;       f32x4 v[5];
; #pragma unroll
;       for (int e = 0; e < 5; ++e) { const int key = keyb + 2 * e;
;         if (key < PAST) v[e] = *(const f32x4*)(Vc + (size_t)key * 1024 + 4 * l31);
;         else { const u32x2 w = *(const u32x2*)(Vn + (size_t)(key - PAST) * 1024 + 4 * l31); v[e] = (f32x4){bflo(w.x), bfhi(w.x), bflo(w.y), bfhi(w.y)}; } }
; #pragma unroll
;       for (int e = 0; e < 5; ++e) { const float* sp = S1 + keyb + 2 * e;
; #pragma unroll
;         for (int q = 0; q < 16; ++q) acc[q] += sp[q * SST] * v[e];
;         asm volatile("" ::: "memory"); }
	v_pk_fma_f32 v[32:33], v[98:99], v[104:105], v[32:33] op_sel_hi:[0,1,1]
	v_pk_fma_f32 v[32:33], v[98:99], v[106:107], v[32:33] op_sel:[1,0,0] op_sel_hi:[1,1,1]
	ds_read_b64 v[98:99], v138 offset:63376
	global_load_dwordx2 v[104:105], v[134:135], off offset:-2048
	global_load_dwordx2 v[106:107], v[134:135], off offset:2048
	v_lshl_add_u64 v[134:135], v[134:135], 0, s[0:1]
	s_waitcnt vmcnt(14)
	s_waitcnt lgkmcnt(15)
	v_pk_fma_f32 v[2:3], v[34:35], v[108:109], v[2:3] op_sel_hi:[0,1,1]
	v_pk_fma_f32 v[2:3], v[34:35], v[110:111], v[2:3] op_sel:[1,0,0] op_sel_hi:[1,1,1]
	ds_read_b64 v[34:35], v138 offset:24
	s_waitcnt lgkmcnt(15)
	v_pk_fma_f32 v[4:5], v[36:37], v[108:109], v[4:5] op_sel_hi:[0,1,1]
	v_pk_fma_f32 v[4:5], v[36:37], v[110:111], v[4:5] op_sel:[1,0,0] op_sel_hi:[1,1,1]
	ds_read_b64 v[36:37], v138 offset:4248
	s_waitcnt lgkmcnt(15)
	v_pk_fma_f32 v[6:7], v[38:39], v[108:109], v[6:7] op_sel_hi:[0,1,1]
	v_pk_fma_f32 v[6:7], v[38:39], v[110:111], v[6:7] op_sel:[1,0,0] op_sel_hi:[1,1,1]
	ds_read_b64 v[38:39], v138 offset:8472
	s_waitcnt lgkmcnt(15)
	v_pk_fma_f32 v[8:9], v[40:41], v[108:109], v[8:9] op_sel_hi:[0,1,1]
	v_pk_fma_f32 v[8:9], v[40:41], v[110:111], v[8:9] op_sel:[1,0,0] op_sel_hi:[1,1,1]
	ds_read_b64 v[40:41], v138 offset:12696
	s_waitcnt lgkmcnt(15)
	v_pk_fma_f32 v[10:11], v[42:43], v[108:109], v[10:11] op_sel_hi:[0,1,1]
	v_pk_fma_f32 v[10:11], v[42:43], v[110:111], v[10:11] op_sel:[1,0,0] op_sel_hi:[1,1,1]
	ds_read_b64 v[42:43], v138 offset:16920
	s_waitcnt lgkmcnt(15)
	v_pk_fma_f32 v[12:13], v[44:45], v[108:109], v[12:13] op_sel_hi:[0,1,1]
	v_pk_fma_f32 v[12:13], v[44:45], v[110:111], v[12:13] op_sel:[1,0,0] op_sel_hi:[1,1,1]
	ds_read_b64 v[44:45], v138 offset:21144
	s_waitcnt lgkmcnt(15)
	v_pk_fma_f32 v[14:15], v[46:47], v[108:109], v[14:15] op_sel_hi:[0,1,1]
	v_pk_fma_f32 v[14:15], v[46:47], v[110:111], v[14:15] op_sel:[1,0,0] op_sel_hi:[1,1,1]
	ds_read_b64 v[46:47], v138 offset:25368
	s_waitcnt lgkmcnt(15)
	v_pk_fma_f32 v[16:17], v[48:49], v[108:109], v[16:17] op_sel_hi:[0,1,1]
	v_pk_fma_f32 v[16:17], v[48:49], v[110:111], v[16:17] op_sel:[1,0,0] op_sel_hi:[1,1,1]
	ds_read_b64 v[48:49], v138 offset:29592
	s_waitcnt lgkmcnt(15)
	v_pk_fma_f32 v[18:19], v[84:85], v[108:109], v[18:19] op_sel_hi:[0,1,1]
	v_pk_fma_f32 v[18:19], v[84:85], v[110:111], v[18:19] op_sel:[1,0,0] op_sel_hi:[1,1,1]
	ds_read_b64 v[84:85], v138 offset:33816
	s_waitcnt lgkmcnt(15)
	v_pk_fma_f32 v[20:21], v[86:87], v[108:109], v[20:21] op_sel_hi:[0,1,1]
	v_pk_fma_f32 v[20:21], v[86:87], v[110:111], v[20:21] op_sel:[1,0,0] op_sel_hi:[1,1,1]
	ds_read_b64 v[86:87], v138 offset:38040
	s_waitcnt lgkmcnt(15)
	v_pk_fma_f32 v[22:23], v[88:89], v[108:109], v[22:23] op_sel_hi:[0,1,1]
	v_pk_fma_f32 v[22:23], v[88:89], v[110:111], v[22:23] op_sel:[1,0,0] op_sel_hi:[1,1,1]
	ds_read_b64 v[88:89], v138 offset:42264
	s_waitcnt lgkmcnt(15)
	v_pk_fma_f32 v[24:25], v[90:91], v[108:109], v[24:25] op_sel_hi:[0,1,1]
	v_pk_fma_f32 v[24:25], v[90:91], v[110:111], v[24:25] op_sel:[1,0,0] op_sel_hi:[1,1,1]
	ds_read_b64 v[90:91], v138 offset:46488
	s_waitcnt lgkmcnt(15)
	v_pk_fma_f32 v[26:27], v[92:93], v[108:109], v[26:27] op_sel_hi:[0,1,1]
	v_pk_fma_f32 v[26:27], v[92:93], v[110:111], v[26:27] op_sel:[1,0,0] op_sel_hi:[1,1,1]
	ds_read_b64 v[92:93], v138 offset:50712
	s_waitcnt lgkmcnt(15)
	v_pk_fma_f32 v[28:29], v[94:95], v[108:109], v[28:29] op_sel_hi:[0,1,1]
	v_pk_fma_f32 v[28:29], v[94:95], v[110:111], v[28:29] op_sel:[1,0,0] op_sel_hi:[1,1,1]
	ds_read_b64 v[94:95], v138 offset:54936
	s_waitcnt lgkmcnt(15)
	v_pk_fma_f32 v[30:31], v[96:97], v[108:109], v[30:31] op_sel_hi:[0,1,1]
	v_pk_fma_f32 v[30:31], v[96:97], v[110:111], v[30:31] op_sel:[1,0,0] op_sel_hi:[1,1,1]
	ds_read_b64 v[96:97], v138 offset:59160
	s_waitcnt lgkmcnt(15)
	v_pk_fma_f32 v[32:33], v[98:99], v[108:109], v[32:33] op_sel_hi:[0,1,1]
	v_pk_fma_f32 v[32:33], v[98:99], v[110:111], v[32:33] op_sel:[1,0,0] op_sel_hi:[1,1,1]
	ds_read_b64 v[98:99], v138 offset:63384
	global_load_dwordx2 v[108:109], v[134:135], off offset:-2048
	global_load_dwordx2 v[110:111], v[134:135], off offset:2048
	v_lshl_add_u64 v[134:135], v[134:135], 0, s[0:1]
	s_waitcnt vmcnt(14)
	s_waitcnt lgkmcnt(15)
	v_pk_fma_f32 v[2:3], v[34:35], v[112:113], v[2:3] op_sel_hi:[0,1,1]
	v_pk_fma_f32 v[2:3], v[34:35], v[114:115], v[2:3] op_sel:[1,0,0] op_sel_hi:[1,1,1]
	ds_read_b64 v[34:35], v138 offset:32
	s_waitcnt lgkmcnt(15)
	v_pk_fma_f32 v[4:5], v[36:37], v[112:113], v[4:5] op_sel_hi:[0,1,1]
	v_pk_fma_f32 v[4:5], v[36:37], v[114:115], v[4:5] op_sel:[1,0,0] op_sel_hi:[1,1,1]
	ds_read_b64 v[36:37], v138 offset:4256
	s_waitcnt lgkmcnt(15)
	v_pk_fma_f32 v[6:7], v[38:39], v[112:113], v[6:7] op_sel_hi:[0,1,1]
	v_pk_fma_f32 v[6:7], v[38:39], v[114:115], v[6:7] op_sel:[1,0,0] op_sel_hi:[1,1,1]
	ds_read_b64 v[38:39], v138 offset:8480
	s_waitcnt lgkmcnt(15)
	v_pk_fma_f32 v[8:9], v[40:41], v[112:113], v[8:9] op_sel_hi:[0,1,1]
	v_pk_fma_f32 v[8:9], v[40:41], v[114:115], v[8:9] op_sel:[1,0,0] op_sel_hi:[1,1,1]
	ds_read_b64 v[40:41], v138 offset:12704
	s_waitcnt lgkmcnt(15)
	v_pk_fma_f32 v[10:11], v[42:43], v[112:113], v[10:11] op_sel_hi:[0,1,1]
	v_pk_fma_f32 v[10:11], v[42:43], v[114:115], v[10:11] op_sel:[1,0,0] op_sel_hi:[1,1,1]
	ds_read_b64 v[42:43], v138 offset:16928
	s_waitcnt lgkmcnt(15)
	v_pk_fma_f32 v[12:13], v[44:45], v[112:113], v[12:13] op_sel_hi:[0,1,1]
	v_pk_fma_f32 v[12:13], v[44:45], v[114:115], v[12:13] op_sel:[1,0,0] op_sel_hi:[1,1,1]
	ds_read_b64 v[44:45], v138 offset:21152
	s_waitcnt lgkmcnt(15)
	v_pk_fma_f32 v[14:15], v[46:47], v[112:113], v[14:15] op_sel_hi:[0,1,1]
	v_pk_fma_f32 v[14:15], v[46:47], v[114:115], v[14:15] op_sel:[1,0,0] op_sel_hi:[1,1,1]
	ds_read_b64 v[46:47], v138 offset:25376
	s_waitcnt lgkmcnt(15)
; __device__ __forceinline__ float bflo(unsigned w) { return __uint_as_float(w << 16); }
; __device__ __forceinline__ float bfhi(unsigned w) { return __uint_as_float(w & 0xffff0000u); }
; template <int BR>
; __device__ __forceinline__ void sample_unit(const SampP& P, int bs, int h, char* lds, float lam) {
;     ...
; #pragma unroll 1
;     for (int k5 = 0; k5 < 13; ++k5) { const int keyb = 130 * wid + 10 * k5 + hf;
;       f32x4 v[5];
; #pragma unroll
;       for (int e = 0; e < 5; ++e) { const int key = keyb + 2 * e;
;         if (key < PAST) v[e] = *(const f32x4*)(Vc + (size_t)key * 1024 + 4 * l31);
;         else { const u32x2 w = *(const u32x2*)(Vn + (size_t)(key - PAST) * 1024 + 4 * l31); v[e] = (f32x4){bflo(w.x), bfhi(w.x), bflo(w.y), bfhi(w.y)}; } }
; #pragma unroll
;       for (int e = 0; e < 5; ++e) { const float* sp = S1 + keyb + 2 * e;
; #pragma unroll
;         for (int q = 0; q < 16; ++q) acc[q] += sp[q * SST] * v[e];
;         asm volatile("" ::: "memory"); }
	v_pk_fma_f32 v[16:17], v[48:49], v[112:113], v[16:17] op_sel_hi:[0,1,1]
	v_pk_fma_f32 v[16:17], v[48:49], v[114:115], v[16:17] op_sel:[1,0,0] op_sel_hi:[1,1,1]
	ds_read_b64 v[48:49], v138 offset:29600
	s_waitcnt lgkmcnt(15)
	v_pk_fma_f32 v[18:19], v[84:85], v[112:113], v[18:19] op_sel_hi:[0,1,1]
	v_pk_fma_f32 v[18:19], v[84:85], v[114:115], v[18:19] op_sel:[1,0,0] op_sel_hi:[1,1,1]
	ds_read_b64 v[84:85], v138 offset:33824
	s_waitcnt lgkmcnt(15)
	v_pk_fma_f32 v[20:21], v[86:87], v[112:113], v[20:21] op_sel_hi:[0,1,1]
	v_pk_fma_f32 v[20:21], v[86:87], v[114:115], v[20:21] op_sel:[1,0,0] op_sel_hi:[1,1,1]
	ds_read_b64 v[86:87], v138 offset:38048
	s_waitcnt lgkmcnt(15)
	v_pk_fma_f32 v[22:23], v[88:89], v[112:113], v[22:23] op_sel_hi:[0,1,1]
	v_pk_fma_f32 v[22:23], v[88:89], v[114:115], v[22:23] op_sel:[1,0,0] op_sel_hi:[1,1,1]
	ds_read_b64 v[88:89], v138 offset:42272
	s_waitcnt lgkmcnt(15)
	v_pk_fma_f32 v[24:25], v[90:91], v[112:113], v[24:25] op_sel_hi:[0,1,1]
	v_pk_fma_f32 v[24:25], v[90:91], v[114:115], v[24:25] op_sel:[1,0,0] op_sel_hi:[1,1,1]
	ds_read_b64 v[90:91], v138 offset:46496
	s_waitcnt lgkmcnt(15)
	v_pk_fma_f32 v[26:27], v[92:93], v[112:113], v[26:27] op_sel_hi:[0,1,1]
	v_pk_fma_f32 v[26:27], v[92:93], v[114:115], v[26:27] op_sel:[1,0,0] op_sel_hi:[1,1,1]
	ds_read_b64 v[92:93], v138 offset:50720
	s_waitcnt lgkmcnt(15)
	v_pk_fma_f32 v[28:29], v[94:95], v[112:113], v[28:29] op_sel_hi:[0,1,1]
	v_pk_fma_f32 v[28:29], v[94:95], v[114:115], v[28:29] op_sel:[1,0,0] op_sel_hi:[1,1,1]
	ds_read_b64 v[94:95], v138 offset:54944
	s_waitcnt lgkmcnt(15)
	v_pk_fma_f32 v[30:31], v[96:97], v[112:113], v[30:31] op_sel_hi:[0,1,1]
	v_pk_fma_f32 v[30:31], v[96:97], v[114:115], v[30:31] op_sel:[1,0,0] op_sel_hi:[1,1,1]
	ds_read_b64 v[96:97], v138 offset:59168
	s_waitcnt lgkmcnt(15)
	v_pk_fma_f32 v[32:33], v[98:99], v[112:113], v[32:33] op_sel_hi:[0,1,1]
	v_pk_fma_f32 v[32:33], v[98:99], v[114:115], v[32:33] op_sel:[1,0,0] op_sel_hi:[1,1,1]
	ds_read_b64 v[98:99], v138 offset:63392
	global_load_dwordx2 v[112:113], v[134:135], off offset:-2048
	global_load_dwordx2 v[114:115], v[134:135], off offset:2048
	v_lshl_add_u64 v[134:135], v[134:135], 0, s[0:1]
	s_waitcnt vmcnt(14)
	s_waitcnt lgkmcnt(15)
	v_pk_fma_f32 v[2:3], v[34:35], v[116:117], v[2:3] op_sel_hi:[0,1,1]
	v_pk_fma_f32 v[2:3], v[34:35], v[118:119], v[2:3] op_sel:[1,0,0] op_sel_hi:[1,1,1]
	ds_read_b64 v[34:35], v138 offset:40
	s_waitcnt lgkmcnt(15)
	v_pk_fma_f32 v[4:5], v[36:37], v[116:117], v[4:5] op_sel_hi:[0,1,1]
	v_pk_fma_f32 v[4:5], v[36:37], v[118:119], v[4:5] op_sel:[1,0,0] op_sel_hi:[1,1,1]
	ds_read_b64 v[36:37], v138 offset:4264
	s_waitcnt lgkmcnt(15)
	v_pk_fma_f32 v[6:7], v[38:39], v[116:117], v[6:7] op_sel_hi:[0,1,1]
	v_pk_fma_f32 v[6:7], v[38:39], v[118:119], v[6:7] op_sel:[1,0,0] op_sel_hi:[1,1,1]
	ds_read_b64 v[38:39], v138 offset:8488
	s_waitcnt lgkmcnt(15)
	v_pk_fma_f32 v[8:9], v[40:41], v[116:117], v[8:9] op_sel_hi:[0,1,1]
	v_pk_fma_f32 v[8:9], v[40:41], v[118:119], v[8:9] op_sel:[1,0,0] op_sel_hi:[1,1,1]
	ds_read_b64 v[40:41], v138 offset:12712
	s_waitcnt lgkmcnt(15)
	v_pk_fma_f32 v[10:11], v[42:43], v[116:117], v[10:11] op_sel_hi:[0,1,1]
	v_pk_fma_f32 v[10:11], v[42:43], v[118:119], v[10:11] op_sel:[1,0,0] op_sel_hi:[1,1,1]
	ds_read_b64 v[42:43], v138 offset:16936
	s_waitcnt lgkmcnt(15)
	v_pk_fma_f32 v[12:13], v[44:45], v[116:117], v[12:13] op_sel_hi:[0,1,1]
	v_pk_fma_f32 v[12:13], v[44:45], v[118:119], v[12:13] op_sel:[1,0,0] op_sel_hi:[1,1,1]
	ds_read_b64 v[44:45], v138 offset:21160
	s_waitcnt lgkmcnt(15)
	v_pk_fma_f32 v[14:15], v[46:47], v[116:117], v[14:15] op_sel_hi:[0,1,1]
	v_pk_fma_f32 v[14:15], v[46:47], v[118:119], v[14:15] op_sel:[1,0,0] op_sel_hi:[1,1,1]
	ds_read_b64 v[46:47], v138 offset:25384
	s_waitcnt lgkmcnt(15)
	v_pk_fma_f32 v[16:17], v[48:49], v[116:117], v[16:17] op_sel_hi:[0,1,1]
	v_pk_fma_f32 v[16:17], v[48:49], v[118:119], v[16:17] op_sel:[1,0,0] op_sel_hi:[1,1,1]
	ds_read_b64 v[48:49], v138 offset:29608
	s_waitcnt lgkmcnt(15)
	v_pk_fma_f32 v[18:19], v[84:85], v[116:117], v[18:19] op_sel_hi:[0,1,1]
	v_pk_fma_f32 v[18:19], v[84:85], v[118:119], v[18:19] op_sel:[1,0,0] op_sel_hi:[1,1,1]
	ds_read_b64 v[84:85], v138 offset:33832
	s_waitcnt lgkmcnt(15)
	v_pk_fma_f32 v[20:21], v[86:87], v[116:117], v[20:21] op_sel_hi:[0,1,1]
	v_pk_fma_f32 v[20:21], v[86:87], v[118:119], v[20:21] op_sel:[1,0,0] op_sel_hi:[1,1,1]
	ds_read_b64 v[86:87], v138 offset:38056
	s_waitcnt lgkmcnt(15)
	v_pk_fma_f32 v[22:23], v[88:89], v[116:117], v[22:23] op_sel_hi:[0,1,1]
	v_pk_fma_f32 v[22:23], v[88:89], v[118:119], v[22:23] op_sel:[1,0,0] op_sel_hi:[1,1,1]
	ds_read_b64 v[88:89], v138 offset:42280
	s_waitcnt lgkmcnt(15)
	v_pk_fma_f32 v[24:25], v[90:91], v[116:117], v[24:25] op_sel_hi:[0,1,1]
	v_pk_fma_f32 v[24:25], v[90:91], v[118:119], v[24:25] op_sel:[1,0,0] op_sel_hi:[1,1,1]
	ds_read_b64 v[90:91], v138 offset:46504
	s_waitcnt lgkmcnt(15)
	v_pk_fma_f32 v[26:27], v[92:93], v[116:117], v[26:27] op_sel_hi:[0,1,1]
	v_pk_fma_f32 v[26:27], v[92:93], v[118:119], v[26:27] op_sel:[1,0,0] op_sel_hi:[1,1,1]
	ds_read_b64 v[92:93], v138 offset:50728
	s_waitcnt lgkmcnt(15)
	v_pk_fma_f32 v[28:29], v[94:95], v[116:117], v[28:29] op_sel_hi:[0,1,1]
	v_pk_fma_f32 v[28:29], v[94:95], v[118:119], v[28:29] op_sel:[1,0,0] op_sel_hi:[1,1,1]
	ds_read_b64 v[94:95], v138 offset:54952
	s_waitcnt lgkmcnt(15)
	v_pk_fma_f32 v[30:31], v[96:97], v[116:117], v[30:31] op_sel_hi:[0,1,1]
	v_pk_fma_f32 v[30:31], v[96:97], v[118:119], v[30:31] op_sel:[1,0,0] op_sel_hi:[1,1,1]
	ds_read_b64 v[96:97], v138 offset:59176
	s_waitcnt lgkmcnt(15)
; __device__ __forceinline__ float bflo(unsigned w) { return __uint_as_float(w << 16); }
; __device__ __forceinline__ float bfhi(unsigned w) { return __uint_as_float(w & 0xffff0000u); }
; template <int BR>
; __device__ __forceinline__ void sample_unit(const SampP& P, int bs, int h, char* lds, float lam) {
;     ...
; #pragma unroll 1
;     for (int k5 = 0; k5 < 13; ++k5) { const int keyb = 130 * wid + 10 * k5 + hf;
;       f32x4 v[5];
; #pragma unroll
;       for (int e = 0; e < 5; ++e) { const int key = keyb + 2 * e;
;         if (key < PAST) v[e] = *(const f32x4*)(Vc + (size_t)key * 1024 + 4 * l31);
;         else { const u32x2 w = *(const u32x2*)(Vn + (size_t)(key - PAST) * 1024 + 4 * l31); v[e] = (f32x4){bflo(w.x), bfhi(w.x), bflo(w.y), bfhi(w.y)}; } }
; #pragma unroll
;       for (int e = 0; e < 5; ++e) { const float* sp = S1 + keyb + 2 * e;
; #pragma unroll
;         for (int q = 0; q < 16; ++q) acc[q] += sp[q * SST] * v[e];
;         asm volatile("" ::: "memory"); }
	v_pk_fma_f32 v[32:33], v[98:99], v[116:117], v[32:33] op_sel_hi:[0,1,1]
	v_pk_fma_f32 v[32:33], v[98:99], v[118:119], v[32:33] op_sel:[1,0,0] op_sel_hi:[1,1,1]
	ds_read_b64 v[98:99], v138 offset:63400
	global_load_dwordx2 v[116:117], v[134:135], off offset:-2048
	global_load_dwordx2 v[118:119], v[134:135], off offset:2048
	v_lshl_add_u64 v[134:135], v[134:135], 0, s[0:1]
	s_waitcnt vmcnt(14)
	s_waitcnt lgkmcnt(15)
	v_pk_fma_f32 v[2:3], v[34:35], v[120:121], v[2:3] op_sel_hi:[0,1,1]
	v_pk_fma_f32 v[2:3], v[34:35], v[122:123], v[2:3] op_sel:[1,0,0] op_sel_hi:[1,1,1]
	ds_read_b64 v[34:35], v138 offset:48
	s_waitcnt lgkmcnt(15)
	v_pk_fma_f32 v[4:5], v[36:37], v[120:121], v[4:5] op_sel_hi:[0,1,1]
	v_pk_fma_f32 v[4:5], v[36:37], v[122:123], v[4:5] op_sel:[1,0,0] op_sel_hi:[1,1,1]
	ds_read_b64 v[36:37], v138 offset:4272
	s_waitcnt lgkmcnt(15)
	v_pk_fma_f32 v[6:7], v[38:39], v[120:121], v[6:7] op_sel_hi:[0,1,1]
	v_pk_fma_f32 v[6:7], v[38:39], v[122:123], v[6:7] op_sel:[1,0,0] op_sel_hi:[1,1,1]
	ds_read_b64 v[38:39], v138 offset:8496
	s_waitcnt lgkmcnt(15)
	v_pk_fma_f32 v[8:9], v[40:41], v[120:121], v[8:9] op_sel_hi:[0,1,1]
	v_pk_fma_f32 v[8:9], v[40:41], v[122:123], v[8:9] op_sel:[1,0,0] op_sel_hi:[1,1,1]
	ds_read_b64 v[40:41], v138 offset:12720
	s_waitcnt lgkmcnt(15)
	v_pk_fma_f32 v[10:11], v[42:43], v[120:121], v[10:11] op_sel_hi:[0,1,1]
	v_pk_fma_f32 v[10:11], v[42:43], v[122:123], v[10:11] op_sel:[1,0,0] op_sel_hi:[1,1,1]
	ds_read_b64 v[42:43], v138 offset:16944
	s_waitcnt lgkmcnt(15)
	v_pk_fma_f32 v[12:13], v[44:45], v[120:121], v[12:13] op_sel_hi:[0,1,1]
	v_pk_fma_f32 v[12:13], v[44:45], v[122:123], v[12:13] op_sel:[1,0,0] op_sel_hi:[1,1,1]
	ds_read_b64 v[44:45], v138 offset:21168
	s_waitcnt lgkmcnt(15)
	v_pk_fma_f32 v[14:15], v[46:47], v[120:121], v[14:15] op_sel_hi:[0,1,1]
	v_pk_fma_f32 v[14:15], v[46:47], v[122:123], v[14:15] op_sel:[1,0,0] op_sel_hi:[1,1,1]
	ds_read_b64 v[46:47], v138 offset:25392
	s_waitcnt lgkmcnt(15)
	v_pk_fma_f32 v[16:17], v[48:49], v[120:121], v[16:17] op_sel_hi:[0,1,1]
	v_pk_fma_f32 v[16:17], v[48:49], v[122:123], v[16:17] op_sel:[1,0,0] op_sel_hi:[1,1,1]
	ds_read_b64 v[48:49], v138 offset:29616
	s_waitcnt lgkmcnt(15)
	v_pk_fma_f32 v[18:19], v[84:85], v[120:121], v[18:19] op_sel_hi:[0,1,1]
	v_pk_fma_f32 v[18:19], v[84:85], v[122:123], v[18:19] op_sel:[1,0,0] op_sel_hi:[1,1,1]
	ds_read_b64 v[84:85], v138 offset:33840
	s_waitcnt lgkmcnt(15)
	v_pk_fma_f32 v[20:21], v[86:87], v[120:121], v[20:21] op_sel_hi:[0,1,1]
	v_pk_fma_f32 v[20:21], v[86:87], v[122:123], v[20:21] op_sel:[1,0,0] op_sel_hi:[1,1,1]
	ds_read_b64 v[86:87], v138 offset:38064
	s_waitcnt lgkmcnt(15)
	v_pk_fma_f32 v[22:23], v[88:89], v[120:121], v[22:23] op_sel_hi:[0,1,1]
	v_pk_fma_f32 v[22:23], v[88:89], v[122:123], v[22:23] op_sel:[1,0,0] op_sel_hi:[1,1,1]
	ds_read_b64 v[88:89], v138 offset:42288
	s_waitcnt lgkmcnt(15)
	v_pk_fma_f32 v[24:25], v[90:91], v[120:121], v[24:25] op_sel_hi:[0,1,1]
	v_pk_fma_f32 v[24:25], v[90:91], v[122:123], v[24:25] op_sel:[1,0,0] op_sel_hi:[1,1,1]
	ds_read_b64 v[90:91], v138 offset:46512
	s_waitcnt lgkmcnt(15)
	v_pk_fma_f32 v[26:27], v[92:93], v[120:121], v[26:27] op_sel_hi:[0,1,1]
	v_pk_fma_f32 v[26:27], v[92:93], v[122:123], v[26:27] op_sel:[1,0,0] op_sel_hi:[1,1,1]
	ds_read_b64 v[92:93], v138 offset:50736
	s_waitcnt lgkmcnt(15)
	v_pk_fma_f32 v[28:29], v[94:95], v[120:121], v[28:29] op_sel_hi:[0,1,1]
	v_pk_fma_f32 v[28:29], v[94:95], v[122:123], v[28:29] op_sel:[1,0,0] op_sel_hi:[1,1,1]
	ds_read_b64 v[94:95], v138 offset:54960
	s_waitcnt lgkmcnt(15)
	v_pk_fma_f32 v[30:31], v[96:97], v[120:121], v[30:31] op_sel_hi:[0,1,1]
	v_pk_fma_f32 v[30:31], v[96:97], v[122:123], v[30:31] op_sel:[1,0,0] op_sel_hi:[1,1,1]
	ds_read_b64 v[96:97], v138 offset:59184
	s_waitcnt lgkmcnt(15)
	v_pk_fma_f32 v[32:33], v[98:99], v[120:121], v[32:33] op_sel_hi:[0,1,1]
	v_pk_fma_f32 v[32:33], v[98:99], v[122:123], v[32:33] op_sel:[1,0,0] op_sel_hi:[1,1,1]
	ds_read_b64 v[98:99], v138 offset:63408
	global_load_dwordx2 v[120:121], v[134:135], off offset:-2048
	global_load_dwordx2 v[122:123], v[134:135], off offset:2048
	v_lshl_add_u64 v[134:135], v[134:135], 0, s[0:1]
	s_waitcnt vmcnt(14)
	s_waitcnt lgkmcnt(15)
	v_pk_fma_f32 v[2:3], v[34:35], v[124:125], v[2:3] op_sel_hi:[0,1,1]
	v_pk_fma_f32 v[2:3], v[34:35], v[126:127], v[2:3] op_sel:[1,0,0] op_sel_hi:[1,1,1]
	ds_read_b64 v[34:35], v138 offset:56
	s_waitcnt lgkmcnt(15)
	v_pk_fma_f32 v[4:5], v[36:37], v[124:125], v[4:5] op_sel_hi:[0,1,1]
	v_pk_fma_f32 v[4:5], v[36:37], v[126:127], v[4:5] op_sel:[1,0,0] op_sel_hi:[1,1,1]
	ds_read_b64 v[36:37], v138 offset:4280
	s_waitcnt lgkmcnt(15)
	v_pk_fma_f32 v[6:7], v[38:39], v[124:125], v[6:7] op_sel_hi:[0,1,1]
	v_pk_fma_f32 v[6:7], v[38:39], v[126:127], v[6:7] op_sel:[1,0,0] op_sel_hi:[1,1,1]
	ds_read_b64 v[38:39], v138 offset:8504
	s_waitcnt lgkmcnt(15)
	v_pk_fma_f32 v[8:9], v[40:41], v[124:125], v[8:9] op_sel_hi:[0,1,1]
	v_pk_fma_f32 v[8:9], v[40:41], v[126:127], v[8:9] op_sel:[1,0,0] op_sel_hi:[1,1,1]
	ds_read_b64 v[40:41], v138 offset:12728
	s_waitcnt lgkmcnt(15)
	v_pk_fma_f32 v[10:11], v[42:43], v[124:125], v[10:11] op_sel_hi:[0,1,1]
	v_pk_fma_f32 v[10:11], v[42:43], v[126:127], v[10:11] op_sel:[1,0,0] op_sel_hi:[1,1,1]
	ds_read_b64 v[42:43], v138 offset:16952
	s_waitcnt lgkmcnt(15)
	v_pk_fma_f32 v[12:13], v[44:45], v[124:125], v[12:13] op_sel_hi:[0,1,1]
	v_pk_fma_f32 v[12:13], v[44:45], v[126:127], v[12:13] op_sel:[1,0,0] op_sel_hi:[1,1,1]
	ds_read_b64 v[44:45], v138 offset:21176
	s_waitcnt lgkmcnt(15)
	v_pk_fma_f32 v[14:15], v[46:47], v[124:125], v[14:15] op_sel_hi:[0,1,1]
	v_pk_fma_f32 v[14:15], v[46:47], v[126:127], v[14:15] op_sel:[1,0,0] op_sel_hi:[1,1,1]
	ds_read_b64 v[46:47], v138 offset:25400
	s_waitcnt lgkmcnt(15)
; __device__ __forceinline__ float bflo(unsigned w) { return __uint_as_float(w << 16); }
; __device__ __forceinline__ float bfhi(unsigned w) { return __uint_as_float(w & 0xffff0000u); }
; template <int BR>
; __device__ __forceinline__ void sample_unit(const SampP& P, int bs, int h, char* lds, float lam) {
;     ...
; #pragma unroll 1
;     for (int k5 = 0; k5 < 13; ++k5) { const int keyb = 130 * wid + 10 * k5 + hf;
;       f32x4 v[5];
; #pragma unroll
;       for (int e = 0; e < 5; ++e) { const int key = keyb + 2 * e;
;         if (key < PAST) v[e] = *(const f32x4*)(Vc + (size_t)key * 1024 + 4 * l31);
;         else { const u32x2 w = *(const u32x2*)(Vn + (size_t)(key - PAST) * 1024 + 4 * l31); v[e] = (f32x4){bflo(w.x), bfhi(w.x), bflo(w.y), bfhi(w.y)}; } }
; #pragma unroll
;       for (int e = 0; e < 5; ++e) { const float* sp = S1 + keyb + 2 * e;
; #pragma unroll
;         for (int q = 0; q < 16; ++q) acc[q] += sp[q * SST] * v[e];
;         asm volatile("" ::: "memory"); }
	v_pk_fma_f32 v[16:17], v[48:49], v[124:125], v[16:17] op_sel_hi:[0,1,1]
	v_pk_fma_f32 v[16:17], v[48:49], v[126:127], v[16:17] op_sel:[1,0,0] op_sel_hi:[1,1,1]
	ds_read_b64 v[48:49], v138 offset:29624
	s_waitcnt lgkmcnt(15)
	v_pk_fma_f32 v[18:19], v[84:85], v[124:125], v[18:19] op_sel_hi:[0,1,1]
	v_pk_fma_f32 v[18:19], v[84:85], v[126:127], v[18:19] op_sel:[1,0,0] op_sel_hi:[1,1,1]
	ds_read_b64 v[84:85], v138 offset:33848
	s_waitcnt lgkmcnt(15)
	v_pk_fma_f32 v[20:21], v[86:87], v[124:125], v[20:21] op_sel_hi:[0,1,1]
	v_pk_fma_f32 v[20:21], v[86:87], v[126:127], v[20:21] op_sel:[1,0,0] op_sel_hi:[1,1,1]
	ds_read_b64 v[86:87], v138 offset:38072
	s_waitcnt lgkmcnt(15)
	v_pk_fma_f32 v[22:23], v[88:89], v[124:125], v[22:23] op_sel_hi:[0,1,1]
	v_pk_fma_f32 v[22:23], v[88:89], v[126:127], v[22:23] op_sel:[1,0,0] op_sel_hi:[1,1,1]
	ds_read_b64 v[88:89], v138 offset:42296
	s_waitcnt lgkmcnt(15)
	v_pk_fma_f32 v[24:25], v[90:91], v[124:125], v[24:25] op_sel_hi:[0,1,1]
	v_pk_fma_f32 v[24:25], v[90:91], v[126:127], v[24:25] op_sel:[1,0,0] op_sel_hi:[1,1,1]
	ds_read_b64 v[90:91], v138 offset:46520
	s_waitcnt lgkmcnt(15)
	v_pk_fma_f32 v[26:27], v[92:93], v[124:125], v[26:27] op_sel_hi:[0,1,1]
	v_pk_fma_f32 v[26:27], v[92:93], v[126:127], v[26:27] op_sel:[1,0,0] op_sel_hi:[1,1,1]
	ds_read_b64 v[92:93], v138 offset:50744
	s_waitcnt lgkmcnt(15)
	v_pk_fma_f32 v[28:29], v[94:95], v[124:125], v[28:29] op_sel_hi:[0,1,1]
	v_pk_fma_f32 v[28:29], v[94:95], v[126:127], v[28:29] op_sel:[1,0,0] op_sel_hi:[1,1,1]
	ds_read_b64 v[94:95], v138 offset:54968
	s_waitcnt lgkmcnt(15)
	v_pk_fma_f32 v[30:31], v[96:97], v[124:125], v[30:31] op_sel_hi:[0,1,1]
	v_pk_fma_f32 v[30:31], v[96:97], v[126:127], v[30:31] op_sel:[1,0,0] op_sel_hi:[1,1,1]
	ds_read_b64 v[96:97], v138 offset:59192
	s_waitcnt lgkmcnt(15)
	v_pk_fma_f32 v[32:33], v[98:99], v[124:125], v[32:33] op_sel_hi:[0,1,1]
	v_pk_fma_f32 v[32:33], v[98:99], v[126:127], v[32:33] op_sel:[1,0,0] op_sel_hi:[1,1,1]
	ds_read_b64 v[98:99], v138 offset:63416
	global_load_dwordx2 v[124:125], v[134:135], off offset:-2048
	global_load_dwordx2 v[126:127], v[134:135], off offset:2048
	v_lshl_add_u64 v[134:135], v[134:135], 0, s[0:1]
	s_waitcnt vmcnt(14)
	s_waitcnt lgkmcnt(15)
	v_pk_fma_f32 v[2:3], v[34:35], v[128:129], v[2:3] op_sel_hi:[0,1,1]
	v_pk_fma_f32 v[2:3], v[34:35], v[130:131], v[2:3] op_sel:[1,0,0] op_sel_hi:[1,1,1]
	ds_read_b64 v[34:35], v138 offset:64
	s_waitcnt lgkmcnt(15)
	v_pk_fma_f32 v[4:5], v[36:37], v[128:129], v[4:5] op_sel_hi:[0,1,1]
	v_pk_fma_f32 v[4:5], v[36:37], v[130:131], v[4:5] op_sel:[1,0,0] op_sel_hi:[1,1,1]
	ds_read_b64 v[36:37], v138 offset:4288
	s_waitcnt lgkmcnt(15)
	v_pk_fma_f32 v[6:7], v[38:39], v[128:129], v[6:7] op_sel_hi:[0,1,1]
	v_pk_fma_f32 v[6:7], v[38:39], v[130:131], v[6:7] op_sel:[1,0,0] op_sel_hi:[1,1,1]
	ds_read_b64 v[38:39], v138 offset:8512
	s_waitcnt lgkmcnt(15)
	v_pk_fma_f32 v[8:9], v[40:41], v[128:129], v[8:9] op_sel_hi:[0,1,1]
	v_pk_fma_f32 v[8:9], v[40:41], v[130:131], v[8:9] op_sel:[1,0,0] op_sel_hi:[1,1,1]
	ds_read_b64 v[40:41], v138 offset:12736
	s_waitcnt lgkmcnt(15)
	v_pk_fma_f32 v[10:11], v[42:43], v[128:129], v[10:11] op_sel_hi:[0,1,1]
	v_pk_fma_f32 v[10:11], v[42:43], v[130:131], v[10:11] op_sel:[1,0,0] op_sel_hi:[1,1,1]
	ds_read_b64 v[42:43], v138 offset:16960
	s_waitcnt lgkmcnt(15)
	v_pk_fma_f32 v[12:13], v[44:45], v[128:129], v[12:13] op_sel_hi:[0,1,1]
	v_pk_fma_f32 v[12:13], v[44:45], v[130:131], v[12:13] op_sel:[1,0,0] op_sel_hi:[1,1,1]
	ds_read_b64 v[44:45], v138 offset:21184
	s_waitcnt lgkmcnt(15)
	v_pk_fma_f32 v[14:15], v[46:47], v[128:129], v[14:15] op_sel_hi:[0,1,1]
	v_pk_fma_f32 v[14:15], v[46:47], v[130:131], v[14:15] op_sel:[1,0,0] op_sel_hi:[1,1,1]
	ds_read_b64 v[46:47], v138 offset:25408
	s_waitcnt lgkmcnt(15)
	v_pk_fma_f32 v[16:17], v[48:49], v[128:129], v[16:17] op_sel_hi:[0,1,1]
	v_pk_fma_f32 v[16:17], v[48:49], v[130:131], v[16:17] op_sel:[1,0,0] op_sel_hi:[1,1,1]
	ds_read_b64 v[48:49], v138 offset:29632
	s_waitcnt lgkmcnt(15)
	v_pk_fma_f32 v[18:19], v[84:85], v[128:129], v[18:19] op_sel_hi:[0,1,1]
	v_pk_fma_f32 v[18:19], v[84:85], v[130:131], v[18:19] op_sel:[1,0,0] op_sel_hi:[1,1,1]
	ds_read_b64 v[84:85], v138 offset:33856
	s_waitcnt lgkmcnt(15)
	v_pk_fma_f32 v[20:21], v[86:87], v[128:129], v[20:21] op_sel_hi:[0,1,1]
	v_pk_fma_f32 v[20:21], v[86:87], v[130:131], v[20:21] op_sel:[1,0,0] op_sel_hi:[1,1,1]
	ds_read_b64 v[86:87], v138 offset:38080
	s_waitcnt lgkmcnt(15)
	v_pk_fma_f32 v[22:23], v[88:89], v[128:129], v[22:23] op_sel_hi:[0,1,1]
	v_pk_fma_f32 v[22:23], v[88:89], v[130:131], v[22:23] op_sel:[1,0,0] op_sel_hi:[1,1,1]
	ds_read_b64 v[88:89], v138 offset:42304
	s_waitcnt lgkmcnt(15)
	v_pk_fma_f32 v[24:25], v[90:91], v[128:129], v[24:25] op_sel_hi:[0,1,1]
	v_pk_fma_f32 v[24:25], v[90:91], v[130:131], v[24:25] op_sel:[1,0,0] op_sel_hi:[1,1,1]
	ds_read_b64 v[90:91], v138 offset:46528
	s_waitcnt lgkmcnt(15)
	v_pk_fma_f32 v[26:27], v[92:93], v[128:129], v[26:27] op_sel_hi:[0,1,1]
	v_pk_fma_f32 v[26:27], v[92:93], v[130:131], v[26:27] op_sel:[1,0,0] op_sel_hi:[1,1,1]
	ds_read_b64 v[92:93], v138 offset:50752
	s_waitcnt lgkmcnt(15)
	v_pk_fma_f32 v[28:29], v[94:95], v[128:129], v[28:29] op_sel_hi:[0,1,1]
	v_pk_fma_f32 v[28:29], v[94:95], v[130:131], v[28:29] op_sel:[1,0,0] op_sel_hi:[1,1,1]
	ds_read_b64 v[94:95], v138 offset:54976
	s_waitcnt lgkmcnt(15)
	v_pk_fma_f32 v[30:31], v[96:97], v[128:129], v[30:31] op_sel_hi:[0,1,1]
	v_pk_fma_f32 v[30:31], v[96:97], v[130:131], v[30:31] op_sel:[1,0,0] op_sel_hi:[1,1,1]
	ds_read_b64 v[96:97], v138 offset:59200
	s_waitcnt lgkmcnt(15)
	v_pk_fma_f32 v[32:33], v[98:99], v[128:129], v[32:33] op_sel_hi:[0,1,1]
	v_pk_fma_f32 v[32:33], v[98:99], v[130:131], v[32:33] op_sel:[1,0,0] op_sel_hi:[1,1,1]
	ds_read_b64 v[98:99], v138 offset:63424
	global_load_dwordx2 v[128:129], v[134:135], off offset:-2048
	global_load_dwordx2 v[130:131], v[134:135], off offset:2048
	v_lshl_add_u64 v[134:135], v[134:135], 0, s[0:1]
	v_add_u32_e32 v138, 64, v138
	s_add_u32 s2, s2, 1
	s_cmp_lt_u32 s2, 7
	s_cbranch_scc1 .Lpvf_loop
; __device__ __forceinline__ float bflo(unsigned w) { return __uint_as_float(w << 16); }
; __device__ __forceinline__ float bfhi(unsigned w) { return __uint_as_float(w & 0xffff0000u); }
; template <int BR>
; __device__ __forceinline__ void sample_unit(const SampP& P, int bs, int h, char* lds, float lam) {
;     ...
; #pragma unroll 1
;     for (int k5 = 0; k5 < 13; ++k5) { const int keyb = 130 * wid + 10 * k5 + hf;
;       f32x4 v[5];
; #pragma unroll
;       for (int e = 0; e < 5; ++e) { const int key = keyb + 2 * e;
;         if (key < PAST) v[e] = *(const f32x4*)(Vc + (size_t)key * 1024 + 4 * l31);
;         else { const u32x2 w = *(const u32x2*)(Vn + (size_t)(key - PAST) * 1024 + 4 * l31); v[e] = (f32x4){bflo(w.x), bfhi(w.x), bflo(w.y), bfhi(w.y)}; } }
; #pragma unroll
;       for (int e = 0; e < 5; ++e) { const float* sp = S1 + keyb + 2 * e;
; #pragma unroll
;         for (int q = 0; q < 16; ++q) acc[q] += sp[q * SST] * v[e];
;         asm volatile("" ::: "memory"); }
	global_load_dword v141, v[136:137], off
	global_load_dword v142, v[136:137], off offset:2048
	s_waitcnt vmcnt(16)
	s_waitcnt lgkmcnt(15)
	v_pk_fma_f32 v[2:3], v[34:35], v[100:101], v[2:3] op_sel_hi:[0,1,1]
	v_pk_fma_f32 v[2:3], v[34:35], v[102:103], v[2:3] op_sel:[1,0,0] op_sel_hi:[1,1,1]
	ds_read_b64 v[34:35], v138 offset:8
	s_waitcnt lgkmcnt(15)
	v_pk_fma_f32 v[4:5], v[36:37], v[100:101], v[4:5] op_sel_hi:[0,1,1]
	v_pk_fma_f32 v[4:5], v[36:37], v[102:103], v[4:5] op_sel:[1,0,0] op_sel_hi:[1,1,1]
	ds_read_b64 v[36:37], v138 offset:4232
	s_waitcnt lgkmcnt(15)
	v_pk_fma_f32 v[6:7], v[38:39], v[100:101], v[6:7] op_sel_hi:[0,1,1]
	v_pk_fma_f32 v[6:7], v[38:39], v[102:103], v[6:7] op_sel:[1,0,0] op_sel_hi:[1,1,1]
	ds_read_b64 v[38:39], v138 offset:8456
	s_waitcnt lgkmcnt(15)
	v_pk_fma_f32 v[8:9], v[40:41], v[100:101], v[8:9] op_sel_hi:[0,1,1]
	v_pk_fma_f32 v[8:9], v[40:41], v[102:103], v[8:9] op_sel:[1,0,0] op_sel_hi:[1,1,1]
	ds_read_b64 v[40:41], v138 offset:12680
	s_waitcnt lgkmcnt(15)
	v_pk_fma_f32 v[10:11], v[42:43], v[100:101], v[10:11] op_sel_hi:[0,1,1]
	v_pk_fma_f32 v[10:11], v[42:43], v[102:103], v[10:11] op_sel:[1,0,0] op_sel_hi:[1,1,1]
	ds_read_b64 v[42:43], v138 offset:16904
	s_waitcnt lgkmcnt(15)
	v_pk_fma_f32 v[12:13], v[44:45], v[100:101], v[12:13] op_sel_hi:[0,1,1]
	v_pk_fma_f32 v[12:13], v[44:45], v[102:103], v[12:13] op_sel:[1,0,0] op_sel_hi:[1,1,1]
	ds_read_b64 v[44:45], v138 offset:21128
	s_waitcnt lgkmcnt(15)
	v_pk_fma_f32 v[14:15], v[46:47], v[100:101], v[14:15] op_sel_hi:[0,1,1]
	v_pk_fma_f32 v[14:15], v[46:47], v[102:103], v[14:15] op_sel:[1,0,0] op_sel_hi:[1,1,1]
	ds_read_b64 v[46:47], v138 offset:25352
	s_waitcnt lgkmcnt(15)
	v_pk_fma_f32 v[16:17], v[48:49], v[100:101], v[16:17] op_sel_hi:[0,1,1]
	v_pk_fma_f32 v[16:17], v[48:49], v[102:103], v[16:17] op_sel:[1,0,0] op_sel_hi:[1,1,1]
	ds_read_b64 v[48:49], v138 offset:29576
	s_waitcnt lgkmcnt(15)
	v_pk_fma_f32 v[18:19], v[84:85], v[100:101], v[18:19] op_sel_hi:[0,1,1]
	v_pk_fma_f32 v[18:19], v[84:85], v[102:103], v[18:19] op_sel:[1,0,0] op_sel_hi:[1,1,1]
	ds_read_b64 v[84:85], v138 offset:33800
	s_waitcnt lgkmcnt(15)
	v_pk_fma_f32 v[20:21], v[86:87], v[100:101], v[20:21] op_sel_hi:[0,1,1]
	v_pk_fma_f32 v[20:21], v[86:87], v[102:103], v[20:21] op_sel:[1,0,0] op_sel_hi:[1,1,1]
	ds_read_b64 v[86:87], v138 offset:38024
	s_waitcnt lgkmcnt(15)
	v_pk_fma_f32 v[22:23], v[88:89], v[100:101], v[22:23] op_sel_hi:[0,1,1]
	v_pk_fma_f32 v[22:23], v[88:89], v[102:103], v[22:23] op_sel:[1,0,0] op_sel_hi:[1,1,1]
	ds_read_b64 v[88:89], v138 offset:42248
	s_waitcnt lgkmcnt(15)
	v_pk_fma_f32 v[24:25], v[90:91], v[100:101], v[24:25] op_sel_hi:[0,1,1]
	v_pk_fma_f32 v[24:25], v[90:91], v[102:103], v[24:25] op_sel:[1,0,0] op_sel_hi:[1,1,1]
	ds_read_b64 v[90:91], v138 offset:46472
	s_waitcnt lgkmcnt(15)
	v_pk_fma_f32 v[26:27], v[92:93], v[100:101], v[26:27] op_sel_hi:[0,1,1]
	v_pk_fma_f32 v[26:27], v[92:93], v[102:103], v[26:27] op_sel:[1,0,0] op_sel_hi:[1,1,1]
	ds_read_b64 v[92:93], v138 offset:50696
	s_waitcnt lgkmcnt(15)
	v_pk_fma_f32 v[28:29], v[94:95], v[100:101], v[28:29] op_sel_hi:[0,1,1]
	v_pk_fma_f32 v[28:29], v[94:95], v[102:103], v[28:29] op_sel:[1,0,0] op_sel_hi:[1,1,1]
	ds_read_b64 v[94:95], v138 offset:54920
	s_waitcnt lgkmcnt(15)
	v_pk_fma_f32 v[30:31], v[96:97], v[100:101], v[30:31] op_sel_hi:[0,1,1]
	v_pk_fma_f32 v[30:31], v[96:97], v[102:103], v[30:31] op_sel:[1,0,0] op_sel_hi:[1,1,1]
	ds_read_b64 v[96:97], v138 offset:59144
	s_waitcnt lgkmcnt(15)
	v_pk_fma_f32 v[32:33], v[98:99], v[100:101], v[32:33] op_sel_hi:[0,1,1]
	v_pk_fma_f32 v[32:33], v[98:99], v[102:103], v[32:33] op_sel:[1,0,0] op_sel_hi:[1,1,1]
	ds_read_b64 v[98:99], v138 offset:63368
	s_waitcnt vmcnt(14)
	s_waitcnt lgkmcnt(15)
	v_pk_fma_f32 v[2:3], v[34:35], v[104:105], v[2:3] op_sel_hi:[0,1,1]
	v_pk_fma_f32 v[2:3], v[34:35], v[106:107], v[2:3] op_sel:[1,0,0] op_sel_hi:[1,1,1]
	ds_read_b64 v[34:35], v138 offset:16
	s_waitcnt lgkmcnt(15)
	v_pk_fma_f32 v[4:5], v[36:37], v[104:105], v[4:5] op_sel_hi:[0,1,1]
	v_pk_fma_f32 v[4:5], v[36:37], v[106:107], v[4:5] op_sel:[1,0,0] op_sel_hi:[1,1,1]
	ds_read_b64 v[36:37], v138 offset:4240
	s_waitcnt lgkmcnt(15)
	v_pk_fma_f32 v[6:7], v[38:39], v[104:105], v[6:7] op_sel_hi:[0,1,1]
	v_pk_fma_f32 v[6:7], v[38:39], v[106:107], v[6:7] op_sel:[1,0,0] op_sel_hi:[1,1,1]
	ds_read_b64 v[38:39], v138 offset:8464
	s_waitcnt lgkmcnt(15)
	v_pk_fma_f32 v[8:9], v[40:41], v[104:105], v[8:9] op_sel_hi:[0,1,1]
	v_pk_fma_f32 v[8:9], v[40:41], v[106:107], v[8:9] op_sel:[1,0,0] op_sel_hi:[1,1,1]
	ds_read_b64 v[40:41], v138 offset:12688
	s_waitcnt lgkmcnt(15)
	v_pk_fma_f32 v[10:11], v[42:43], v[104:105], v[10:11] op_sel_hi:[0,1,1]
	v_pk_fma_f32 v[10:11], v[42:43], v[106:107], v[10:11] op_sel:[1,0,0] op_sel_hi:[1,1,1]
	ds_read_b64 v[42:43], v138 offset:16912
	s_waitcnt lgkmcnt(15)
	v_pk_fma_f32 v[12:13], v[44:45], v[104:105], v[12:13] op_sel_hi:[0,1,1]
	v_pk_fma_f32 v[12:13], v[44:45], v[106:107], v[12:13] op_sel:[1,0,0] op_sel_hi:[1,1,1]
	ds_read_b64 v[44:45], v138 offset:21136
	s_waitcnt lgkmcnt(15)
	v_pk_fma_f32 v[14:15], v[46:47], v[104:105], v[14:15] op_sel_hi:[0,1,1]
	v_pk_fma_f32 v[14:15], v[46:47], v[106:107], v[14:15] op_sel:[1,0,0] op_sel_hi:[1,1,1]
	ds_read_b64 v[46:47], v138 offset:25360
	s_waitcnt lgkmcnt(15)
	v_pk_fma_f32 v[16:17], v[48:49], v[104:105], v[16:17] op_sel_hi:[0,1,1]
	v_pk_fma_f32 v[16:17], v[48:49], v[106:107], v[16:17] op_sel:[1,0,0] op_sel_hi:[1,1,1]
	ds_read_b64 v[48:49], v138 offset:29584
	s_waitcnt lgkmcnt(15)
	v_pk_fma_f32 v[18:19], v[84:85], v[104:105], v[18:19] op_sel_hi:[0,1,1]
	v_pk_fma_f32 v[18:19], v[84:85], v[106:107], v[18:19] op_sel:[1,0,0] op_sel_hi:[1,1,1]
	ds_read_b64 v[84:85], v138 offset:33808
	s_waitcnt lgkmcnt(15)
; __device__ __forceinline__ float bflo(unsigned w) { return __uint_as_float(w << 16); }
; __device__ __forceinline__ float bfhi(unsigned w) { return __uint_as_float(w & 0xffff0000u); }
; template <int BR>
; __device__ __forceinline__ void sample_unit(const SampP& P, int bs, int h, char* lds, float lam) {
;     ...
; #pragma unroll 1
;     for (int k5 = 0; k5 < 13; ++k5) { const int keyb = 130 * wid + 10 * k5 + hf;
;       f32x4 v[5];
; #pragma unroll
;       for (int e = 0; e < 5; ++e) { const int key = keyb + 2 * e;
;         if (key < PAST) v[e] = *(const f32x4*)(Vc + (size_t)key * 1024 + 4 * l31);
;         else { const u32x2 w = *(const u32x2*)(Vn + (size_t)(key - PAST) * 1024 + 4 * l31); v[e] = (f32x4){bflo(w.x), bfhi(w.x), bflo(w.y), bfhi(w.y)}; } }
; #pragma unroll
;       for (int e = 0; e < 5; ++e) { const float* sp = S1 + keyb + 2 * e;
; #pragma unroll
;         for (int q = 0; q < 16; ++q) acc[q] += sp[q * SST] * v[e];
;         asm volatile("" ::: "memory"); }
	v_pk_fma_f32 v[20:21], v[86:87], v[104:105], v[20:21] op_sel_hi:[0,1,1]
	v_pk_fma_f32 v[20:21], v[86:87], v[106:107], v[20:21] op_sel:[1,0,0] op_sel_hi:[1,1,1]
	ds_read_b64 v[86:87], v138 offset:38032
	s_waitcnt lgkmcnt(15)
	v_pk_fma_f32 v[22:23], v[88:89], v[104:105], v[22:23] op_sel_hi:[0,1,1]
	v_pk_fma_f32 v[22:23], v[88:89], v[106:107], v[22:23] op_sel:[1,0,0] op_sel_hi:[1,1,1]
	ds_read_b64 v[88:89], v138 offset:42256
	s_waitcnt lgkmcnt(15)
	v_pk_fma_f32 v[24:25], v[90:91], v[104:105], v[24:25] op_sel_hi:[0,1,1]
	v_pk_fma_f32 v[24:25], v[90:91], v[106:107], v[24:25] op_sel:[1,0,0] op_sel_hi:[1,1,1]
	ds_read_b64 v[90:91], v138 offset:46480
	s_waitcnt lgkmcnt(15)
	v_pk_fma_f32 v[26:27], v[92:93], v[104:105], v[26:27] op_sel_hi:[0,1,1]
	v_pk_fma_f32 v[26:27], v[92:93], v[106:107], v[26:27] op_sel:[1,0,0] op_sel_hi:[1,1,1]
	ds_read_b64 v[92:93], v138 offset:50704
	s_waitcnt lgkmcnt(15)
	v_pk_fma_f32 v[28:29], v[94:95], v[104:105], v[28:29] op_sel_hi:[0,1,1]
	v_pk_fma_f32 v[28:29], v[94:95], v[106:107], v[28:29] op_sel:[1,0,0] op_sel_hi:[1,1,1]
	ds_read_b64 v[94:95], v138 offset:54928
	s_waitcnt lgkmcnt(15)
	v_pk_fma_f32 v[30:31], v[96:97], v[104:105], v[30:31] op_sel_hi:[0,1,1]
	v_pk_fma_f32 v[30:31], v[96:97], v[106:107], v[30:31] op_sel:[1,0,0] op_sel_hi:[1,1,1]
	ds_read_b64 v[96:97], v138 offset:59152
	s_waitcnt lgkmcnt(15)
	v_pk_fma_f32 v[32:33], v[98:99], v[104:105], v[32:33] op_sel_hi:[0,1,1]
	v_pk_fma_f32 v[32:33], v[98:99], v[106:107], v[32:33] op_sel:[1,0,0] op_sel_hi:[1,1,1]
	ds_read_b64 v[98:99], v138 offset:63376
	s_waitcnt vmcnt(12)
	s_waitcnt lgkmcnt(15)
	v_pk_fma_f32 v[2:3], v[34:35], v[108:109], v[2:3] op_sel_hi:[0,1,1]
	v_pk_fma_f32 v[2:3], v[34:35], v[110:111], v[2:3] op_sel:[1,0,0] op_sel_hi:[1,1,1]
	ds_read_b64 v[34:35], v138 offset:24
	s_waitcnt lgkmcnt(15)
	v_pk_fma_f32 v[4:5], v[36:37], v[108:109], v[4:5] op_sel_hi:[0,1,1]
	v_pk_fma_f32 v[4:5], v[36:37], v[110:111], v[4:5] op_sel:[1,0,0] op_sel_hi:[1,1,1]
	ds_read_b64 v[36:37], v138 offset:4248
	s_waitcnt lgkmcnt(15)
	v_pk_fma_f32 v[6:7], v[38:39], v[108:109], v[6:7] op_sel_hi:[0,1,1]
	v_pk_fma_f32 v[6:7], v[38:39], v[110:111], v[6:7] op_sel:[1,0,0] op_sel_hi:[1,1,1]
	ds_read_b64 v[38:39], v138 offset:8472
	s_waitcnt lgkmcnt(15)
	v_pk_fma_f32 v[8:9], v[40:41], v[108:109], v[8:9] op_sel_hi:[0,1,1]
	v_pk_fma_f32 v[8:9], v[40:41], v[110:111], v[8:9] op_sel:[1,0,0] op_sel_hi:[1,1,1]
	ds_read_b64 v[40:41], v138 offset:12696
	s_waitcnt lgkmcnt(15)
	v_pk_fma_f32 v[10:11], v[42:43], v[108:109], v[10:11] op_sel_hi:[0,1,1]
	v_pk_fma_f32 v[10:11], v[42:43], v[110:111], v[10:11] op_sel:[1,0,0] op_sel_hi:[1,1,1]
	ds_read_b64 v[42:43], v138 offset:16920
	s_waitcnt lgkmcnt(15)
	v_pk_fma_f32 v[12:13], v[44:45], v[108:109], v[12:13] op_sel_hi:[0,1,1]
	v_pk_fma_f32 v[12:13], v[44:45], v[110:111], v[12:13] op_sel:[1,0,0] op_sel_hi:[1,1,1]
	ds_read_b64 v[44:45], v138 offset:21144
	s_waitcnt lgkmcnt(15)
	v_pk_fma_f32 v[14:15], v[46:47], v[108:109], v[14:15] op_sel_hi:[0,1,1]
	v_pk_fma_f32 v[14:15], v[46:47], v[110:111], v[14:15] op_sel:[1,0,0] op_sel_hi:[1,1,1]
	ds_read_b64 v[46:47], v138 offset:25368
	s_waitcnt lgkmcnt(15)
	v_pk_fma_f32 v[16:17], v[48:49], v[108:109], v[16:17] op_sel_hi:[0,1,1]
	v_pk_fma_f32 v[16:17], v[48:49], v[110:111], v[16:17] op_sel:[1,0,0] op_sel_hi:[1,1,1]
	ds_read_b64 v[48:49], v138 offset:29592
	s_waitcnt lgkmcnt(15)
	v_pk_fma_f32 v[18:19], v[84:85], v[108:109], v[18:19] op_sel_hi:[0,1,1]
	v_pk_fma_f32 v[18:19], v[84:85], v[110:111], v[18:19] op_sel:[1,0,0] op_sel_hi:[1,1,1]
	ds_read_b64 v[84:85], v138 offset:33816
	s_waitcnt lgkmcnt(15)
	v_pk_fma_f32 v[20:21], v[86:87], v[108:109], v[20:21] op_sel_hi:[0,1,1]
	v_pk_fma_f32 v[20:21], v[86:87], v[110:111], v[20:21] op_sel:[1,0,0] op_sel_hi:[1,1,1]
	ds_read_b64 v[86:87], v138 offset:38040
	s_waitcnt lgkmcnt(15)
	v_pk_fma_f32 v[22:23], v[88:89], v[108:109], v[22:23] op_sel_hi:[0,1,1]
	v_pk_fma_f32 v[22:23], v[88:89], v[110:111], v[22:23] op_sel:[1,0,0] op_sel_hi:[1,1,1]
	ds_read_b64 v[88:89], v138 offset:42264
	s_waitcnt lgkmcnt(15)
	v_pk_fma_f32 v[24:25], v[90:91], v[108:109], v[24:25] op_sel_hi:[0,1,1]
	v_pk_fma_f32 v[24:25], v[90:91], v[110:111], v[24:25] op_sel:[1,0,0] op_sel_hi:[1,1,1]
	ds_read_b64 v[90:91], v138 offset:46488
	s_waitcnt lgkmcnt(15)
	v_pk_fma_f32 v[26:27], v[92:93], v[108:109], v[26:27] op_sel_hi:[0,1,1]
	v_pk_fma_f32 v[26:27], v[92:93], v[110:111], v[26:27] op_sel:[1,0,0] op_sel_hi:[1,1,1]
	ds_read_b64 v[92:93], v138 offset:50712
	s_waitcnt lgkmcnt(15)
	v_pk_fma_f32 v[28:29], v[94:95], v[108:109], v[28:29] op_sel_hi:[0,1,1]
	v_pk_fma_f32 v[28:29], v[94:95], v[110:111], v[28:29] op_sel:[1,0,0] op_sel_hi:[1,1,1]
	ds_read_b64 v[94:95], v138 offset:54936
	s_waitcnt lgkmcnt(15)
	v_pk_fma_f32 v[30:31], v[96:97], v[108:109], v[30:31] op_sel_hi:[0,1,1]
	v_pk_fma_f32 v[30:31], v[96:97], v[110:111], v[30:31] op_sel:[1,0,0] op_sel_hi:[1,1,1]
	ds_read_b64 v[96:97], v138 offset:59160
	s_waitcnt lgkmcnt(15)
	v_pk_fma_f32 v[32:33], v[98:99], v[108:109], v[32:33] op_sel_hi:[0,1,1]
	v_pk_fma_f32 v[32:33], v[98:99], v[110:111], v[32:33] op_sel:[1,0,0] op_sel_hi:[1,1,1]
	ds_read_b64 v[98:99], v138 offset:63384
	s_waitcnt vmcnt(10)
	s_waitcnt lgkmcnt(15)
	v_pk_fma_f32 v[2:3], v[34:35], v[112:113], v[2:3] op_sel_hi:[0,1,1]
	v_pk_fma_f32 v[2:3], v[34:35], v[114:115], v[2:3] op_sel:[1,0,0] op_sel_hi:[1,1,1]
	ds_read_b64 v[34:35], v138 offset:32
	s_waitcnt lgkmcnt(15)
	v_pk_fma_f32 v[4:5], v[36:37], v[112:113], v[4:5] op_sel_hi:[0,1,1]
	v_pk_fma_f32 v[4:5], v[36:37], v[114:115], v[4:5] op_sel:[1,0,0] op_sel_hi:[1,1,1]
	ds_read_b64 v[36:37], v138 offset:4256
	s_waitcnt lgkmcnt(15)
; __device__ __forceinline__ float bflo(unsigned w) { return __uint_as_float(w << 16); }
; __device__ __forceinline__ float bfhi(unsigned w) { return __uint_as_float(w & 0xffff0000u); }
; template <int BR>
; __device__ __forceinline__ void sample_unit(const SampP& P, int bs, int h, char* lds, float lam) {
;     ...
;   { const int hf = lane >> 5, l31 = lane & 31;
;     f32x4 acc[16];
; #pragma unroll
;     for (int q = 0; q < 16; ++q) acc[q] = (f32x4){0.f, 0.f, 0.f, 0.f};
; #pragma unroll 1
;     for (int k5 = 0; k5 < 13; ++k5) { const int keyb = 130 * wid + 10 * k5 + hf;
;       f32x4 v[5];
; #pragma unroll
;       for (int e = 0; e < 5; ++e) { const int key = keyb + 2 * e;
;         if (key < PAST) v[e] = *(const f32x4*)(Vc + (size_t)key * 1024 + 4 * l31);
;         else { const u32x2 w = *(const u32x2*)(Vn + (size_t)(key - PAST) * 1024 + 4 * l31); v[e] = (f32x4){bflo(w.x), bfhi(w.x), bflo(w.y), bfhi(w.y)}; } }
; #pragma unroll
;       for (int e = 0; e < 5; ++e) { const float* sp = S1 + keyb + 2 * e;
; #pragma unroll
;         for (int q = 0; q < 16; ++q) acc[q] += sp[q * SST] * v[e];
;         asm volatile("" ::: "memory"); }
;     }
	v_pk_fma_f32 v[6:7], v[38:39], v[112:113], v[6:7] op_sel_hi:[0,1,1]
	v_pk_fma_f32 v[6:7], v[38:39], v[114:115], v[6:7] op_sel:[1,0,0] op_sel_hi:[1,1,1]
	ds_read_b64 v[38:39], v138 offset:8480
	s_waitcnt lgkmcnt(15)
	v_pk_fma_f32 v[8:9], v[40:41], v[112:113], v[8:9] op_sel_hi:[0,1,1]
	v_pk_fma_f32 v[8:9], v[40:41], v[114:115], v[8:9] op_sel:[1,0,0] op_sel_hi:[1,1,1]
	ds_read_b64 v[40:41], v138 offset:12704
	s_waitcnt lgkmcnt(15)
	v_pk_fma_f32 v[10:11], v[42:43], v[112:113], v[10:11] op_sel_hi:[0,1,1]
	v_pk_fma_f32 v[10:11], v[42:43], v[114:115], v[10:11] op_sel:[1,0,0] op_sel_hi:[1,1,1]
	ds_read_b64 v[42:43], v138 offset:16928
	s_waitcnt lgkmcnt(15)
	v_pk_fma_f32 v[12:13], v[44:45], v[112:113], v[12:13] op_sel_hi:[0,1,1]
	v_pk_fma_f32 v[12:13], v[44:45], v[114:115], v[12:13] op_sel:[1,0,0] op_sel_hi:[1,1,1]
	ds_read_b64 v[44:45], v138 offset:21152
	s_waitcnt lgkmcnt(15)
	v_pk_fma_f32 v[14:15], v[46:47], v[112:113], v[14:15] op_sel_hi:[0,1,1]
	v_pk_fma_f32 v[14:15], v[46:47], v[114:115], v[14:15] op_sel:[1,0,0] op_sel_hi:[1,1,1]
	ds_read_b64 v[46:47], v138 offset:25376
	s_waitcnt lgkmcnt(15)
	v_pk_fma_f32 v[16:17], v[48:49], v[112:113], v[16:17] op_sel_hi:[0,1,1]
	v_pk_fma_f32 v[16:17], v[48:49], v[114:115], v[16:17] op_sel:[1,0,0] op_sel_hi:[1,1,1]
	ds_read_b64 v[48:49], v138 offset:29600
	s_waitcnt lgkmcnt(15)
	v_pk_fma_f32 v[18:19], v[84:85], v[112:113], v[18:19] op_sel_hi:[0,1,1]
	v_pk_fma_f32 v[18:19], v[84:85], v[114:115], v[18:19] op_sel:[1,0,0] op_sel_hi:[1,1,1]
	ds_read_b64 v[84:85], v138 offset:33824
	s_waitcnt lgkmcnt(15)
	v_pk_fma_f32 v[20:21], v[86:87], v[112:113], v[20:21] op_sel_hi:[0,1,1]
	v_pk_fma_f32 v[20:21], v[86:87], v[114:115], v[20:21] op_sel:[1,0,0] op_sel_hi:[1,1,1]
	ds_read_b64 v[86:87], v138 offset:38048
	s_waitcnt lgkmcnt(15)
	v_pk_fma_f32 v[22:23], v[88:89], v[112:113], v[22:23] op_sel_hi:[0,1,1]
	v_pk_fma_f32 v[22:23], v[88:89], v[114:115], v[22:23] op_sel:[1,0,0] op_sel_hi:[1,1,1]
	ds_read_b64 v[88:89], v138 offset:42272
	s_waitcnt lgkmcnt(15)
	v_pk_fma_f32 v[24:25], v[90:91], v[112:113], v[24:25] op_sel_hi:[0,1,1]
	v_pk_fma_f32 v[24:25], v[90:91], v[114:115], v[24:25] op_sel:[1,0,0] op_sel_hi:[1,1,1]
	ds_read_b64 v[90:91], v138 offset:46496
	s_waitcnt lgkmcnt(15)
	v_pk_fma_f32 v[26:27], v[92:93], v[112:113], v[26:27] op_sel_hi:[0,1,1]
	v_pk_fma_f32 v[26:27], v[92:93], v[114:115], v[26:27] op_sel:[1,0,0] op_sel_hi:[1,1,1]
	ds_read_b64 v[92:93], v138 offset:50720
	s_waitcnt lgkmcnt(15)
	v_pk_fma_f32 v[28:29], v[94:95], v[112:113], v[28:29] op_sel_hi:[0,1,1]
	v_pk_fma_f32 v[28:29], v[94:95], v[114:115], v[28:29] op_sel:[1,0,0] op_sel_hi:[1,1,1]
	ds_read_b64 v[94:95], v138 offset:54944
	s_waitcnt lgkmcnt(15)
	v_pk_fma_f32 v[30:31], v[96:97], v[112:113], v[30:31] op_sel_hi:[0,1,1]
	v_pk_fma_f32 v[30:31], v[96:97], v[114:115], v[30:31] op_sel:[1,0,0] op_sel_hi:[1,1,1]
	ds_read_b64 v[96:97], v138 offset:59168
	s_waitcnt lgkmcnt(15)
	v_pk_fma_f32 v[32:33], v[98:99], v[112:113], v[32:33] op_sel_hi:[0,1,1]
	v_pk_fma_f32 v[32:33], v[98:99], v[114:115], v[32:33] op_sel:[1,0,0] op_sel_hi:[1,1,1]
	ds_read_b64 v[98:99], v138 offset:63392
	s_waitcnt vmcnt(8)
	s_waitcnt lgkmcnt(15)
	v_pk_fma_f32 v[2:3], v[34:35], v[116:117], v[2:3] op_sel_hi:[0,1,1]
	v_pk_fma_f32 v[2:3], v[34:35], v[118:119], v[2:3] op_sel:[1,0,0] op_sel_hi:[1,1,1]
	ds_read_b64 v[34:35], v138 offset:40
	s_waitcnt lgkmcnt(15)
	v_pk_fma_f32 v[4:5], v[36:37], v[116:117], v[4:5] op_sel_hi:[0,1,1]
	v_pk_fma_f32 v[4:5], v[36:37], v[118:119], v[4:5] op_sel:[1,0,0] op_sel_hi:[1,1,1]
	ds_read_b64 v[36:37], v138 offset:4264
	s_waitcnt lgkmcnt(15)
	v_pk_fma_f32 v[6:7], v[38:39], v[116:117], v[6:7] op_sel_hi:[0,1,1]
	v_pk_fma_f32 v[6:7], v[38:39], v[118:119], v[6:7] op_sel:[1,0,0] op_sel_hi:[1,1,1]
	ds_read_b64 v[38:39], v138 offset:8488
	s_waitcnt lgkmcnt(15)
	v_pk_fma_f32 v[8:9], v[40:41], v[116:117], v[8:9] op_sel_hi:[0,1,1]
	v_pk_fma_f32 v[8:9], v[40:41], v[118:119], v[8:9] op_sel:[1,0,0] op_sel_hi:[1,1,1]
	ds_read_b64 v[40:41], v138 offset:12712
	s_waitcnt lgkmcnt(15)
	v_pk_fma_f32 v[10:11], v[42:43], v[116:117], v[10:11] op_sel_hi:[0,1,1]
	v_pk_fma_f32 v[10:11], v[42:43], v[118:119], v[10:11] op_sel:[1,0,0] op_sel_hi:[1,1,1]
	ds_read_b64 v[42:43], v138 offset:16936
	s_waitcnt lgkmcnt(15)
	v_pk_fma_f32 v[12:13], v[44:45], v[116:117], v[12:13] op_sel_hi:[0,1,1]
	v_pk_fma_f32 v[12:13], v[44:45], v[118:119], v[12:13] op_sel:[1,0,0] op_sel_hi:[1,1,1]
	ds_read_b64 v[44:45], v138 offset:21160
	s_waitcnt lgkmcnt(15)
	v_pk_fma_f32 v[14:15], v[46:47], v[116:117], v[14:15] op_sel_hi:[0,1,1]
	v_pk_fma_f32 v[14:15], v[46:47], v[118:119], v[14:15] op_sel:[1,0,0] op_sel_hi:[1,1,1]
	ds_read_b64 v[46:47], v138 offset:25384
	s_waitcnt lgkmcnt(15)
	v_pk_fma_f32 v[16:17], v[48:49], v[116:117], v[16:17] op_sel_hi:[0,1,1]
	v_pk_fma_f32 v[16:17], v[48:49], v[118:119], v[16:17] op_sel:[1,0,0] op_sel_hi:[1,1,1]
	ds_read_b64 v[48:49], v138 offset:29608
	s_waitcnt lgkmcnt(15)
	v_pk_fma_f32 v[18:19], v[84:85], v[116:117], v[18:19] op_sel_hi:[0,1,1]
	v_pk_fma_f32 v[18:19], v[84:85], v[118:119], v[18:19] op_sel:[1,0,0] op_sel_hi:[1,1,1]
	ds_read_b64 v[84:85], v138 offset:33832
	s_waitcnt lgkmcnt(15)
	v_pk_fma_f32 v[20:21], v[86:87], v[116:117], v[20:21] op_sel_hi:[0,1,1]
	v_pk_fma_f32 v[20:21], v[86:87], v[118:119], v[20:21] op_sel:[1,0,0] op_sel_hi:[1,1,1]
	ds_read_b64 v[86:87], v138 offset:38056
	s_waitcnt lgkmcnt(15)
	v_pk_fma_f32 v[22:23], v[88:89], v[116:117], v[22:23] op_sel_hi:[0,1,1]
	v_pk_fma_f32 v[22:23], v[88:89], v[118:119], v[22:23] op_sel:[1,0,0] op_sel_hi:[1,1,1]
	ds_read_b64 v[88:89], v138 offset:42280
	s_waitcnt lgkmcnt(15)
; __device__ __forceinline__ float bflo(unsigned w) { return __uint_as_float(w << 16); }
; __device__ __forceinline__ float bfhi(unsigned w) { return __uint_as_float(w & 0xffff0000u); }
; template <int BR>
; __device__ __forceinline__ void sample_unit(const SampP& P, int bs, int h, char* lds, float lam) {
;     ...
;   { const int hf = lane >> 5, l31 = lane & 31;
;     f32x4 acc[16];
; #pragma unroll
;     for (int q = 0; q < 16; ++q) acc[q] = (f32x4){0.f, 0.f, 0.f, 0.f};
; #pragma unroll 1
;     for (int k5 = 0; k5 < 13; ++k5) { const int keyb = 130 * wid + 10 * k5 + hf;
;       f32x4 v[5];
; #pragma unroll
;       for (int e = 0; e < 5; ++e) { const int key = keyb + 2 * e;
;         if (key < PAST) v[e] = *(const f32x4*)(Vc + (size_t)key * 1024 + 4 * l31);
;         else { const u32x2 w = *(const u32x2*)(Vn + (size_t)(key - PAST) * 1024 + 4 * l31); v[e] = (f32x4){bflo(w.x), bfhi(w.x), bflo(w.y), bfhi(w.y)}; } }
; #pragma unroll
;       for (int e = 0; e < 5; ++e) { const float* sp = S1 + keyb + 2 * e;
; #pragma unroll
;         for (int q = 0; q < 16; ++q) acc[q] += sp[q * SST] * v[e];
;         asm volatile("" ::: "memory"); }
;     }
	v_pk_fma_f32 v[24:25], v[90:91], v[116:117], v[24:25] op_sel_hi:[0,1,1]
	v_pk_fma_f32 v[24:25], v[90:91], v[118:119], v[24:25] op_sel:[1,0,0] op_sel_hi:[1,1,1]
	ds_read_b64 v[90:91], v138 offset:46504
	s_waitcnt lgkmcnt(15)
	v_pk_fma_f32 v[26:27], v[92:93], v[116:117], v[26:27] op_sel_hi:[0,1,1]
	v_pk_fma_f32 v[26:27], v[92:93], v[118:119], v[26:27] op_sel:[1,0,0] op_sel_hi:[1,1,1]
	ds_read_b64 v[92:93], v138 offset:50728
	s_waitcnt lgkmcnt(15)
	v_pk_fma_f32 v[28:29], v[94:95], v[116:117], v[28:29] op_sel_hi:[0,1,1]
	v_pk_fma_f32 v[28:29], v[94:95], v[118:119], v[28:29] op_sel:[1,0,0] op_sel_hi:[1,1,1]
	ds_read_b64 v[94:95], v138 offset:54952
	s_waitcnt lgkmcnt(15)
	v_pk_fma_f32 v[30:31], v[96:97], v[116:117], v[30:31] op_sel_hi:[0,1,1]
	v_pk_fma_f32 v[30:31], v[96:97], v[118:119], v[30:31] op_sel:[1,0,0] op_sel_hi:[1,1,1]
	ds_read_b64 v[96:97], v138 offset:59176
	s_waitcnt lgkmcnt(15)
	v_pk_fma_f32 v[32:33], v[98:99], v[116:117], v[32:33] op_sel_hi:[0,1,1]
	v_pk_fma_f32 v[32:33], v[98:99], v[118:119], v[32:33] op_sel:[1,0,0] op_sel_hi:[1,1,1]
	ds_read_b64 v[98:99], v138 offset:63400
	s_waitcnt vmcnt(6)
	s_waitcnt lgkmcnt(15)
	v_pk_fma_f32 v[2:3], v[34:35], v[120:121], v[2:3] op_sel_hi:[0,1,1]
	v_pk_fma_f32 v[2:3], v[34:35], v[122:123], v[2:3] op_sel:[1,0,0] op_sel_hi:[1,1,1]
	ds_read_b64 v[34:35], v138 offset:48
	s_waitcnt lgkmcnt(15)
	v_pk_fma_f32 v[4:5], v[36:37], v[120:121], v[4:5] op_sel_hi:[0,1,1]
	v_pk_fma_f32 v[4:5], v[36:37], v[122:123], v[4:5] op_sel:[1,0,0] op_sel_hi:[1,1,1]
	ds_read_b64 v[36:37], v138 offset:4272
	s_waitcnt lgkmcnt(15)
	v_pk_fma_f32 v[6:7], v[38:39], v[120:121], v[6:7] op_sel_hi:[0,1,1]
	v_pk_fma_f32 v[6:7], v[38:39], v[122:123], v[6:7] op_sel:[1,0,0] op_sel_hi:[1,1,1]
	ds_read_b64 v[38:39], v138 offset:8496
	s_waitcnt lgkmcnt(15)
	v_pk_fma_f32 v[8:9], v[40:41], v[120:121], v[8:9] op_sel_hi:[0,1,1]
	v_pk_fma_f32 v[8:9], v[40:41], v[122:123], v[8:9] op_sel:[1,0,0] op_sel_hi:[1,1,1]
	ds_read_b64 v[40:41], v138 offset:12720
	s_waitcnt lgkmcnt(15)
	v_pk_fma_f32 v[10:11], v[42:43], v[120:121], v[10:11] op_sel_hi:[0,1,1]
	v_pk_fma_f32 v[10:11], v[42:43], v[122:123], v[10:11] op_sel:[1,0,0] op_sel_hi:[1,1,1]
	ds_read_b64 v[42:43], v138 offset:16944
	s_waitcnt lgkmcnt(15)
	v_pk_fma_f32 v[12:13], v[44:45], v[120:121], v[12:13] op_sel_hi:[0,1,1]
	v_pk_fma_f32 v[12:13], v[44:45], v[122:123], v[12:13] op_sel:[1,0,0] op_sel_hi:[1,1,1]
	ds_read_b64 v[44:45], v138 offset:21168
	s_waitcnt lgkmcnt(15)
	v_pk_fma_f32 v[14:15], v[46:47], v[120:121], v[14:15] op_sel_hi:[0,1,1]
	v_pk_fma_f32 v[14:15], v[46:47], v[122:123], v[14:15] op_sel:[1,0,0] op_sel_hi:[1,1,1]
	ds_read_b64 v[46:47], v138 offset:25392
	s_waitcnt lgkmcnt(15)
	v_pk_fma_f32 v[16:17], v[48:49], v[120:121], v[16:17] op_sel_hi:[0,1,1]
	v_pk_fma_f32 v[16:17], v[48:49], v[122:123], v[16:17] op_sel:[1,0,0] op_sel_hi:[1,1,1]
	ds_read_b64 v[48:49], v138 offset:29616
	s_waitcnt lgkmcnt(15)
	v_pk_fma_f32 v[18:19], v[84:85], v[120:121], v[18:19] op_sel_hi:[0,1,1]
	v_pk_fma_f32 v[18:19], v[84:85], v[122:123], v[18:19] op_sel:[1,0,0] op_sel_hi:[1,1,1]
	ds_read_b64 v[84:85], v138 offset:33840
	s_waitcnt lgkmcnt(15)
	v_pk_fma_f32 v[20:21], v[86:87], v[120:121], v[20:21] op_sel_hi:[0,1,1]
	v_pk_fma_f32 v[20:21], v[86:87], v[122:123], v[20:21] op_sel:[1,0,0] op_sel_hi:[1,1,1]
	ds_read_b64 v[86:87], v138 offset:38064
	s_waitcnt lgkmcnt(15)
	v_pk_fma_f32 v[22:23], v[88:89], v[120:121], v[22:23] op_sel_hi:[0,1,1]
	v_pk_fma_f32 v[22:23], v[88:89], v[122:123], v[22:23] op_sel:[1,0,0] op_sel_hi:[1,1,1]
	ds_read_b64 v[88:89], v138 offset:42288
	s_waitcnt lgkmcnt(15)
	v_pk_fma_f32 v[24:25], v[90:91], v[120:121], v[24:25] op_sel_hi:[0,1,1]
	v_pk_fma_f32 v[24:25], v[90:91], v[122:123], v[24:25] op_sel:[1,0,0] op_sel_hi:[1,1,1]
	ds_read_b64 v[90:91], v138 offset:46512
	s_waitcnt lgkmcnt(15)
	v_pk_fma_f32 v[26:27], v[92:93], v[120:121], v[26:27] op_sel_hi:[0,1,1]
	v_pk_fma_f32 v[26:27], v[92:93], v[122:123], v[26:27] op_sel:[1,0,0] op_sel_hi:[1,1,1]
	ds_read_b64 v[92:93], v138 offset:50736
	s_waitcnt lgkmcnt(15)
	v_pk_fma_f32 v[28:29], v[94:95], v[120:121], v[28:29] op_sel_hi:[0,1,1]
	v_pk_fma_f32 v[28:29], v[94:95], v[122:123], v[28:29] op_sel:[1,0,0] op_sel_hi:[1,1,1]
	ds_read_b64 v[94:95], v138 offset:54960
	s_waitcnt lgkmcnt(15)
	v_pk_fma_f32 v[30:31], v[96:97], v[120:121], v[30:31] op_sel_hi:[0,1,1]
	v_pk_fma_f32 v[30:31], v[96:97], v[122:123], v[30:31] op_sel:[1,0,0] op_sel_hi:[1,1,1]
	ds_read_b64 v[96:97], v138 offset:59184
	s_waitcnt lgkmcnt(15)
	v_pk_fma_f32 v[32:33], v[98:99], v[120:121], v[32:33] op_sel_hi:[0,1,1]
	v_pk_fma_f32 v[32:33], v[98:99], v[122:123], v[32:33] op_sel:[1,0,0] op_sel_hi:[1,1,1]
	ds_read_b64 v[98:99], v138 offset:63408
	s_waitcnt vmcnt(4)
	s_waitcnt lgkmcnt(15)
	v_pk_fma_f32 v[2:3], v[34:35], v[124:125], v[2:3] op_sel_hi:[0,1,1]
	v_pk_fma_f32 v[2:3], v[34:35], v[126:127], v[2:3] op_sel:[1,0,0] op_sel_hi:[1,1,1]
	ds_read_b64 v[34:35], v138 offset:56
	s_waitcnt lgkmcnt(15)
	v_pk_fma_f32 v[4:5], v[36:37], v[124:125], v[4:5] op_sel_hi:[0,1,1]
	v_pk_fma_f32 v[4:5], v[36:37], v[126:127], v[4:5] op_sel:[1,0,0] op_sel_hi:[1,1,1]
	ds_read_b64 v[36:37], v138 offset:4280
	s_waitcnt lgkmcnt(15)
	v_pk_fma_f32 v[6:7], v[38:39], v[124:125], v[6:7] op_sel_hi:[0,1,1]
	v_pk_fma_f32 v[6:7], v[38:39], v[126:127], v[6:7] op_sel:[1,0,0] op_sel_hi:[1,1,1]
	ds_read_b64 v[38:39], v138 offset:8504
	s_waitcnt lgkmcnt(15)
	v_pk_fma_f32 v[8:9], v[40:41], v[124:125], v[8:9] op_sel_hi:[0,1,1]
	v_pk_fma_f32 v[8:9], v[40:41], v[126:127], v[8:9] op_sel:[1,0,0] op_sel_hi:[1,1,1]
	ds_read_b64 v[40:41], v138 offset:12728
	s_waitcnt lgkmcnt(15)
; __device__ __forceinline__ float bflo(unsigned w) { return __uint_as_float(w << 16); }
; __device__ __forceinline__ float bfhi(unsigned w) { return __uint_as_float(w & 0xffff0000u); }
; template <int BR>
; __device__ __forceinline__ void sample_unit(const SampP& P, int bs, int h, char* lds, float lam) {
;     ...
;   { const int hf = lane >> 5, l31 = lane & 31;
;     f32x4 acc[16];
; #pragma unroll
;     for (int q = 0; q < 16; ++q) acc[q] = (f32x4){0.f, 0.f, 0.f, 0.f};
; #pragma unroll 1
;     for (int k5 = 0; k5 < 13; ++k5) { const int keyb = 130 * wid + 10 * k5 + hf;
;       f32x4 v[5];
; #pragma unroll
;       for (int e = 0; e < 5; ++e) { const int key = keyb + 2 * e;
;         if (key < PAST) v[e] = *(const f32x4*)(Vc + (size_t)key * 1024 + 4 * l31);
;         else { const u32x2 w = *(const u32x2*)(Vn + (size_t)(key - PAST) * 1024 + 4 * l31); v[e] = (f32x4){bflo(w.x), bfhi(w.x), bflo(w.y), bfhi(w.y)}; } }
; #pragma unroll
;       for (int e = 0; e < 5; ++e) { const float* sp = S1 + keyb + 2 * e;
; #pragma unroll
;         for (int q = 0; q < 16; ++q) acc[q] += sp[q * SST] * v[e];
;         asm volatile("" ::: "memory"); }
;     }
	v_pk_fma_f32 v[10:11], v[42:43], v[124:125], v[10:11] op_sel_hi:[0,1,1]
	v_pk_fma_f32 v[10:11], v[42:43], v[126:127], v[10:11] op_sel:[1,0,0] op_sel_hi:[1,1,1]
	ds_read_b64 v[42:43], v138 offset:16952
	s_waitcnt lgkmcnt(15)
	v_pk_fma_f32 v[12:13], v[44:45], v[124:125], v[12:13] op_sel_hi:[0,1,1]
	v_pk_fma_f32 v[12:13], v[44:45], v[126:127], v[12:13] op_sel:[1,0,0] op_sel_hi:[1,1,1]
	ds_read_b64 v[44:45], v138 offset:21176
	s_waitcnt lgkmcnt(15)
	v_pk_fma_f32 v[14:15], v[46:47], v[124:125], v[14:15] op_sel_hi:[0,1,1]
	v_pk_fma_f32 v[14:15], v[46:47], v[126:127], v[14:15] op_sel:[1,0,0] op_sel_hi:[1,1,1]
	ds_read_b64 v[46:47], v138 offset:25400
	s_waitcnt lgkmcnt(15)
	v_pk_fma_f32 v[16:17], v[48:49], v[124:125], v[16:17] op_sel_hi:[0,1,1]
	v_pk_fma_f32 v[16:17], v[48:49], v[126:127], v[16:17] op_sel:[1,0,0] op_sel_hi:[1,1,1]
	ds_read_b64 v[48:49], v138 offset:29624
	s_waitcnt lgkmcnt(15)
	v_pk_fma_f32 v[18:19], v[84:85], v[124:125], v[18:19] op_sel_hi:[0,1,1]
	v_pk_fma_f32 v[18:19], v[84:85], v[126:127], v[18:19] op_sel:[1,0,0] op_sel_hi:[1,1,1]
	ds_read_b64 v[84:85], v138 offset:33848
	s_waitcnt lgkmcnt(15)
	v_pk_fma_f32 v[20:21], v[86:87], v[124:125], v[20:21] op_sel_hi:[0,1,1]
	v_pk_fma_f32 v[20:21], v[86:87], v[126:127], v[20:21] op_sel:[1,0,0] op_sel_hi:[1,1,1]
	ds_read_b64 v[86:87], v138 offset:38072
	s_waitcnt lgkmcnt(15)
	v_pk_fma_f32 v[22:23], v[88:89], v[124:125], v[22:23] op_sel_hi:[0,1,1]
	v_pk_fma_f32 v[22:23], v[88:89], v[126:127], v[22:23] op_sel:[1,0,0] op_sel_hi:[1,1,1]
	ds_read_b64 v[88:89], v138 offset:42296
	s_waitcnt lgkmcnt(15)
	v_pk_fma_f32 v[24:25], v[90:91], v[124:125], v[24:25] op_sel_hi:[0,1,1]
	v_pk_fma_f32 v[24:25], v[90:91], v[126:127], v[24:25] op_sel:[1,0,0] op_sel_hi:[1,1,1]
	ds_read_b64 v[90:91], v138 offset:46520
	s_waitcnt lgkmcnt(15)
	v_pk_fma_f32 v[26:27], v[92:93], v[124:125], v[26:27] op_sel_hi:[0,1,1]
	v_pk_fma_f32 v[26:27], v[92:93], v[126:127], v[26:27] op_sel:[1,0,0] op_sel_hi:[1,1,1]
	ds_read_b64 v[92:93], v138 offset:50744
	s_waitcnt lgkmcnt(15)
	v_pk_fma_f32 v[28:29], v[94:95], v[124:125], v[28:29] op_sel_hi:[0,1,1]
	v_pk_fma_f32 v[28:29], v[94:95], v[126:127], v[28:29] op_sel:[1,0,0] op_sel_hi:[1,1,1]
	ds_read_b64 v[94:95], v138 offset:54968
	s_waitcnt lgkmcnt(15)
	v_pk_fma_f32 v[30:31], v[96:97], v[124:125], v[30:31] op_sel_hi:[0,1,1]
	v_pk_fma_f32 v[30:31], v[96:97], v[126:127], v[30:31] op_sel:[1,0,0] op_sel_hi:[1,1,1]
	ds_read_b64 v[96:97], v138 offset:59192
	s_waitcnt lgkmcnt(15)
	v_pk_fma_f32 v[32:33], v[98:99], v[124:125], v[32:33] op_sel_hi:[0,1,1]
	v_pk_fma_f32 v[32:33], v[98:99], v[126:127], v[32:33] op_sel:[1,0,0] op_sel_hi:[1,1,1]
	ds_read_b64 v[98:99], v138 offset:63416
	s_waitcnt vmcnt(2)
	s_waitcnt lgkmcnt(15)
	v_pk_fma_f32 v[2:3], v[34:35], v[128:129], v[2:3] op_sel_hi:[0,1,1]
	v_pk_fma_f32 v[2:3], v[34:35], v[130:131], v[2:3] op_sel:[1,0,0] op_sel_hi:[1,1,1]
	ds_read_b64 v[34:35], v139 offset:0
	s_waitcnt lgkmcnt(15)
	v_pk_fma_f32 v[4:5], v[36:37], v[128:129], v[4:5] op_sel_hi:[0,1,1]
	v_pk_fma_f32 v[4:5], v[36:37], v[130:131], v[4:5] op_sel:[1,0,0] op_sel_hi:[1,1,1]
	ds_read_b64 v[36:37], v139 offset:4224
	s_waitcnt lgkmcnt(15)
	v_pk_fma_f32 v[6:7], v[38:39], v[128:129], v[6:7] op_sel_hi:[0,1,1]
	v_pk_fma_f32 v[6:7], v[38:39], v[130:131], v[6:7] op_sel:[1,0,0] op_sel_hi:[1,1,1]
	ds_read_b64 v[38:39], v139 offset:8448
	s_waitcnt lgkmcnt(15)
	v_pk_fma_f32 v[8:9], v[40:41], v[128:129], v[8:9] op_sel_hi:[0,1,1]
	v_pk_fma_f32 v[8:9], v[40:41], v[130:131], v[8:9] op_sel:[1,0,0] op_sel_hi:[1,1,1]
	ds_read_b64 v[40:41], v139 offset:12672
	s_waitcnt lgkmcnt(15)
	v_pk_fma_f32 v[10:11], v[42:43], v[128:129], v[10:11] op_sel_hi:[0,1,1]
	v_pk_fma_f32 v[10:11], v[42:43], v[130:131], v[10:11] op_sel:[1,0,0] op_sel_hi:[1,1,1]
	ds_read_b64 v[42:43], v139 offset:16896
	s_waitcnt lgkmcnt(15)
	v_pk_fma_f32 v[12:13], v[44:45], v[128:129], v[12:13] op_sel_hi:[0,1,1]
	v_pk_fma_f32 v[12:13], v[44:45], v[130:131], v[12:13] op_sel:[1,0,0] op_sel_hi:[1,1,1]
	ds_read_b64 v[44:45], v139 offset:21120
	s_waitcnt lgkmcnt(15)
	v_pk_fma_f32 v[14:15], v[46:47], v[128:129], v[14:15] op_sel_hi:[0,1,1]
	v_pk_fma_f32 v[14:15], v[46:47], v[130:131], v[14:15] op_sel:[1,0,0] op_sel_hi:[1,1,1]
	ds_read_b64 v[46:47], v139 offset:25344
	s_waitcnt lgkmcnt(15)
	v_pk_fma_f32 v[16:17], v[48:49], v[128:129], v[16:17] op_sel_hi:[0,1,1]
	v_pk_fma_f32 v[16:17], v[48:49], v[130:131], v[16:17] op_sel:[1,0,0] op_sel_hi:[1,1,1]
	ds_read_b64 v[48:49], v139 offset:29568
	s_waitcnt lgkmcnt(15)
	v_pk_fma_f32 v[18:19], v[84:85], v[128:129], v[18:19] op_sel_hi:[0,1,1]
	v_pk_fma_f32 v[18:19], v[84:85], v[130:131], v[18:19] op_sel:[1,0,0] op_sel_hi:[1,1,1]
	ds_read_b64 v[84:85], v139 offset:33792
	s_waitcnt lgkmcnt(15)
	v_pk_fma_f32 v[20:21], v[86:87], v[128:129], v[20:21] op_sel_hi:[0,1,1]
	v_pk_fma_f32 v[20:21], v[86:87], v[130:131], v[20:21] op_sel:[1,0,0] op_sel_hi:[1,1,1]
	ds_read_b64 v[86:87], v139 offset:38016
	s_waitcnt lgkmcnt(15)
; __device__ __forceinline__ float bflo(unsigned w) { return __uint_as_float(w << 16); }
; __device__ __forceinline__ float bfhi(unsigned w) { return __uint_as_float(w & 0xffff0000u); }
; template <int BR>
; __device__ __forceinline__ void sample_unit(const SampP& P, int bs, int h, char* lds, float lam) {
;     ...
;   { const int hf = lane >> 5, l31 = lane & 31;
;     f32x4 acc[16];
; #pragma unroll
;     for (int q = 0; q < 16; ++q) acc[q] = (f32x4){0.f, 0.f, 0.f, 0.f};
; #pragma unroll 1
;     for (int k5 = 0; k5 < 13; ++k5) { const int keyb = 130 * wid + 10 * k5 + hf;
;       f32x4 v[5];
; #pragma unroll
;       for (int e = 0; e < 5; ++e) { const int key = keyb + 2 * e;
;         if (key < PAST) v[e] = *(const f32x4*)(Vc + (size_t)key * 1024 + 4 * l31);
;         else { const u32x2 w = *(const u32x2*)(Vn + (size_t)(key - PAST) * 1024 + 4 * l31); v[e] = (f32x4){bflo(w.x), bfhi(w.x), bflo(w.y), bfhi(w.y)}; } }
; #pragma unroll
;       for (int e = 0; e < 5; ++e) { const float* sp = S1 + keyb + 2 * e;
; #pragma unroll
;         for (int q = 0; q < 16; ++q) acc[q] += sp[q * SST] * v[e];
;         asm volatile("" ::: "memory"); }
;     }
; #pragma unroll
;     for (int q = 0; q < 16; ++q) {
; #pragma unroll
;       for (int i = 0; i < 4; ++i) acc[q][i] += __shfl_xor(acc[q][i], 32); }
;     __syncthreads();
;     if (hf == 0) {
; #pragma unroll
;       for (int q = 0; q < 16; ++q) *(f32x4*)(red + (wid * 16 + q) * 128 + 4 * l31) = acc[q]; }
	v_pk_fma_f32 v[22:23], v[88:89], v[128:129], v[22:23] op_sel_hi:[0,1,1]
	v_pk_fma_f32 v[22:23], v[88:89], v[130:131], v[22:23] op_sel:[1,0,0] op_sel_hi:[1,1,1]
	ds_read_b64 v[88:89], v139 offset:42240
	s_waitcnt lgkmcnt(15)
	v_pk_fma_f32 v[24:25], v[90:91], v[128:129], v[24:25] op_sel_hi:[0,1,1]
	v_pk_fma_f32 v[24:25], v[90:91], v[130:131], v[24:25] op_sel:[1,0,0] op_sel_hi:[1,1,1]
	ds_read_b64 v[90:91], v139 offset:46464
	s_waitcnt lgkmcnt(15)
	v_pk_fma_f32 v[26:27], v[92:93], v[128:129], v[26:27] op_sel_hi:[0,1,1]
	v_pk_fma_f32 v[26:27], v[92:93], v[130:131], v[26:27] op_sel:[1,0,0] op_sel_hi:[1,1,1]
	ds_read_b64 v[92:93], v139 offset:50688
	s_waitcnt lgkmcnt(15)
	v_pk_fma_f32 v[28:29], v[94:95], v[128:129], v[28:29] op_sel_hi:[0,1,1]
	v_pk_fma_f32 v[28:29], v[94:95], v[130:131], v[28:29] op_sel:[1,0,0] op_sel_hi:[1,1,1]
	ds_read_b64 v[94:95], v139 offset:54912
	s_waitcnt lgkmcnt(15)
	v_pk_fma_f32 v[30:31], v[96:97], v[128:129], v[30:31] op_sel_hi:[0,1,1]
	v_pk_fma_f32 v[30:31], v[96:97], v[130:131], v[30:31] op_sel:[1,0,0] op_sel_hi:[1,1,1]
	ds_read_b64 v[96:97], v139 offset:59136
	s_waitcnt lgkmcnt(15)
	v_pk_fma_f32 v[32:33], v[98:99], v[128:129], v[32:33] op_sel_hi:[0,1,1]
	v_pk_fma_f32 v[32:33], v[98:99], v[130:131], v[32:33] op_sel:[1,0,0] op_sel_hi:[1,1,1]
	ds_read_b64 v[98:99], v139 offset:63360
	s_waitcnt vmcnt(0)
	v_lshlrev_b32_e32 v144, 16, v141
	v_and_b32_e32 v145, 0xffff0000, v141
	v_lshlrev_b32_e32 v146, 16, v142
	v_and_b32_e32 v147, 0xffff0000, v142
	s_waitcnt lgkmcnt(15)
	v_pk_fma_f32 v[2:3], v[34:35], v[144:145], v[2:3] op_sel_hi:[0,1,1]
	v_pk_fma_f32 v[2:3], v[34:35], v[146:147], v[2:3] op_sel:[1,0,0] op_sel_hi:[1,1,1]
	s_waitcnt lgkmcnt(14)
	v_pk_fma_f32 v[4:5], v[36:37], v[144:145], v[4:5] op_sel_hi:[0,1,1]
	v_pk_fma_f32 v[4:5], v[36:37], v[146:147], v[4:5] op_sel:[1,0,0] op_sel_hi:[1,1,1]
	s_waitcnt lgkmcnt(13)
	v_pk_fma_f32 v[6:7], v[38:39], v[144:145], v[6:7] op_sel_hi:[0,1,1]
	v_pk_fma_f32 v[6:7], v[38:39], v[146:147], v[6:7] op_sel:[1,0,0] op_sel_hi:[1,1,1]
	s_waitcnt lgkmcnt(12)
	v_pk_fma_f32 v[8:9], v[40:41], v[144:145], v[8:9] op_sel_hi:[0,1,1]
	v_pk_fma_f32 v[8:9], v[40:41], v[146:147], v[8:9] op_sel:[1,0,0] op_sel_hi:[1,1,1]
	s_waitcnt lgkmcnt(11)
	v_pk_fma_f32 v[10:11], v[42:43], v[144:145], v[10:11] op_sel_hi:[0,1,1]
	v_pk_fma_f32 v[10:11], v[42:43], v[146:147], v[10:11] op_sel:[1,0,0] op_sel_hi:[1,1,1]
	s_waitcnt lgkmcnt(10)
	v_pk_fma_f32 v[12:13], v[44:45], v[144:145], v[12:13] op_sel_hi:[0,1,1]
	v_pk_fma_f32 v[12:13], v[44:45], v[146:147], v[12:13] op_sel:[1,0,0] op_sel_hi:[1,1,1]
	s_waitcnt lgkmcnt(9)
	v_pk_fma_f32 v[14:15], v[46:47], v[144:145], v[14:15] op_sel_hi:[0,1,1]
	v_pk_fma_f32 v[14:15], v[46:47], v[146:147], v[14:15] op_sel:[1,0,0] op_sel_hi:[1,1,1]
	s_waitcnt lgkmcnt(8)
	v_pk_fma_f32 v[16:17], v[48:49], v[144:145], v[16:17] op_sel_hi:[0,1,1]
	v_pk_fma_f32 v[16:17], v[48:49], v[146:147], v[16:17] op_sel:[1,0,0] op_sel_hi:[1,1,1]
	s_waitcnt lgkmcnt(7)
	v_pk_fma_f32 v[18:19], v[84:85], v[144:145], v[18:19] op_sel_hi:[0,1,1]
	v_pk_fma_f32 v[18:19], v[84:85], v[146:147], v[18:19] op_sel:[1,0,0] op_sel_hi:[1,1,1]
	s_waitcnt lgkmcnt(6)
	v_pk_fma_f32 v[20:21], v[86:87], v[144:145], v[20:21] op_sel_hi:[0,1,1]
	v_pk_fma_f32 v[20:21], v[86:87], v[146:147], v[20:21] op_sel:[1,0,0] op_sel_hi:[1,1,1]
	s_waitcnt lgkmcnt(5)
	v_pk_fma_f32 v[22:23], v[88:89], v[144:145], v[22:23] op_sel_hi:[0,1,1]
	v_pk_fma_f32 v[22:23], v[88:89], v[146:147], v[22:23] op_sel:[1,0,0] op_sel_hi:[1,1,1]
	s_waitcnt lgkmcnt(4)
	v_pk_fma_f32 v[24:25], v[90:91], v[144:145], v[24:25] op_sel_hi:[0,1,1]
	v_pk_fma_f32 v[24:25], v[90:91], v[146:147], v[24:25] op_sel:[1,0,0] op_sel_hi:[1,1,1]
	s_waitcnt lgkmcnt(3)
	v_pk_fma_f32 v[26:27], v[92:93], v[144:145], v[26:27] op_sel_hi:[0,1,1]
	v_pk_fma_f32 v[26:27], v[92:93], v[146:147], v[26:27] op_sel:[1,0,0] op_sel_hi:[1,1,1]
	s_waitcnt lgkmcnt(2)
	v_pk_fma_f32 v[28:29], v[94:95], v[144:145], v[28:29] op_sel_hi:[0,1,1]
	v_pk_fma_f32 v[28:29], v[94:95], v[146:147], v[28:29] op_sel:[1,0,0] op_sel_hi:[1,1,1]
	s_waitcnt lgkmcnt(1)
	v_pk_fma_f32 v[30:31], v[96:97], v[144:145], v[30:31] op_sel_hi:[0,1,1]
	v_pk_fma_f32 v[30:31], v[96:97], v[146:147], v[30:31] op_sel:[1,0,0] op_sel_hi:[1,1,1]
	s_waitcnt lgkmcnt(0)
	v_pk_fma_f32 v[32:33], v[98:99], v[144:145], v[32:33] op_sel_hi:[0,1,1]
	v_pk_fma_f32 v[32:33], v[98:99], v[146:147], v[32:33] op_sel:[1,0,0] op_sel_hi:[1,1,1]
	ds_write_b64 v140, v[2:3] offset:0
	ds_write_b64 v140, v[4:5] offset:512
	ds_write_b64 v140, v[6:7] offset:1024
	ds_write_b64 v140, v[8:9] offset:1536
	ds_write_b64 v140, v[10:11] offset:2048
	ds_write_b64 v140, v[12:13] offset:2560
	ds_write_b64 v140, v[14:15] offset:3072
	ds_write_b64 v140, v[16:17] offset:3584
	ds_write_b64 v140, v[18:19] offset:4096
	ds_write_b64 v140, v[20:21] offset:4608
	ds_write_b64 v140, v[22:23] offset:5120
	ds_write_b64 v140, v[24:25] offset:5632
	ds_write_b64 v140, v[26:27] offset:6144
	ds_write_b64 v140, v[28:29] offset:6656
	ds_write_b64 v140, v[30:31] offset:7168
	ds_write_b64 v140, v[32:33] offset:7680

; __device__ __forceinline__ float bflo(unsigned w) { return __uint_as_float(w << 16); }
; __device__ __forceinline__ float bfhi(unsigned w) { return __uint_as_float(w & 0xffff0000u); }
; template <int BR>
; __device__ __forceinline__ void sample_unit(const SampP& P, int bs, int h, char* lds, float lam) {
;     ...
;   { const int hf = lane >> 5, l31 = lane & 31;
;     f32x4 acc[16];
; #pragma unroll
;     for (int q = 0; q < 16; ++q) acc[q] = (f32x4){0.f, 0.f, 0.f, 0.f};
; #pragma unroll 1
;     for (int k5 = 0; k5 < 13; ++k5) { const int keyb = 130 * wid + 10 * k5 + hf;
;       f32x4 v[5];
; #pragma unroll
;       for (int e = 0; e < 5; ++e) { const int key = keyb + 2 * e;
;         if (key < PAST) v[e] = *(const f32x4*)(Vc + (size_t)key * 1024 + 4 * l31);
;         else { const u32x2 w = *(const u32x2*)(Vn + (size_t)(key - PAST) * 1024 + 4 * l31); v[e] = (f32x4){bflo(w.x), bfhi(w.x), bflo(w.y), bfhi(w.y)}; } }
; #pragma unroll
;       for (int e = 0; e < 5; ++e) { const float* sp = S1 + keyb + 2 * e;
; #pragma unroll
;         for (int q = 0; q < 16; ++q) acc[q] += sp[q * SST] * v[e];
;         asm volatile("" ::: "memory"); }
;     }
.LBB0_797:
	s_or_b64 exec, exec, s[0:1]
	s_mov_b64 exec, -1
	v_and_b32_e32 v141, 63, v1
	v_lshlrev_b32_e32 v132, 3, v141
	v_lshlrev_b32_e32 v142, 2, v141
	v_readlane_b32 s14, v251, 21
	v_readlane_b32 s0, v251, 9
	v_readlane_b32 s1, v251, 10
	s_nop 3
	s_lshl_b32 s2, s91, 22
	s_add_u32 s0, s0, s2
	s_addc_u32 s1, s1, 0
	s_lshl_b32 s2, s89, 2
	s_add_u32 s0, s0, s2
	s_addc_u32 s1, s1, 0
	s_lshl_b32 s2, s14, 19
	s_add_u32 s0, s0, s2
	s_addc_u32 s1, s1, 0
	s_add_u32 s0, s0, 0x800
	s_addc_u32 s1, s1, 0
	v_mov_b32_e32 v134, s0
	v_mov_b32_e32 v135, s1
	v_add_co_u32_e32 v134, vcc, v134, v132
	s_nop 1
	v_addc_co_u32_e32 v135, vcc, 0, v135, vcc
	v_readlane_b32 s0, v251, 26
	v_readlane_b32 s1, v251, 27
	s_nop 3
	s_add_u32 s0, s0, 0x13d00000
	s_addc_u32 s1, s1, 0
	s_lshl_b32 s2, s91, 15
	s_add_u32 s0, s0, s2
	s_addc_u32 s1, s1, 0
	s_lshl_b32 s2, s14, 12
	s_add_u32 s0, s0, s2
	s_addc_u32 s1, s1, 0
	s_lshl_b32 s2, s89, 1
	s_add_u32 s0, s0, s2
	s_addc_u32 s1, s1, 0
	v_mov_b32_e32 v136, s0
	v_mov_b32_e32 v137, s1
	v_add_co_u32_e32 v136, vcc, v136, v142
	s_nop 1
	v_addc_co_u32_e32 v137, vcc, 0, v137, vcc
	v_mov_b32_e32 v141, s14
	v_lshlrev_b32_e32 v138, 9, v141
	v_lshlrev_b32_e32 v139, 3, v141
	v_add_u32_e32 v139, 0x1000, v139
	v_lshlrev_b32_e32 v140, 13, v141
	v_add_u32_e32 v140, 0x10800, v140
	v_add_u32_e32 v140, v140, v132
	s_mov_b64 s[0:1], 0x2000
	global_load_dwordx2 v[100:101], v[134:135], off offset:-2048
	global_load_dwordx2 v[102:103], v[134:135], off offset:2048
	v_lshl_add_u64 v[134:135], v[134:135], 0, s[0:1]
	global_load_dwordx2 v[104:105], v[134:135], off offset:-2048
	global_load_dwordx2 v[106:107], v[134:135], off offset:2048
	v_lshl_add_u64 v[134:135], v[134:135], 0, s[0:1]
	global_load_dwordx2 v[108:109], v[134:135], off offset:-2048
	global_load_dwordx2 v[110:111], v[134:135], off offset:2048
	v_lshl_add_u64 v[134:135], v[134:135], 0, s[0:1]
	global_load_dwordx2 v[112:113], v[134:135], off offset:-2048
	global_load_dwordx2 v[114:115], v[134:135], off offset:2048
	v_lshl_add_u64 v[134:135], v[134:135], 0, s[0:1]
	global_load_dwordx2 v[116:117], v[134:135], off offset:-2048
	global_load_dwordx2 v[118:119], v[134:135], off offset:2048
	v_lshl_add_u64 v[134:135], v[134:135], 0, s[0:1]
	global_load_dwordx2 v[120:121], v[134:135], off offset:-2048
	global_load_dwordx2 v[122:123], v[134:135], off offset:2048
	v_lshl_add_u64 v[134:135], v[134:135], 0, s[0:1]
	global_load_dwordx2 v[124:125], v[134:135], off offset:-2048
	global_load_dwordx2 v[126:127], v[134:135], off offset:2048
	v_lshl_add_u64 v[134:135], v[134:135], 0, s[0:1]
	global_load_dwordx2 v[128:129], v[134:135], off offset:-2048
	global_load_dwordx2 v[130:131], v[134:135], off offset:2048
	v_lshl_add_u64 v[134:135], v[134:135], 0, s[0:1]
	v_mov_b32_e32 v2, 0
	v_mov_b32_e32 v3, 0
	v_mov_b32_e32 v4, 0
	v_mov_b32_e32 v5, 0
	v_mov_b32_e32 v6, 0
	v_mov_b32_e32 v7, 0
	v_mov_b32_e32 v8, 0
	v_mov_b32_e32 v9, 0
	v_mov_b32_e32 v10, 0
	v_mov_b32_e32 v11, 0
	v_mov_b32_e32 v12, 0
	v_mov_b32_e32 v13, 0
	v_mov_b32_e32 v14, 0
	v_mov_b32_e32 v15, 0
	v_mov_b32_e32 v16, 0
	v_mov_b32_e32 v17, 0
	v_mov_b32_e32 v18, 0
	v_mov_b32_e32 v19, 0
	v_mov_b32_e32 v20, 0
	v_mov_b32_e32 v21, 0
	v_mov_b32_e32 v22, 0
	v_mov_b32_e32 v23, 0
	v_mov_b32_e32 v24, 0
	v_mov_b32_e32 v25, 0
	v_mov_b32_e32 v26, 0
	v_mov_b32_e32 v27, 0
	v_mov_b32_e32 v28, 0
	v_mov_b32_e32 v29, 0
	v_mov_b32_e32 v30, 0
	v_mov_b32_e32 v31, 0
	v_mov_b32_e32 v32, 0
	v_mov_b32_e32 v33, 0
	s_waitcnt lgkmcnt(0)
	s_barrier
	ds_read_b64 v[34:35], v138 offset:0
	ds_read_b64 v[36:37], v138 offset:4224
	ds_read_b64 v[38:39], v138 offset:8448
	ds_read_b64 v[40:41], v138 offset:12672
	ds_read_b64 v[42:43], v138 offset:16896
	ds_read_b64 v[44:45], v138 offset:21120
	ds_read_b64 v[46:47], v138 offset:25344
	ds_read_b64 v[48:49], v138 offset:29568
	ds_read_b64 v[84:85], v138 offset:33792
	ds_read_b64 v[86:87], v138 offset:38016
	ds_read_b64 v[88:89], v138 offset:42240
	ds_read_b64 v[90:91], v138 offset:46464
	ds_read_b64 v[92:93], v138 offset:50688
	ds_read_b64 v[94:95], v138 offset:54912
	ds_read_b64 v[96:97], v138 offset:59136
	ds_read_b64 v[98:99], v138 offset:63360
	s_mov_b32 s2, 0
.Lpvd_loop:
	s_waitcnt vmcnt(14)
	s_waitcnt lgkmcnt(15)
	v_pk_fma_f32 v[2:3], v[34:35], v[100:101], v[2:3] op_sel_hi:[0,1,1]
	v_pk_fma_f32 v[2:3], v[34:35], v[102:103], v[2:3] op_sel:[1,0,0] op_sel_hi:[1,1,1]
	ds_read_b64 v[34:35], v138 offset:8
	s_waitcnt lgkmcnt(15)
	v_pk_fma_f32 v[4:5], v[36:37], v[100:101], v[4:5] op_sel_hi:[0,1,1]
	v_pk_fma_f32 v[4:5], v[36:37], v[102:103], v[4:5] op_sel:[1,0,0] op_sel_hi:[1,1,1]
	ds_read_b64 v[36:37], v138 offset:4232
	s_waitcnt lgkmcnt(15)
	v_pk_fma_f32 v[6:7], v[38:39], v[100:101], v[6:7] op_sel_hi:[0,1,1]
	v_pk_fma_f32 v[6:7], v[38:39], v[102:103], v[6:7] op_sel:[1,0,0] op_sel_hi:[1,1,1]
	ds_read_b64 v[38:39], v138 offset:8456
	s_waitcnt lgkmcnt(15)
	v_pk_fma_f32 v[8:9], v[40:41], v[100:101], v[8:9] op_sel_hi:[0,1,1]
	v_pk_fma_f32 v[8:9], v[40:41], v[102:103], v[8:9] op_sel:[1,0,0] op_sel_hi:[1,1,1]
	ds_read_b64 v[40:41], v138 offset:12680
	s_waitcnt lgkmcnt(15)
	v_pk_fma_f32 v[10:11], v[42:43], v[100:101], v[10:11] op_sel_hi:[0,1,1]
	v_pk_fma_f32 v[10:11], v[42:43], v[102:103], v[10:11] op_sel:[1,0,0] op_sel_hi:[1,1,1]
	ds_read_b64 v[42:43], v138 offset:16904
	s_waitcnt lgkmcnt(15)
	v_pk_fma_f32 v[12:13], v[44:45], v[100:101], v[12:13] op_sel_hi:[0,1,1]
	v_pk_fma_f32 v[12:13], v[44:45], v[102:103], v[12:13] op_sel:[1,0,0] op_sel_hi:[1,1,1]
	ds_read_b64 v[44:45], v138 offset:21128
	s_waitcnt lgkmcnt(15)
	v_pk_fma_f32 v[14:15], v[46:47], v[100:101], v[14:15] op_sel_hi:[0,1,1]
	v_pk_fma_f32 v[14:15], v[46:47], v[102:103], v[14:15] op_sel:[1,0,0] op_sel_hi:[1,1,1]
	ds_read_b64 v[46:47], v138 offset:25352
	s_waitcnt lgkmcnt(15)
; __device__ __forceinline__ float bflo(unsigned w) { return __uint_as_float(w << 16); }
; __device__ __forceinline__ float bfhi(unsigned w) { return __uint_as_float(w & 0xffff0000u); }
; template <int BR>
; __device__ __forceinline__ void sample_unit(const SampP& P, int bs, int h, char* lds, float lam) {
;     ...
;     for (int k5 = 0; k5 < 13; ++k5) { const int keyb = 130 * wid + 10 * k5 + hf;
;       f32x4 v[5];
; #pragma unroll
;       for (int e = 0; e < 5; ++e) { const int key = keyb + 2 * e;
;         if (key < PAST) v[e] = *(const f32x4*)(Vc + (size_t)key * 1024 + 4 * l31);
;         else { const u32x2 w = *(const u32x2*)(Vn + (size_t)(key - PAST) * 1024 + 4 * l31); v[e] = (f32x4){bflo(w.x), bfhi(w.x), bflo(w.y), bfhi(w.y)}; } }
; #pragma unroll
;       for (int e = 0; e < 5; ++e) { const float* sp = S1 + keyb + 2 * e;
; #pragma unroll
;         for (int q = 0; q < 16; ++q) acc[q] += sp[q * SST] * v[e];
;         asm volatile("" ::: "memory"); }
	v_pk_fma_f32 v[16:17], v[48:49], v[100:101], v[16:17] op_sel_hi:[0,1,1]
	v_pk_fma_f32 v[16:17], v[48:49], v[102:103], v[16:17] op_sel:[1,0,0] op_sel_hi:[1,1,1]
	ds_read_b64 v[48:49], v138 offset:29576
	s_waitcnt lgkmcnt(15)
	v_pk_fma_f32 v[18:19], v[84:85], v[100:101], v[18:19] op_sel_hi:[0,1,1]
	v_pk_fma_f32 v[18:19], v[84:85], v[102:103], v[18:19] op_sel:[1,0,0] op_sel_hi:[1,1,1]
	ds_read_b64 v[84:85], v138 offset:33800
	s_waitcnt lgkmcnt(15)
	v_pk_fma_f32 v[20:21], v[86:87], v[100:101], v[20:21] op_sel_hi:[0,1,1]
	v_pk_fma_f32 v[20:21], v[86:87], v[102:103], v[20:21] op_sel:[1,0,0] op_sel_hi:[1,1,1]
	ds_read_b64 v[86:87], v138 offset:38024
	s_waitcnt lgkmcnt(15)
	v_pk_fma_f32 v[22:23], v[88:89], v[100:101], v[22:23] op_sel_hi:[0,1,1]
	v_pk_fma_f32 v[22:23], v[88:89], v[102:103], v[22:23] op_sel:[1,0,0] op_sel_hi:[1,1,1]
	ds_read_b64 v[88:89], v138 offset:42248
	s_waitcnt lgkmcnt(15)
	v_pk_fma_f32 v[24:25], v[90:91], v[100:101], v[24:25] op_sel_hi:[0,1,1]
	v_pk_fma_f32 v[24:25], v[90:91], v[102:103], v[24:25] op_sel:[1,0,0] op_sel_hi:[1,1,1]
	ds_read_b64 v[90:91], v138 offset:46472
	s_waitcnt lgkmcnt(15)
	v_pk_fma_f32 v[26:27], v[92:93], v[100:101], v[26:27] op_sel_hi:[0,1,1]
	v_pk_fma_f32 v[26:27], v[92:93], v[102:103], v[26:27] op_sel:[1,0,0] op_sel_hi:[1,1,1]
	ds_read_b64 v[92:93], v138 offset:50696
	s_waitcnt lgkmcnt(15)
	v_pk_fma_f32 v[28:29], v[94:95], v[100:101], v[28:29] op_sel_hi:[0,1,1]
	v_pk_fma_f32 v[28:29], v[94:95], v[102:103], v[28:29] op_sel:[1,0,0] op_sel_hi:[1,1,1]
	ds_read_b64 v[94:95], v138 offset:54920
	s_waitcnt lgkmcnt(15)
	v_pk_fma_f32 v[30:31], v[96:97], v[100:101], v[30:31] op_sel_hi:[0,1,1]
	v_pk_fma_f32 v[30:31], v[96:97], v[102:103], v[30:31] op_sel:[1,0,0] op_sel_hi:[1,1,1]
	ds_read_b64 v[96:97], v138 offset:59144
	s_waitcnt lgkmcnt(15)
	v_pk_fma_f32 v[32:33], v[98:99], v[100:101], v[32:33] op_sel_hi:[0,1,1]
	v_pk_fma_f32 v[32:33], v[98:99], v[102:103], v[32:33] op_sel:[1,0,0] op_sel_hi:[1,1,1]
	ds_read_b64 v[98:99], v138 offset:63368
	global_load_dwordx2 v[100:101], v[134:135], off offset:-2048
	global_load_dwordx2 v[102:103], v[134:135], off offset:2048
	v_lshl_add_u64 v[134:135], v[134:135], 0, s[0:1]
	s_waitcnt vmcnt(14)
	s_waitcnt lgkmcnt(15)
	v_pk_fma_f32 v[2:3], v[34:35], v[104:105], v[2:3] op_sel_hi:[0,1,1]
	v_pk_fma_f32 v[2:3], v[34:35], v[106:107], v[2:3] op_sel:[1,0,0] op_sel_hi:[1,1,1]
	ds_read_b64 v[34:35], v138 offset:16
	s_waitcnt lgkmcnt(15)
	v_pk_fma_f32 v[4:5], v[36:37], v[104:105], v[4:5] op_sel_hi:[0,1,1]
	v_pk_fma_f32 v[4:5], v[36:37], v[106:107], v[4:5] op_sel:[1,0,0] op_sel_hi:[1,1,1]
	ds_read_b64 v[36:37], v138 offset:4240
	s_waitcnt lgkmcnt(15)
	v_pk_fma_f32 v[6:7], v[38:39], v[104:105], v[6:7] op_sel_hi:[0,1,1]
	v_pk_fma_f32 v[6:7], v[38:39], v[106:107], v[6:7] op_sel:[1,0,0] op_sel_hi:[1,1,1]
	ds_read_b64 v[38:39], v138 offset:8464
	s_waitcnt lgkmcnt(15)
	v_pk_fma_f32 v[8:9], v[40:41], v[104:105], v[8:9] op_sel_hi:[0,1,1]
	v_pk_fma_f32 v[8:9], v[40:41], v[106:107], v[8:9] op_sel:[1,0,0] op_sel_hi:[1,1,1]
	ds_read_b64 v[40:41], v138 offset:12688
	s_waitcnt lgkmcnt(15)
	v_pk_fma_f32 v[10:11], v[42:43], v[104:105], v[10:11] op_sel_hi:[0,1,1]
	v_pk_fma_f32 v[10:11], v[42:43], v[106:107], v[10:11] op_sel:[1,0,0] op_sel_hi:[1,1,1]
	ds_read_b64 v[42:43], v138 offset:16912
	s_waitcnt lgkmcnt(15)
	v_pk_fma_f32 v[12:13], v[44:45], v[104:105], v[12:13] op_sel_hi:[0,1,1]
	v_pk_fma_f32 v[12:13], v[44:45], v[106:107], v[12:13] op_sel:[1,0,0] op_sel_hi:[1,1,1]
	ds_read_b64 v[44:45], v138 offset:21136
	s_waitcnt lgkmcnt(15)
	v_pk_fma_f32 v[14:15], v[46:47], v[104:105], v[14:15] op_sel_hi:[0,1,1]
	v_pk_fma_f32 v[14:15], v[46:47], v[106:107], v[14:15] op_sel:[1,0,0] op_sel_hi:[1,1,1]
	ds_read_b64 v[46:47], v138 offset:25360
	s_waitcnt lgkmcnt(15)
	v_pk_fma_f32 v[16:17], v[48:49], v[104:105], v[16:17] op_sel_hi:[0,1,1]
	v_pk_fma_f32 v[16:17], v[48:49], v[106:107], v[16:17] op_sel:[1,0,0] op_sel_hi:[1,1,1]
	ds_read_b64 v[48:49], v138 offset:29584
	s_waitcnt lgkmcnt(15)
	v_pk_fma_f32 v[18:19], v[84:85], v[104:105], v[18:19] op_sel_hi:[0,1,1]
	v_pk_fma_f32 v[18:19], v[84:85], v[106:107], v[18:19] op_sel:[1,0,0] op_sel_hi:[1,1,1]
	ds_read_b64 v[84:85], v138 offset:33808
	s_waitcnt lgkmcnt(15)
	v_pk_fma_f32 v[20:21], v[86:87], v[104:105], v[20:21] op_sel_hi:[0,1,1]
	v_pk_fma_f32 v[20:21], v[86:87], v[106:107], v[20:21] op_sel:[1,0,0] op_sel_hi:[1,1,1]
	ds_read_b64 v[86:87], v138 offset:38032
	s_waitcnt lgkmcnt(15)
	v_pk_fma_f32 v[22:23], v[88:89], v[104:105], v[22:23] op_sel_hi:[0,1,1]
	v_pk_fma_f32 v[22:23], v[88:89], v[106:107], v[22:23] op_sel:[1,0,0] op_sel_hi:[1,1,1]
	ds_read_b64 v[88:89], v138 offset:42256
	s_waitcnt lgkmcnt(15)
	v_pk_fma_f32 v[24:25], v[90:91], v[104:105], v[24:25] op_sel_hi:[0,1,1]
	v_pk_fma_f32 v[24:25], v[90:91], v[106:107], v[24:25] op_sel:[1,0,0] op_sel_hi:[1,1,1]
	ds_read_b64 v[90:91], v138 offset:46480
	s_waitcnt lgkmcnt(15)
	v_pk_fma_f32 v[26:27], v[92:93], v[104:105], v[26:27] op_sel_hi:[0,1,1]
	v_pk_fma_f32 v[26:27], v[92:93], v[106:107], v[26:27] op_sel:[1,0,0] op_sel_hi:[1,1,1]
	ds_read_b64 v[92:93], v138 offset:50704
	s_waitcnt lgkmcnt(15)
	v_pk_fma_f32 v[28:29], v[94:95], v[104:105], v[28:29] op_sel_hi:[0,1,1]
	v_pk_fma_f32 v[28:29], v[94:95], v[106:107], v[28:29] op_sel:[1,0,0] op_sel_hi:[1,1,1]
	ds_read_b64 v[94:95], v138 offset:54928
	s_waitcnt lgkmcnt(15)
	v_pk_fma_f32 v[30:31], v[96:97], v[104:105], v[30:31] op_sel_hi:[0,1,1]
	v_pk_fma_f32 v[30:31], v[96:97], v[106:107], v[30:31] op_sel:[1,0,0] op_sel_hi:[1,1,1]
	ds_read_b64 v[96:97], v138 offset:59152
	s_waitcnt lgkmcnt(15)
; __device__ __forceinline__ float bflo(unsigned w) { return __uint_as_float(w << 16); }
; __device__ __forceinline__ float bfhi(unsigned w) { return __uint_as_float(w & 0xffff0000u); }
; template <int BR>
; __device__ __forceinline__ void sample_unit(const SampP& P, int bs, int h, char* lds, float lam) {
;     ...
;     for (int k5 = 0; k5 < 13; ++k5) { const int keyb = 130 * wid + 10 * k5 + hf;
;       f32x4 v[5];
; #pragma unroll
;       for (int e = 0; e < 5; ++e) { const int key = keyb + 2 * e;
;         if (key < PAST) v[e] = *(const f32x4*)(Vc + (size_t)key * 1024 + 4 * l31);
;         else { const u32x2 w = *(const u32x2*)(Vn + (size_t)(key - PAST) * 1024 + 4 * l31); v[e] = (f32x4){bflo(w.x), bfhi(w.x), bflo(w.y), bfhi(w.y)}; } }
; #pragma unroll
;       for (int e = 0; e < 5; ++e) { const float* sp = S1 + keyb + 2 * e;
; #pragma unroll
;         for (int q = 0; q < 16; ++q) acc[q] += sp[q * SST] * v[e];
;         asm volatile("" ::: "memory"); }
	v_pk_fma_f32 v[32:33], v[98:99], v[104:105], v[32:33] op_sel_hi:[0,1,1]
	v_pk_fma_f32 v[32:33], v[98:99], v[106:107], v[32:33] op_sel:[1,0,0] op_sel_hi:[1,1,1]
	ds_read_b64 v[98:99], v138 offset:63376
	global_load_dwordx2 v[104:105], v[134:135], off offset:-2048
	global_load_dwordx2 v[106:107], v[134:135], off offset:2048
	v_lshl_add_u64 v[134:135], v[134:135], 0, s[0:1]
	s_waitcnt vmcnt(14)
	s_waitcnt lgkmcnt(15)
	v_pk_fma_f32 v[2:3], v[34:35], v[108:109], v[2:3] op_sel_hi:[0,1,1]
	v_pk_fma_f32 v[2:3], v[34:35], v[110:111], v[2:3] op_sel:[1,0,0] op_sel_hi:[1,1,1]
	ds_read_b64 v[34:35], v138 offset:24
	s_waitcnt lgkmcnt(15)
	v_pk_fma_f32 v[4:5], v[36:37], v[108:109], v[4:5] op_sel_hi:[0,1,1]
	v_pk_fma_f32 v[4:5], v[36:37], v[110:111], v[4:5] op_sel:[1,0,0] op_sel_hi:[1,1,1]
	ds_read_b64 v[36:37], v138 offset:4248
	s_waitcnt lgkmcnt(15)
	v_pk_fma_f32 v[6:7], v[38:39], v[108:109], v[6:7] op_sel_hi:[0,1,1]
	v_pk_fma_f32 v[6:7], v[38:39], v[110:111], v[6:7] op_sel:[1,0,0] op_sel_hi:[1,1,1]
	ds_read_b64 v[38:39], v138 offset:8472
	s_waitcnt lgkmcnt(15)
	v_pk_fma_f32 v[8:9], v[40:41], v[108:109], v[8:9] op_sel_hi:[0,1,1]
	v_pk_fma_f32 v[8:9], v[40:41], v[110:111], v[8:9] op_sel:[1,0,0] op_sel_hi:[1,1,1]
	ds_read_b64 v[40:41], v138 offset:12696
	s_waitcnt lgkmcnt(15)
	v_pk_fma_f32 v[10:11], v[42:43], v[108:109], v[10:11] op_sel_hi:[0,1,1]
	v_pk_fma_f32 v[10:11], v[42:43], v[110:111], v[10:11] op_sel:[1,0,0] op_sel_hi:[1,1,1]
	ds_read_b64 v[42:43], v138 offset:16920
	s_waitcnt lgkmcnt(15)
	v_pk_fma_f32 v[12:13], v[44:45], v[108:109], v[12:13] op_sel_hi:[0,1,1]
	v_pk_fma_f32 v[12:13], v[44:45], v[110:111], v[12:13] op_sel:[1,0,0] op_sel_hi:[1,1,1]
	ds_read_b64 v[44:45], v138 offset:21144
	s_waitcnt lgkmcnt(15)
	v_pk_fma_f32 v[14:15], v[46:47], v[108:109], v[14:15] op_sel_hi:[0,1,1]
	v_pk_fma_f32 v[14:15], v[46:47], v[110:111], v[14:15] op_sel:[1,0,0] op_sel_hi:[1,1,1]
	ds_read_b64 v[46:47], v138 offset:25368
	s_waitcnt lgkmcnt(15)
	v_pk_fma_f32 v[16:17], v[48:49], v[108:109], v[16:17] op_sel_hi:[0,1,1]
	v_pk_fma_f32 v[16:17], v[48:49], v[110:111], v[16:17] op_sel:[1,0,0] op_sel_hi:[1,1,1]
	ds_read_b64 v[48:49], v138 offset:29592
	s_waitcnt lgkmcnt(15)
	v_pk_fma_f32 v[18:19], v[84:85], v[108:109], v[18:19] op_sel_hi:[0,1,1]
	v_pk_fma_f32 v[18:19], v[84:85], v[110:111], v[18:19] op_sel:[1,0,0] op_sel_hi:[1,1,1]
	ds_read_b64 v[84:85], v138 offset:33816
	s_waitcnt lgkmcnt(15)
	v_pk_fma_f32 v[20:21], v[86:87], v[108:109], v[20:21] op_sel_hi:[0,1,1]
	v_pk_fma_f32 v[20:21], v[86:87], v[110:111], v[20:21] op_sel:[1,0,0] op_sel_hi:[1,1,1]
	ds_read_b64 v[86:87], v138 offset:38040
	s_waitcnt lgkmcnt(15)
	v_pk_fma_f32 v[22:23], v[88:89], v[108:109], v[22:23] op_sel_hi:[0,1,1]
	v_pk_fma_f32 v[22:23], v[88:89], v[110:111], v[22:23] op_sel:[1,0,0] op_sel_hi:[1,1,1]
	ds_read_b64 v[88:89], v138 offset:42264
	s_waitcnt lgkmcnt(15)
	v_pk_fma_f32 v[24:25], v[90:91], v[108:109], v[24:25] op_sel_hi:[0,1,1]
	v_pk_fma_f32 v[24:25], v[90:91], v[110:111], v[24:25] op_sel:[1,0,0] op_sel_hi:[1,1,1]
	ds_read_b64 v[90:91], v138 offset:46488
	s_waitcnt lgkmcnt(15)
	v_pk_fma_f32 v[26:27], v[92:93], v[108:109], v[26:27] op_sel_hi:[0,1,1]
	v_pk_fma_f32 v[26:27], v[92:93], v[110:111], v[26:27] op_sel:[1,0,0] op_sel_hi:[1,1,1]
	ds_read_b64 v[92:93], v138 offset:50712
	s_waitcnt lgkmcnt(15)
	v_pk_fma_f32 v[28:29], v[94:95], v[108:109], v[28:29] op_sel_hi:[0,1,1]
	v_pk_fma_f32 v[28:29], v[94:95], v[110:111], v[28:29] op_sel:[1,0,0] op_sel_hi:[1,1,1]
	ds_read_b64 v[94:95], v138 offset:54936
	s_waitcnt lgkmcnt(15)
	v_pk_fma_f32 v[30:31], v[96:97], v[108:109], v[30:31] op_sel_hi:[0,1,1]
	v_pk_fma_f32 v[30:31], v[96:97], v[110:111], v[30:31] op_sel:[1,0,0] op_sel_hi:[1,1,1]
	ds_read_b64 v[96:97], v138 offset:59160
	s_waitcnt lgkmcnt(15)
	v_pk_fma_f32 v[32:33], v[98:99], v[108:109], v[32:33] op_sel_hi:[0,1,1]
	v_pk_fma_f32 v[32:33], v[98:99], v[110:111], v[32:33] op_sel:[1,0,0] op_sel_hi:[1,1,1]
	ds_read_b64 v[98:99], v138 offset:63384
	global_load_dwordx2 v[108:109], v[134:135], off offset:-2048
	global_load_dwordx2 v[110:111], v[134:135], off offset:2048
	v_lshl_add_u64 v[134:135], v[134:135], 0, s[0:1]
	s_waitcnt vmcnt(14)
	s_waitcnt lgkmcnt(15)
	v_pk_fma_f32 v[2:3], v[34:35], v[112:113], v[2:3] op_sel_hi:[0,1,1]
	v_pk_fma_f32 v[2:3], v[34:35], v[114:115], v[2:3] op_sel:[1,0,0] op_sel_hi:[1,1,1]
	ds_read_b64 v[34:35], v138 offset:32
	s_waitcnt lgkmcnt(15)
	v_pk_fma_f32 v[4:5], v[36:37], v[112:113], v[4:5] op_sel_hi:[0,1,1]
	v_pk_fma_f32 v[4:5], v[36:37], v[114:115], v[4:5] op_sel:[1,0,0] op_sel_hi:[1,1,1]
	ds_read_b64 v[36:37], v138 offset:4256
	s_waitcnt lgkmcnt(15)
	v_pk_fma_f32 v[6:7], v[38:39], v[112:113], v[6:7] op_sel_hi:[0,1,1]
	v_pk_fma_f32 v[6:7], v[38:39], v[114:115], v[6:7] op_sel:[1,0,0] op_sel_hi:[1,1,1]
	ds_read_b64 v[38:39], v138 offset:8480
	s_waitcnt lgkmcnt(15)
	v_pk_fma_f32 v[8:9], v[40:41], v[112:113], v[8:9] op_sel_hi:[0,1,1]
	v_pk_fma_f32 v[8:9], v[40:41], v[114:115], v[8:9] op_sel:[1,0,0] op_sel_hi:[1,1,1]
	ds_read_b64 v[40:41], v138 offset:12704
	s_waitcnt lgkmcnt(15)
	v_pk_fma_f32 v[10:11], v[42:43], v[112:113], v[10:11] op_sel_hi:[0,1,1]
	v_pk_fma_f32 v[10:11], v[42:43], v[114:115], v[10:11] op_sel:[1,0,0] op_sel_hi:[1,1,1]
	ds_read_b64 v[42:43], v138 offset:16928
	s_waitcnt lgkmcnt(15)
	v_pk_fma_f32 v[12:13], v[44:45], v[112:113], v[12:13] op_sel_hi:[0,1,1]
	v_pk_fma_f32 v[12:13], v[44:45], v[114:115], v[12:13] op_sel:[1,0,0] op_sel_hi:[1,1,1]
	ds_read_b64 v[44:45], v138 offset:21152
	s_waitcnt lgkmcnt(15)
	v_pk_fma_f32 v[14:15], v[46:47], v[112:113], v[14:15] op_sel_hi:[0,1,1]
	v_pk_fma_f32 v[14:15], v[46:47], v[114:115], v[14:15] op_sel:[1,0,0] op_sel_hi:[1,1,1]
	ds_read_b64 v[46:47], v138 offset:25376
	s_waitcnt lgkmcnt(15)
; __device__ __forceinline__ float bflo(unsigned w) { return __uint_as_float(w << 16); }
; __device__ __forceinline__ float bfhi(unsigned w) { return __uint_as_float(w & 0xffff0000u); }
; template <int BR>
; __device__ __forceinline__ void sample_unit(const SampP& P, int bs, int h, char* lds, float lam) {
;     ...
;     for (int k5 = 0; k5 < 13; ++k5) { const int keyb = 130 * wid + 10 * k5 + hf;
;       f32x4 v[5];
; #pragma unroll
;       for (int e = 0; e < 5; ++e) { const int key = keyb + 2 * e;
;         if (key < PAST) v[e] = *(const f32x4*)(Vc + (size_t)key * 1024 + 4 * l31);
;         else { const u32x2 w = *(const u32x2*)(Vn + (size_t)(key - PAST) * 1024 + 4 * l31); v[e] = (f32x4){bflo(w.x), bfhi(w.x), bflo(w.y), bfhi(w.y)}; } }
; #pragma unroll
;       for (int e = 0; e < 5; ++e) { const float* sp = S1 + keyb + 2 * e;
; #pragma unroll
;         for (int q = 0; q < 16; ++q) acc[q] += sp[q * SST] * v[e];
;         asm volatile("" ::: "memory"); }
	v_pk_fma_f32 v[16:17], v[48:49], v[112:113], v[16:17] op_sel_hi:[0,1,1]
	v_pk_fma_f32 v[16:17], v[48:49], v[114:115], v[16:17] op_sel:[1,0,0] op_sel_hi:[1,1,1]
	ds_read_b64 v[48:49], v138 offset:29600
	s_waitcnt lgkmcnt(15)
	v_pk_fma_f32 v[18:19], v[84:85], v[112:113], v[18:19] op_sel_hi:[0,1,1]
	v_pk_fma_f32 v[18:19], v[84:85], v[114:115], v[18:19] op_sel:[1,0,0] op_sel_hi:[1,1,1]
	ds_read_b64 v[84:85], v138 offset:33824
	s_waitcnt lgkmcnt(15)
	v_pk_fma_f32 v[20:21], v[86:87], v[112:113], v[20:21] op_sel_hi:[0,1,1]
	v_pk_fma_f32 v[20:21], v[86:87], v[114:115], v[20:21] op_sel:[1,0,0] op_sel_hi:[1,1,1]
	ds_read_b64 v[86:87], v138 offset:38048
	s_waitcnt lgkmcnt(15)
	v_pk_fma_f32 v[22:23], v[88:89], v[112:113], v[22:23] op_sel_hi:[0,1,1]
	v_pk_fma_f32 v[22:23], v[88:89], v[114:115], v[22:23] op_sel:[1,0,0] op_sel_hi:[1,1,1]
	ds_read_b64 v[88:89], v138 offset:42272
	s_waitcnt lgkmcnt(15)
	v_pk_fma_f32 v[24:25], v[90:91], v[112:113], v[24:25] op_sel_hi:[0,1,1]
	v_pk_fma_f32 v[24:25], v[90:91], v[114:115], v[24:25] op_sel:[1,0,0] op_sel_hi:[1,1,1]
	ds_read_b64 v[90:91], v138 offset:46496
	s_waitcnt lgkmcnt(15)
	v_pk_fma_f32 v[26:27], v[92:93], v[112:113], v[26:27] op_sel_hi:[0,1,1]
	v_pk_fma_f32 v[26:27], v[92:93], v[114:115], v[26:27] op_sel:[1,0,0] op_sel_hi:[1,1,1]
	ds_read_b64 v[92:93], v138 offset:50720
	s_waitcnt lgkmcnt(15)
	v_pk_fma_f32 v[28:29], v[94:95], v[112:113], v[28:29] op_sel_hi:[0,1,1]
	v_pk_fma_f32 v[28:29], v[94:95], v[114:115], v[28:29] op_sel:[1,0,0] op_sel_hi:[1,1,1]
	ds_read_b64 v[94:95], v138 offset:54944
	s_waitcnt lgkmcnt(15)
	v_pk_fma_f32 v[30:31], v[96:97], v[112:113], v[30:31] op_sel_hi:[0,1,1]
	v_pk_fma_f32 v[30:31], v[96:97], v[114:115], v[30:31] op_sel:[1,0,0] op_sel_hi:[1,1,1]
	ds_read_b64 v[96:97], v138 offset:59168
	s_waitcnt lgkmcnt(15)
	v_pk_fma_f32 v[32:33], v[98:99], v[112:113], v[32:33] op_sel_hi:[0,1,1]
	v_pk_fma_f32 v[32:33], v[98:99], v[114:115], v[32:33] op_sel:[1,0,0] op_sel_hi:[1,1,1]
	ds_read_b64 v[98:99], v138 offset:63392
	global_load_dwordx2 v[112:113], v[134:135], off offset:-2048
	global_load_dwordx2 v[114:115], v[134:135], off offset:2048
	v_lshl_add_u64 v[134:135], v[134:135], 0, s[0:1]
	s_waitcnt vmcnt(14)
	s_waitcnt lgkmcnt(15)
	v_pk_fma_f32 v[2:3], v[34:35], v[116:117], v[2:3] op_sel_hi:[0,1,1]
	v_pk_fma_f32 v[2:3], v[34:35], v[118:119], v[2:3] op_sel:[1,0,0] op_sel_hi:[1,1,1]
	ds_read_b64 v[34:35], v138 offset:40
	s_waitcnt lgkmcnt(15)
	v_pk_fma_f32 v[4:5], v[36:37], v[116:117], v[4:5] op_sel_hi:[0,1,1]
	v_pk_fma_f32 v[4:5], v[36:37], v[118:119], v[4:5] op_sel:[1,0,0] op_sel_hi:[1,1,1]
	ds_read_b64 v[36:37], v138 offset:4264
	s_waitcnt lgkmcnt(15)
	v_pk_fma_f32 v[6:7], v[38:39], v[116:117], v[6:7] op_sel_hi:[0,1,1]
	v_pk_fma_f32 v[6:7], v[38:39], v[118:119], v[6:7] op_sel:[1,0,0] op_sel_hi:[1,1,1]
	ds_read_b64 v[38:39], v138 offset:8488
	s_waitcnt lgkmcnt(15)
	v_pk_fma_f32 v[8:9], v[40:41], v[116:117], v[8:9] op_sel_hi:[0,1,1]
	v_pk_fma_f32 v[8:9], v[40:41], v[118:119], v[8:9] op_sel:[1,0,0] op_sel_hi:[1,1,1]
	ds_read_b64 v[40:41], v138 offset:12712
	s_waitcnt lgkmcnt(15)
	v_pk_fma_f32 v[10:11], v[42:43], v[116:117], v[10:11] op_sel_hi:[0,1,1]
	v_pk_fma_f32 v[10:11], v[42:43], v[118:119], v[10:11] op_sel:[1,0,0] op_sel_hi:[1,1,1]
	ds_read_b64 v[42:43], v138 offset:16936
	s_waitcnt lgkmcnt(15)
	v_pk_fma_f32 v[12:13], v[44:45], v[116:117], v[12:13] op_sel_hi:[0,1,1]
	v_pk_fma_f32 v[12:13], v[44:45], v[118:119], v[12:13] op_sel:[1,0,0] op_sel_hi:[1,1,1]
	ds_read_b64 v[44:45], v138 offset:21160
	s_waitcnt lgkmcnt(15)
	v_pk_fma_f32 v[14:15], v[46:47], v[116:117], v[14:15] op_sel_hi:[0,1,1]
	v_pk_fma_f32 v[14:15], v[46:47], v[118:119], v[14:15] op_sel:[1,0,0] op_sel_hi:[1,1,1]
	ds_read_b64 v[46:47], v138 offset:25384
	s_waitcnt lgkmcnt(15)
	v_pk_fma_f32 v[16:17], v[48:49], v[116:117], v[16:17] op_sel_hi:[0,1,1]
	v_pk_fma_f32 v[16:17], v[48:49], v[118:119], v[16:17] op_sel:[1,0,0] op_sel_hi:[1,1,1]
	ds_read_b64 v[48:49], v138 offset:29608
	s_waitcnt lgkmcnt(15)
	v_pk_fma_f32 v[18:19], v[84:85], v[116:117], v[18:19] op_sel_hi:[0,1,1]
	v_pk_fma_f32 v[18:19], v[84:85], v[118:119], v[18:19] op_sel:[1,0,0] op_sel_hi:[1,1,1]
	ds_read_b64 v[84:85], v138 offset:33832
	s_waitcnt lgkmcnt(15)
	v_pk_fma_f32 v[20:21], v[86:87], v[116:117], v[20:21] op_sel_hi:[0,1,1]
	v_pk_fma_f32 v[20:21], v[86:87], v[118:119], v[20:21] op_sel:[1,0,0] op_sel_hi:[1,1,1]
	ds_read_b64 v[86:87], v138 offset:38056
	s_waitcnt lgkmcnt(15)
	v_pk_fma_f32 v[22:23], v[88:89], v[116:117], v[22:23] op_sel_hi:[0,1,1]
	v_pk_fma_f32 v[22:23], v[88:89], v[118:119], v[22:23] op_sel:[1,0,0] op_sel_hi:[1,1,1]
	ds_read_b64 v[88:89], v138 offset:42280
	s_waitcnt lgkmcnt(15)
	v_pk_fma_f32 v[24:25], v[90:91], v[116:117], v[24:25] op_sel_hi:[0,1,1]
	v_pk_fma_f32 v[24:25], v[90:91], v[118:119], v[24:25] op_sel:[1,0,0] op_sel_hi:[1,1,1]
	ds_read_b64 v[90:91], v138 offset:46504
	s_waitcnt lgkmcnt(15)
	v_pk_fma_f32 v[26:27], v[92:93], v[116:117], v[26:27] op_sel_hi:[0,1,1]
	v_pk_fma_f32 v[26:27], v[92:93], v[118:119], v[26:27] op_sel:[1,0,0] op_sel_hi:[1,1,1]
	ds_read_b64 v[92:93], v138 offset:50728
	s_waitcnt lgkmcnt(15)
	v_pk_fma_f32 v[28:29], v[94:95], v[116:117], v[28:29] op_sel_hi:[0,1,1]
	v_pk_fma_f32 v[28:29], v[94:95], v[118:119], v[28:29] op_sel:[1,0,0] op_sel_hi:[1,1,1]
	ds_read_b64 v[94:95], v138 offset:54952
	s_waitcnt lgkmcnt(15)
	v_pk_fma_f32 v[30:31], v[96:97], v[116:117], v[30:31] op_sel_hi:[0,1,1]
	v_pk_fma_f32 v[30:31], v[96:97], v[118:119], v[30:31] op_sel:[1,0,0] op_sel_hi:[1,1,1]
	ds_read_b64 v[96:97], v138 offset:59176
	s_waitcnt lgkmcnt(15)
; __device__ __forceinline__ float bflo(unsigned w) { return __uint_as_float(w << 16); }
; __device__ __forceinline__ float bfhi(unsigned w) { return __uint_as_float(w & 0xffff0000u); }
; template <int BR>
; __device__ __forceinline__ void sample_unit(const SampP& P, int bs, int h, char* lds, float lam) {
;     ...
;     for (int k5 = 0; k5 < 13; ++k5) { const int keyb = 130 * wid + 10 * k5 + hf;
;       f32x4 v[5];
; #pragma unroll
;       for (int e = 0; e < 5; ++e) { const int key = keyb + 2 * e;
;         if (key < PAST) v[e] = *(const f32x4*)(Vc + (size_t)key * 1024 + 4 * l31);
;         else { const u32x2 w = *(const u32x2*)(Vn + (size_t)(key - PAST) * 1024 + 4 * l31); v[e] = (f32x4){bflo(w.x), bfhi(w.x), bflo(w.y), bfhi(w.y)}; } }
; #pragma unroll
;       for (int e = 0; e < 5; ++e) { const float* sp = S1 + keyb + 2 * e;
; #pragma unroll
;         for (int q = 0; q < 16; ++q) acc[q] += sp[q * SST] * v[e];
;         asm volatile("" ::: "memory"); }
	v_pk_fma_f32 v[32:33], v[98:99], v[116:117], v[32:33] op_sel_hi:[0,1,1]
	v_pk_fma_f32 v[32:33], v[98:99], v[118:119], v[32:33] op_sel:[1,0,0] op_sel_hi:[1,1,1]
	ds_read_b64 v[98:99], v138 offset:63400
	global_load_dwordx2 v[116:117], v[134:135], off offset:-2048
	global_load_dwordx2 v[118:119], v[134:135], off offset:2048
	v_lshl_add_u64 v[134:135], v[134:135], 0, s[0:1]
	s_waitcnt vmcnt(14)
	s_waitcnt lgkmcnt(15)
	v_pk_fma_f32 v[2:3], v[34:35], v[120:121], v[2:3] op_sel_hi:[0,1,1]
	v_pk_fma_f32 v[2:3], v[34:35], v[122:123], v[2:3] op_sel:[1,0,0] op_sel_hi:[1,1,1]
	ds_read_b64 v[34:35], v138 offset:48
	s_waitcnt lgkmcnt(15)
	v_pk_fma_f32 v[4:5], v[36:37], v[120:121], v[4:5] op_sel_hi:[0,1,1]
	v_pk_fma_f32 v[4:5], v[36:37], v[122:123], v[4:5] op_sel:[1,0,0] op_sel_hi:[1,1,1]
	ds_read_b64 v[36:37], v138 offset:4272
	s_waitcnt lgkmcnt(15)
	v_pk_fma_f32 v[6:7], v[38:39], v[120:121], v[6:7] op_sel_hi:[0,1,1]
	v_pk_fma_f32 v[6:7], v[38:39], v[122:123], v[6:7] op_sel:[1,0,0] op_sel_hi:[1,1,1]
	ds_read_b64 v[38:39], v138 offset:8496
	s_waitcnt lgkmcnt(15)
	v_pk_fma_f32 v[8:9], v[40:41], v[120:121], v[8:9] op_sel_hi:[0,1,1]
	v_pk_fma_f32 v[8:9], v[40:41], v[122:123], v[8:9] op_sel:[1,0,0] op_sel_hi:[1,1,1]
	ds_read_b64 v[40:41], v138 offset:12720
	s_waitcnt lgkmcnt(15)
	v_pk_fma_f32 v[10:11], v[42:43], v[120:121], v[10:11] op_sel_hi:[0,1,1]
	v_pk_fma_f32 v[10:11], v[42:43], v[122:123], v[10:11] op_sel:[1,0,0] op_sel_hi:[1,1,1]
	ds_read_b64 v[42:43], v138 offset:16944
	s_waitcnt lgkmcnt(15)
	v_pk_fma_f32 v[12:13], v[44:45], v[120:121], v[12:13] op_sel_hi:[0,1,1]
	v_pk_fma_f32 v[12:13], v[44:45], v[122:123], v[12:13] op_sel:[1,0,0] op_sel_hi:[1,1,1]
	ds_read_b64 v[44:45], v138 offset:21168
	s_waitcnt lgkmcnt(15)
	v_pk_fma_f32 v[14:15], v[46:47], v[120:121], v[14:15] op_sel_hi:[0,1,1]
	v_pk_fma_f32 v[14:15], v[46:47], v[122:123], v[14:15] op_sel:[1,0,0] op_sel_hi:[1,1,1]
	ds_read_b64 v[46:47], v138 offset:25392
	s_waitcnt lgkmcnt(15)
	v_pk_fma_f32 v[16:17], v[48:49], v[120:121], v[16:17] op_sel_hi:[0,1,1]
	v_pk_fma_f32 v[16:17], v[48:49], v[122:123], v[16:17] op_sel:[1,0,0] op_sel_hi:[1,1,1]
	ds_read_b64 v[48:49], v138 offset:29616
	s_waitcnt lgkmcnt(15)
	v_pk_fma_f32 v[18:19], v[84:85], v[120:121], v[18:19] op_sel_hi:[0,1,1]
	v_pk_fma_f32 v[18:19], v[84:85], v[122:123], v[18:19] op_sel:[1,0,0] op_sel_hi:[1,1,1]
	ds_read_b64 v[84:85], v138 offset:33840
	s_waitcnt lgkmcnt(15)
	v_pk_fma_f32 v[20:21], v[86:87], v[120:121], v[20:21] op_sel_hi:[0,1,1]
	v_pk_fma_f32 v[20:21], v[86:87], v[122:123], v[20:21] op_sel:[1,0,0] op_sel_hi:[1,1,1]
	ds_read_b64 v[86:87], v138 offset:38064
	s_waitcnt lgkmcnt(15)
	v_pk_fma_f32 v[22:23], v[88:89], v[120:121], v[22:23] op_sel_hi:[0,1,1]
	v_pk_fma_f32 v[22:23], v[88:89], v[122:123], v[22:23] op_sel:[1,0,0] op_sel_hi:[1,1,1]
	ds_read_b64 v[88:89], v138 offset:42288
	s_waitcnt lgkmcnt(15)
	v_pk_fma_f32 v[24:25], v[90:91], v[120:121], v[24:25] op_sel_hi:[0,1,1]
	v_pk_fma_f32 v[24:25], v[90:91], v[122:123], v[24:25] op_sel:[1,0,0] op_sel_hi:[1,1,1]
	ds_read_b64 v[90:91], v138 offset:46512
	s_waitcnt lgkmcnt(15)
	v_pk_fma_f32 v[26:27], v[92:93], v[120:121], v[26:27] op_sel_hi:[0,1,1]
	v_pk_fma_f32 v[26:27], v[92:93], v[122:123], v[26:27] op_sel:[1,0,0] op_sel_hi:[1,1,1]
	ds_read_b64 v[92:93], v138 offset:50736
	s_waitcnt lgkmcnt(15)
	v_pk_fma_f32 v[28:29], v[94:95], v[120:121], v[28:29] op_sel_hi:[0,1,1]
	v_pk_fma_f32 v[28:29], v[94:95], v[122:123], v[28:29] op_sel:[1,0,0] op_sel_hi:[1,1,1]
	ds_read_b64 v[94:95], v138 offset:54960
	s_waitcnt lgkmcnt(15)
	v_pk_fma_f32 v[30:31], v[96:97], v[120:121], v[30:31] op_sel_hi:[0,1,1]
	v_pk_fma_f32 v[30:31], v[96:97], v[122:123], v[30:31] op_sel:[1,0,0] op_sel_hi:[1,1,1]
	ds_read_b64 v[96:97], v138 offset:59184
	s_waitcnt lgkmcnt(15)
	v_pk_fma_f32 v[32:33], v[98:99], v[120:121], v[32:33] op_sel_hi:[0,1,1]
	v_pk_fma_f32 v[32:33], v[98:99], v[122:123], v[32:33] op_sel:[1,0,0] op_sel_hi:[1,1,1]
	ds_read_b64 v[98:99], v138 offset:63408
	global_load_dwordx2 v[120:121], v[134:135], off offset:-2048
	global_load_dwordx2 v[122:123], v[134:135], off offset:2048
	v_lshl_add_u64 v[134:135], v[134:135], 0, s[0:1]
	s_waitcnt vmcnt(14)
	s_waitcnt lgkmcnt(15)
	v_pk_fma_f32 v[2:3], v[34:35], v[124:125], v[2:3] op_sel_hi:[0,1,1]
	v_pk_fma_f32 v[2:3], v[34:35], v[126:127], v[2:3] op_sel:[1,0,0] op_sel_hi:[1,1,1]
	ds_read_b64 v[34:35], v138 offset:56
	s_waitcnt lgkmcnt(15)
	v_pk_fma_f32 v[4:5], v[36:37], v[124:125], v[4:5] op_sel_hi:[0,1,1]
	v_pk_fma_f32 v[4:5], v[36:37], v[126:127], v[4:5] op_sel:[1,0,0] op_sel_hi:[1,1,1]
	ds_read_b64 v[36:37], v138 offset:4280
	s_waitcnt lgkmcnt(15)
	v_pk_fma_f32 v[6:7], v[38:39], v[124:125], v[6:7] op_sel_hi:[0,1,1]
	v_pk_fma_f32 v[6:7], v[38:39], v[126:127], v[6:7] op_sel:[1,0,0] op_sel_hi:[1,1,1]
	ds_read_b64 v[38:39], v138 offset:8504
	s_waitcnt lgkmcnt(15)
	v_pk_fma_f32 v[8:9], v[40:41], v[124:125], v[8:9] op_sel_hi:[0,1,1]
	v_pk_fma_f32 v[8:9], v[40:41], v[126:127], v[8:9] op_sel:[1,0,0] op_sel_hi:[1,1,1]
	ds_read_b64 v[40:41], v138 offset:12728
	s_waitcnt lgkmcnt(15)
	v_pk_fma_f32 v[10:11], v[42:43], v[124:125], v[10:11] op_sel_hi:[0,1,1]
	v_pk_fma_f32 v[10:11], v[42:43], v[126:127], v[10:11] op_sel:[1,0,0] op_sel_hi:[1,1,1]
	ds_read_b64 v[42:43], v138 offset:16952
	s_waitcnt lgkmcnt(15)
	v_pk_fma_f32 v[12:13], v[44:45], v[124:125], v[12:13] op_sel_hi:[0,1,1]
	v_pk_fma_f32 v[12:13], v[44:45], v[126:127], v[12:13] op_sel:[1,0,0] op_sel_hi:[1,1,1]
	ds_read_b64 v[44:45], v138 offset:21176
	s_waitcnt lgkmcnt(15)
	v_pk_fma_f32 v[14:15], v[46:47], v[124:125], v[14:15] op_sel_hi:[0,1,1]
	v_pk_fma_f32 v[14:15], v[46:47], v[126:127], v[14:15] op_sel:[1,0,0] op_sel_hi:[1,1,1]
	ds_read_b64 v[46:47], v138 offset:25400
	s_waitcnt lgkmcnt(15)
; __device__ __forceinline__ float bflo(unsigned w) { return __uint_as_float(w << 16); }
; __device__ __forceinline__ float bfhi(unsigned w) { return __uint_as_float(w & 0xffff0000u); }
; template <int BR>
; __device__ __forceinline__ void sample_unit(const SampP& P, int bs, int h, char* lds, float lam) {
;     ...
;     for (int k5 = 0; k5 < 13; ++k5) { const int keyb = 130 * wid + 10 * k5 + hf;
;       f32x4 v[5];
; #pragma unroll
;       for (int e = 0; e < 5; ++e) { const int key = keyb + 2 * e;
;         if (key < PAST) v[e] = *(const f32x4*)(Vc + (size_t)key * 1024 + 4 * l31);
;         else { const u32x2 w = *(const u32x2*)(Vn + (size_t)(key - PAST) * 1024 + 4 * l31); v[e] = (f32x4){bflo(w.x), bfhi(w.x), bflo(w.y), bfhi(w.y)}; } }
; #pragma unroll
;       for (int e = 0; e < 5; ++e) { const float* sp = S1 + keyb + 2 * e;
; #pragma unroll
;         for (int q = 0; q < 16; ++q) acc[q] += sp[q * SST] * v[e];
;         asm volatile("" ::: "memory"); }
	v_pk_fma_f32 v[16:17], v[48:49], v[124:125], v[16:17] op_sel_hi:[0,1,1]
	v_pk_fma_f32 v[16:17], v[48:49], v[126:127], v[16:17] op_sel:[1,0,0] op_sel_hi:[1,1,1]
	ds_read_b64 v[48:49], v138 offset:29624
	s_waitcnt lgkmcnt(15)
	v_pk_fma_f32 v[18:19], v[84:85], v[124:125], v[18:19] op_sel_hi:[0,1,1]
	v_pk_fma_f32 v[18:19], v[84:85], v[126:127], v[18:19] op_sel:[1,0,0] op_sel_hi:[1,1,1]
	ds_read_b64 v[84:85], v138 offset:33848
	s_waitcnt lgkmcnt(15)
	v_pk_fma_f32 v[20:21], v[86:87], v[124:125], v[20:21] op_sel_hi:[0,1,1]
	v_pk_fma_f32 v[20:21], v[86:87], v[126:127], v[20:21] op_sel:[1,0,0] op_sel_hi:[1,1,1]
	ds_read_b64 v[86:87], v138 offset:38072
	s_waitcnt lgkmcnt(15)
	v_pk_fma_f32 v[22:23], v[88:89], v[124:125], v[22:23] op_sel_hi:[0,1,1]
	v_pk_fma_f32 v[22:23], v[88:89], v[126:127], v[22:23] op_sel:[1,0,0] op_sel_hi:[1,1,1]
	ds_read_b64 v[88:89], v138 offset:42296
	s_waitcnt lgkmcnt(15)
	v_pk_fma_f32 v[24:25], v[90:91], v[124:125], v[24:25] op_sel_hi:[0,1,1]
	v_pk_fma_f32 v[24:25], v[90:91], v[126:127], v[24:25] op_sel:[1,0,0] op_sel_hi:[1,1,1]
	ds_read_b64 v[90:91], v138 offset:46520
	s_waitcnt lgkmcnt(15)
	v_pk_fma_f32 v[26:27], v[92:93], v[124:125], v[26:27] op_sel_hi:[0,1,1]
	v_pk_fma_f32 v[26:27], v[92:93], v[126:127], v[26:27] op_sel:[1,0,0] op_sel_hi:[1,1,1]
	ds_read_b64 v[92:93], v138 offset:50744
	s_waitcnt lgkmcnt(15)
	v_pk_fma_f32 v[28:29], v[94:95], v[124:125], v[28:29] op_sel_hi:[0,1,1]
	v_pk_fma_f32 v[28:29], v[94:95], v[126:127], v[28:29] op_sel:[1,0,0] op_sel_hi:[1,1,1]
	ds_read_b64 v[94:95], v138 offset:54968
	s_waitcnt lgkmcnt(15)
	v_pk_fma_f32 v[30:31], v[96:97], v[124:125], v[30:31] op_sel_hi:[0,1,1]
	v_pk_fma_f32 v[30:31], v[96:97], v[126:127], v[30:31] op_sel:[1,0,0] op_sel_hi:[1,1,1]
	ds_read_b64 v[96:97], v138 offset:59192
	s_waitcnt lgkmcnt(15)
	v_pk_fma_f32 v[32:33], v[98:99], v[124:125], v[32:33] op_sel_hi:[0,1,1]
	v_pk_fma_f32 v[32:33], v[98:99], v[126:127], v[32:33] op_sel:[1,0,0] op_sel_hi:[1,1,1]
	ds_read_b64 v[98:99], v138 offset:63416
	global_load_dwordx2 v[124:125], v[134:135], off offset:-2048
	global_load_dwordx2 v[126:127], v[134:135], off offset:2048
	v_lshl_add_u64 v[134:135], v[134:135], 0, s[0:1]
	s_waitcnt vmcnt(14)
	s_waitcnt lgkmcnt(15)
	v_pk_fma_f32 v[2:3], v[34:35], v[128:129], v[2:3] op_sel_hi:[0,1,1]
	v_pk_fma_f32 v[2:3], v[34:35], v[130:131], v[2:3] op_sel:[1,0,0] op_sel_hi:[1,1,1]
	ds_read_b64 v[34:35], v138 offset:64
	s_waitcnt lgkmcnt(15)
	v_pk_fma_f32 v[4:5], v[36:37], v[128:129], v[4:5] op_sel_hi:[0,1,1]
	v_pk_fma_f32 v[4:5], v[36:37], v[130:131], v[4:5] op_sel:[1,0,0] op_sel_hi:[1,1,1]
	ds_read_b64 v[36:37], v138 offset:4288
	s_waitcnt lgkmcnt(15)
	v_pk_fma_f32 v[6:7], v[38:39], v[128:129], v[6:7] op_sel_hi:[0,1,1]
	v_pk_fma_f32 v[6:7], v[38:39], v[130:131], v[6:7] op_sel:[1,0,0] op_sel_hi:[1,1,1]
	ds_read_b64 v[38:39], v138 offset:8512
	s_waitcnt lgkmcnt(15)
	v_pk_fma_f32 v[8:9], v[40:41], v[128:129], v[8:9] op_sel_hi:[0,1,1]
	v_pk_fma_f32 v[8:9], v[40:41], v[130:131], v[8:9] op_sel:[1,0,0] op_sel_hi:[1,1,1]
	ds_read_b64 v[40:41], v138 offset:12736
	s_waitcnt lgkmcnt(15)
	v_pk_fma_f32 v[10:11], v[42:43], v[128:129], v[10:11] op_sel_hi:[0,1,1]
	v_pk_fma_f32 v[10:11], v[42:43], v[130:131], v[10:11] op_sel:[1,0,0] op_sel_hi:[1,1,1]
	ds_read_b64 v[42:43], v138 offset:16960
	s_waitcnt lgkmcnt(15)
	v_pk_fma_f32 v[12:13], v[44:45], v[128:129], v[12:13] op_sel_hi:[0,1,1]
	v_pk_fma_f32 v[12:13], v[44:45], v[130:131], v[12:13] op_sel:[1,0,0] op_sel_hi:[1,1,1]
	ds_read_b64 v[44:45], v138 offset:21184
	s_waitcnt lgkmcnt(15)
	v_pk_fma_f32 v[14:15], v[46:47], v[128:129], v[14:15] op_sel_hi:[0,1,1]
	v_pk_fma_f32 v[14:15], v[46:47], v[130:131], v[14:15] op_sel:[1,0,0] op_sel_hi:[1,1,1]
	ds_read_b64 v[46:47], v138 offset:25408
	s_waitcnt lgkmcnt(15)
	v_pk_fma_f32 v[16:17], v[48:49], v[128:129], v[16:17] op_sel_hi:[0,1,1]
	v_pk_fma_f32 v[16:17], v[48:49], v[130:131], v[16:17] op_sel:[1,0,0] op_sel_hi:[1,1,1]
	ds_read_b64 v[48:49], v138 offset:29632
	s_waitcnt lgkmcnt(15)
	v_pk_fma_f32 v[18:19], v[84:85], v[128:129], v[18:19] op_sel_hi:[0,1,1]
	v_pk_fma_f32 v[18:19], v[84:85], v[130:131], v[18:19] op_sel:[1,0,0] op_sel_hi:[1,1,1]
	ds_read_b64 v[84:85], v138 offset:33856
	s_waitcnt lgkmcnt(15)
	v_pk_fma_f32 v[20:21], v[86:87], v[128:129], v[20:21] op_sel_hi:[0,1,1]
	v_pk_fma_f32 v[20:21], v[86:87], v[130:131], v[20:21] op_sel:[1,0,0] op_sel_hi:[1,1,1]
	ds_read_b64 v[86:87], v138 offset:38080
	s_waitcnt lgkmcnt(15)
	v_pk_fma_f32 v[22:23], v[88:89], v[128:129], v[22:23] op_sel_hi:[0,1,1]
	v_pk_fma_f32 v[22:23], v[88:89], v[130:131], v[22:23] op_sel:[1,0,0] op_sel_hi:[1,1,1]
	ds_read_b64 v[88:89], v138 offset:42304
	s_waitcnt lgkmcnt(15)
	v_pk_fma_f32 v[24:25], v[90:91], v[128:129], v[24:25] op_sel_hi:[0,1,1]
	v_pk_fma_f32 v[24:25], v[90:91], v[130:131], v[24:25] op_sel:[1,0,0] op_sel_hi:[1,1,1]
	ds_read_b64 v[90:91], v138 offset:46528
	s_waitcnt lgkmcnt(15)
	v_pk_fma_f32 v[26:27], v[92:93], v[128:129], v[26:27] op_sel_hi:[0,1,1]
	v_pk_fma_f32 v[26:27], v[92:93], v[130:131], v[26:27] op_sel:[1,0,0] op_sel_hi:[1,1,1]
	ds_read_b64 v[92:93], v138 offset:50752
	s_waitcnt lgkmcnt(15)
	v_pk_fma_f32 v[28:29], v[94:95], v[128:129], v[28:29] op_sel_hi:[0,1,1]
	v_pk_fma_f32 v[28:29], v[94:95], v[130:131], v[28:29] op_sel:[1,0,0] op_sel_hi:[1,1,1]
	ds_read_b64 v[94:95], v138 offset:54976
	s_waitcnt lgkmcnt(15)
	v_pk_fma_f32 v[30:31], v[96:97], v[128:129], v[30:31] op_sel_hi:[0,1,1]
	v_pk_fma_f32 v[30:31], v[96:97], v[130:131], v[30:31] op_sel:[1,0,0] op_sel_hi:[1,1,1]
	ds_read_b64 v[96:97], v138 offset:59200
	s_waitcnt lgkmcnt(15)
	v_pk_fma_f32 v[32:33], v[98:99], v[128:129], v[32:33] op_sel_hi:[0,1,1]
	v_pk_fma_f32 v[32:33], v[98:99], v[130:131], v[32:33] op_sel:[1,0,0] op_sel_hi:[1,1,1]
	ds_read_b64 v[98:99], v138 offset:63424
	global_load_dwordx2 v[128:129], v[134:135], off offset:-2048
	global_load_dwordx2 v[130:131], v[134:135], off offset:2048
	v_lshl_add_u64 v[134:135], v[134:135], 0, s[0:1]
	v_add_u32_e32 v138, 64, v138
	s_add_u32 s2, s2, 1
	s_cmp_lt_u32 s2, 7
	s_cbranch_scc1 .Lpvd_loop
; __device__ __forceinline__ float bflo(unsigned w) { return __uint_as_float(w << 16); }
; __device__ __forceinline__ float bfhi(unsigned w) { return __uint_as_float(w & 0xffff0000u); }
; template <int BR>
; __device__ __forceinline__ void sample_unit(const SampP& P, int bs, int h, char* lds, float lam) {
;     ...
;     for (int k5 = 0; k5 < 13; ++k5) { const int keyb = 130 * wid + 10 * k5 + hf;
;       f32x4 v[5];
; #pragma unroll
;       for (int e = 0; e < 5; ++e) { const int key = keyb + 2 * e;
;         if (key < PAST) v[e] = *(const f32x4*)(Vc + (size_t)key * 1024 + 4 * l31);
;         else { const u32x2 w = *(const u32x2*)(Vn + (size_t)(key - PAST) * 1024 + 4 * l31); v[e] = (f32x4){bflo(w.x), bfhi(w.x), bflo(w.y), bfhi(w.y)}; } }
; #pragma unroll
;       for (int e = 0; e < 5; ++e) { const float* sp = S1 + keyb + 2 * e;
; #pragma unroll
;         for (int q = 0; q < 16; ++q) acc[q] += sp[q * SST] * v[e];
;         asm volatile("" ::: "memory"); }
	global_load_dword v141, v[136:137], off
	global_load_dword v142, v[136:137], off offset:2048
	s_waitcnt vmcnt(16)
	s_waitcnt lgkmcnt(15)
	v_pk_fma_f32 v[2:3], v[34:35], v[100:101], v[2:3] op_sel_hi:[0,1,1]
	v_pk_fma_f32 v[2:3], v[34:35], v[102:103], v[2:3] op_sel:[1,0,0] op_sel_hi:[1,1,1]
	ds_read_b64 v[34:35], v138 offset:8
	s_waitcnt lgkmcnt(15)
	v_pk_fma_f32 v[4:5], v[36:37], v[100:101], v[4:5] op_sel_hi:[0,1,1]
	v_pk_fma_f32 v[4:5], v[36:37], v[102:103], v[4:5] op_sel:[1,0,0] op_sel_hi:[1,1,1]
	ds_read_b64 v[36:37], v138 offset:4232
	s_waitcnt lgkmcnt(15)
	v_pk_fma_f32 v[6:7], v[38:39], v[100:101], v[6:7] op_sel_hi:[0,1,1]
	v_pk_fma_f32 v[6:7], v[38:39], v[102:103], v[6:7] op_sel:[1,0,0] op_sel_hi:[1,1,1]
	ds_read_b64 v[38:39], v138 offset:8456
	s_waitcnt lgkmcnt(15)
	v_pk_fma_f32 v[8:9], v[40:41], v[100:101], v[8:9] op_sel_hi:[0,1,1]
	v_pk_fma_f32 v[8:9], v[40:41], v[102:103], v[8:9] op_sel:[1,0,0] op_sel_hi:[1,1,1]
	ds_read_b64 v[40:41], v138 offset:12680
	s_waitcnt lgkmcnt(15)
	v_pk_fma_f32 v[10:11], v[42:43], v[100:101], v[10:11] op_sel_hi:[0,1,1]
	v_pk_fma_f32 v[10:11], v[42:43], v[102:103], v[10:11] op_sel:[1,0,0] op_sel_hi:[1,1,1]
	ds_read_b64 v[42:43], v138 offset:16904
	s_waitcnt lgkmcnt(15)
	v_pk_fma_f32 v[12:13], v[44:45], v[100:101], v[12:13] op_sel_hi:[0,1,1]
	v_pk_fma_f32 v[12:13], v[44:45], v[102:103], v[12:13] op_sel:[1,0,0] op_sel_hi:[1,1,1]
	ds_read_b64 v[44:45], v138 offset:21128
	s_waitcnt lgkmcnt(15)
	v_pk_fma_f32 v[14:15], v[46:47], v[100:101], v[14:15] op_sel_hi:[0,1,1]
	v_pk_fma_f32 v[14:15], v[46:47], v[102:103], v[14:15] op_sel:[1,0,0] op_sel_hi:[1,1,1]
	ds_read_b64 v[46:47], v138 offset:25352
	s_waitcnt lgkmcnt(15)
	v_pk_fma_f32 v[16:17], v[48:49], v[100:101], v[16:17] op_sel_hi:[0,1,1]
	v_pk_fma_f32 v[16:17], v[48:49], v[102:103], v[16:17] op_sel:[1,0,0] op_sel_hi:[1,1,1]
	ds_read_b64 v[48:49], v138 offset:29576
	s_waitcnt lgkmcnt(15)
	v_pk_fma_f32 v[18:19], v[84:85], v[100:101], v[18:19] op_sel_hi:[0,1,1]
	v_pk_fma_f32 v[18:19], v[84:85], v[102:103], v[18:19] op_sel:[1,0,0] op_sel_hi:[1,1,1]
	ds_read_b64 v[84:85], v138 offset:33800
	s_waitcnt lgkmcnt(15)
	v_pk_fma_f32 v[20:21], v[86:87], v[100:101], v[20:21] op_sel_hi:[0,1,1]
	v_pk_fma_f32 v[20:21], v[86:87], v[102:103], v[20:21] op_sel:[1,0,0] op_sel_hi:[1,1,1]
	ds_read_b64 v[86:87], v138 offset:38024
	s_waitcnt lgkmcnt(15)
	v_pk_fma_f32 v[22:23], v[88:89], v[100:101], v[22:23] op_sel_hi:[0,1,1]
	v_pk_fma_f32 v[22:23], v[88:89], v[102:103], v[22:23] op_sel:[1,0,0] op_sel_hi:[1,1,1]
	ds_read_b64 v[88:89], v138 offset:42248
	s_waitcnt lgkmcnt(15)
	v_pk_fma_f32 v[24:25], v[90:91], v[100:101], v[24:25] op_sel_hi:[0,1,1]
	v_pk_fma_f32 v[24:25], v[90:91], v[102:103], v[24:25] op_sel:[1,0,0] op_sel_hi:[1,1,1]
	ds_read_b64 v[90:91], v138 offset:46472
	s_waitcnt lgkmcnt(15)
	v_pk_fma_f32 v[26:27], v[92:93], v[100:101], v[26:27] op_sel_hi:[0,1,1]
	v_pk_fma_f32 v[26:27], v[92:93], v[102:103], v[26:27] op_sel:[1,0,0] op_sel_hi:[1,1,1]
	ds_read_b64 v[92:93], v138 offset:50696
	s_waitcnt lgkmcnt(15)
	v_pk_fma_f32 v[28:29], v[94:95], v[100:101], v[28:29] op_sel_hi:[0,1,1]
	v_pk_fma_f32 v[28:29], v[94:95], v[102:103], v[28:29] op_sel:[1,0,0] op_sel_hi:[1,1,1]
	ds_read_b64 v[94:95], v138 offset:54920
	s_waitcnt lgkmcnt(15)
	v_pk_fma_f32 v[30:31], v[96:97], v[100:101], v[30:31] op_sel_hi:[0,1,1]
	v_pk_fma_f32 v[30:31], v[96:97], v[102:103], v[30:31] op_sel:[1,0,0] op_sel_hi:[1,1,1]
	ds_read_b64 v[96:97], v138 offset:59144
	s_waitcnt lgkmcnt(15)
	v_pk_fma_f32 v[32:33], v[98:99], v[100:101], v[32:33] op_sel_hi:[0,1,1]
	v_pk_fma_f32 v[32:33], v[98:99], v[102:103], v[32:33] op_sel:[1,0,0] op_sel_hi:[1,1,1]
	ds_read_b64 v[98:99], v138 offset:63368
	s_waitcnt vmcnt(14)
	s_waitcnt lgkmcnt(15)
	v_pk_fma_f32 v[2:3], v[34:35], v[104:105], v[2:3] op_sel_hi:[0,1,1]
	v_pk_fma_f32 v[2:3], v[34:35], v[106:107], v[2:3] op_sel:[1,0,0] op_sel_hi:[1,1,1]
	ds_read_b64 v[34:35], v138 offset:16
	s_waitcnt lgkmcnt(15)
	v_pk_fma_f32 v[4:5], v[36:37], v[104:105], v[4:5] op_sel_hi:[0,1,1]
	v_pk_fma_f32 v[4:5], v[36:37], v[106:107], v[4:5] op_sel:[1,0,0] op_sel_hi:[1,1,1]
	ds_read_b64 v[36:37], v138 offset:4240
	s_waitcnt lgkmcnt(15)
	v_pk_fma_f32 v[6:7], v[38:39], v[104:105], v[6:7] op_sel_hi:[0,1,1]
	v_pk_fma_f32 v[6:7], v[38:39], v[106:107], v[6:7] op_sel:[1,0,0] op_sel_hi:[1,1,1]
	ds_read_b64 v[38:39], v138 offset:8464
	s_waitcnt lgkmcnt(15)
	v_pk_fma_f32 v[8:9], v[40:41], v[104:105], v[8:9] op_sel_hi:[0,1,1]
	v_pk_fma_f32 v[8:9], v[40:41], v[106:107], v[8:9] op_sel:[1,0,0] op_sel_hi:[1,1,1]
	ds_read_b64 v[40:41], v138 offset:12688
	s_waitcnt lgkmcnt(15)
	v_pk_fma_f32 v[10:11], v[42:43], v[104:105], v[10:11] op_sel_hi:[0,1,1]
	v_pk_fma_f32 v[10:11], v[42:43], v[106:107], v[10:11] op_sel:[1,0,0] op_sel_hi:[1,1,1]
	ds_read_b64 v[42:43], v138 offset:16912
	s_waitcnt lgkmcnt(15)
	v_pk_fma_f32 v[12:13], v[44:45], v[104:105], v[12:13] op_sel_hi:[0,1,1]
	v_pk_fma_f32 v[12:13], v[44:45], v[106:107], v[12:13] op_sel:[1,0,0] op_sel_hi:[1,1,1]
	ds_read_b64 v[44:45], v138 offset:21136
	s_waitcnt lgkmcnt(15)
	v_pk_fma_f32 v[14:15], v[46:47], v[104:105], v[14:15] op_sel_hi:[0,1,1]
	v_pk_fma_f32 v[14:15], v[46:47], v[106:107], v[14:15] op_sel:[1,0,0] op_sel_hi:[1,1,1]
	ds_read_b64 v[46:47], v138 offset:25360
	s_waitcnt lgkmcnt(15)
	v_pk_fma_f32 v[16:17], v[48:49], v[104:105], v[16:17] op_sel_hi:[0,1,1]
	v_pk_fma_f32 v[16:17], v[48:49], v[106:107], v[16:17] op_sel:[1,0,0] op_sel_hi:[1,1,1]
	ds_read_b64 v[48:49], v138 offset:29584
	s_waitcnt lgkmcnt(15)
	v_pk_fma_f32 v[18:19], v[84:85], v[104:105], v[18:19] op_sel_hi:[0,1,1]
	v_pk_fma_f32 v[18:19], v[84:85], v[106:107], v[18:19] op_sel:[1,0,0] op_sel_hi:[1,1,1]
	ds_read_b64 v[84:85], v138 offset:33808
	s_waitcnt lgkmcnt(15)
; __device__ __forceinline__ float bflo(unsigned w) { return __uint_as_float(w << 16); }
; __device__ __forceinline__ float bfhi(unsigned w) { return __uint_as_float(w & 0xffff0000u); }
; template <int BR>
; __device__ __forceinline__ void sample_unit(const SampP& P, int bs, int h, char* lds, float lam) {
;     ...
;     for (int k5 = 0; k5 < 13; ++k5) { const int keyb = 130 * wid + 10 * k5 + hf;
;       f32x4 v[5];
; #pragma unroll
;       for (int e = 0; e < 5; ++e) { const int key = keyb + 2 * e;
;         if (key < PAST) v[e] = *(const f32x4*)(Vc + (size_t)key * 1024 + 4 * l31);
;         else { const u32x2 w = *(const u32x2*)(Vn + (size_t)(key - PAST) * 1024 + 4 * l31); v[e] = (f32x4){bflo(w.x), bfhi(w.x), bflo(w.y), bfhi(w.y)}; } }
; #pragma unroll
;       for (int e = 0; e < 5; ++e) { const float* sp = S1 + keyb + 2 * e;
; #pragma unroll
;         for (int q = 0; q < 16; ++q) acc[q] += sp[q * SST] * v[e];
;         asm volatile("" ::: "memory"); }
	v_pk_fma_f32 v[20:21], v[86:87], v[104:105], v[20:21] op_sel_hi:[0,1,1]
	v_pk_fma_f32 v[20:21], v[86:87], v[106:107], v[20:21] op_sel:[1,0,0] op_sel_hi:[1,1,1]
	ds_read_b64 v[86:87], v138 offset:38032
	s_waitcnt lgkmcnt(15)
	v_pk_fma_f32 v[22:23], v[88:89], v[104:105], v[22:23] op_sel_hi:[0,1,1]
	v_pk_fma_f32 v[22:23], v[88:89], v[106:107], v[22:23] op_sel:[1,0,0] op_sel_hi:[1,1,1]
	ds_read_b64 v[88:89], v138 offset:42256
	s_waitcnt lgkmcnt(15)
	v_pk_fma_f32 v[24:25], v[90:91], v[104:105], v[24:25] op_sel_hi:[0,1,1]
	v_pk_fma_f32 v[24:25], v[90:91], v[106:107], v[24:25] op_sel:[1,0,0] op_sel_hi:[1,1,1]
	ds_read_b64 v[90:91], v138 offset:46480
	s_waitcnt lgkmcnt(15)
	v_pk_fma_f32 v[26:27], v[92:93], v[104:105], v[26:27] op_sel_hi:[0,1,1]
	v_pk_fma_f32 v[26:27], v[92:93], v[106:107], v[26:27] op_sel:[1,0,0] op_sel_hi:[1,1,1]
	ds_read_b64 v[92:93], v138 offset:50704
	s_waitcnt lgkmcnt(15)
	v_pk_fma_f32 v[28:29], v[94:95], v[104:105], v[28:29] op_sel_hi:[0,1,1]
	v_pk_fma_f32 v[28:29], v[94:95], v[106:107], v[28:29] op_sel:[1,0,0] op_sel_hi:[1,1,1]
	ds_read_b64 v[94:95], v138 offset:54928
	s_waitcnt lgkmcnt(15)
	v_pk_fma_f32 v[30:31], v[96:97], v[104:105], v[30:31] op_sel_hi:[0,1,1]
	v_pk_fma_f32 v[30:31], v[96:97], v[106:107], v[30:31] op_sel:[1,0,0] op_sel_hi:[1,1,1]
	ds_read_b64 v[96:97], v138 offset:59152
	s_waitcnt lgkmcnt(15)
	v_pk_fma_f32 v[32:33], v[98:99], v[104:105], v[32:33] op_sel_hi:[0,1,1]
	v_pk_fma_f32 v[32:33], v[98:99], v[106:107], v[32:33] op_sel:[1,0,0] op_sel_hi:[1,1,1]
	ds_read_b64 v[98:99], v138 offset:63376
	s_waitcnt vmcnt(12)
	s_waitcnt lgkmcnt(15)
	v_pk_fma_f32 v[2:3], v[34:35], v[108:109], v[2:3] op_sel_hi:[0,1,1]
	v_pk_fma_f32 v[2:3], v[34:35], v[110:111], v[2:3] op_sel:[1,0,0] op_sel_hi:[1,1,1]
	ds_read_b64 v[34:35], v138 offset:24
	s_waitcnt lgkmcnt(15)
	v_pk_fma_f32 v[4:5], v[36:37], v[108:109], v[4:5] op_sel_hi:[0,1,1]
	v_pk_fma_f32 v[4:5], v[36:37], v[110:111], v[4:5] op_sel:[1,0,0] op_sel_hi:[1,1,1]
	ds_read_b64 v[36:37], v138 offset:4248
	s_waitcnt lgkmcnt(15)
	v_pk_fma_f32 v[6:7], v[38:39], v[108:109], v[6:7] op_sel_hi:[0,1,1]
	v_pk_fma_f32 v[6:7], v[38:39], v[110:111], v[6:7] op_sel:[1,0,0] op_sel_hi:[1,1,1]
	ds_read_b64 v[38:39], v138 offset:8472
	s_waitcnt lgkmcnt(15)
	v_pk_fma_f32 v[8:9], v[40:41], v[108:109], v[8:9] op_sel_hi:[0,1,1]
	v_pk_fma_f32 v[8:9], v[40:41], v[110:111], v[8:9] op_sel:[1,0,0] op_sel_hi:[1,1,1]
	ds_read_b64 v[40:41], v138 offset:12696
	s_waitcnt lgkmcnt(15)
	v_pk_fma_f32 v[10:11], v[42:43], v[108:109], v[10:11] op_sel_hi:[0,1,1]
	v_pk_fma_f32 v[10:11], v[42:43], v[110:111], v[10:11] op_sel:[1,0,0] op_sel_hi:[1,1,1]
	ds_read_b64 v[42:43], v138 offset:16920
	s_waitcnt lgkmcnt(15)
	v_pk_fma_f32 v[12:13], v[44:45], v[108:109], v[12:13] op_sel_hi:[0,1,1]
	v_pk_fma_f32 v[12:13], v[44:45], v[110:111], v[12:13] op_sel:[1,0,0] op_sel_hi:[1,1,1]
	ds_read_b64 v[44:45], v138 offset:21144
	s_waitcnt lgkmcnt(15)
	v_pk_fma_f32 v[14:15], v[46:47], v[108:109], v[14:15] op_sel_hi:[0,1,1]
	v_pk_fma_f32 v[14:15], v[46:47], v[110:111], v[14:15] op_sel:[1,0,0] op_sel_hi:[1,1,1]
	ds_read_b64 v[46:47], v138 offset:25368
	s_waitcnt lgkmcnt(15)
	v_pk_fma_f32 v[16:17], v[48:49], v[108:109], v[16:17] op_sel_hi:[0,1,1]
	v_pk_fma_f32 v[16:17], v[48:49], v[110:111], v[16:17] op_sel:[1,0,0] op_sel_hi:[1,1,1]
	ds_read_b64 v[48:49], v138 offset:29592
	s_waitcnt lgkmcnt(15)
	v_pk_fma_f32 v[18:19], v[84:85], v[108:109], v[18:19] op_sel_hi:[0,1,1]
	v_pk_fma_f32 v[18:19], v[84:85], v[110:111], v[18:19] op_sel:[1,0,0] op_sel_hi:[1,1,1]
	ds_read_b64 v[84:85], v138 offset:33816
	s_waitcnt lgkmcnt(15)
	v_pk_fma_f32 v[20:21], v[86:87], v[108:109], v[20:21] op_sel_hi:[0,1,1]
	v_pk_fma_f32 v[20:21], v[86:87], v[110:111], v[20:21] op_sel:[1,0,0] op_sel_hi:[1,1,1]
	ds_read_b64 v[86:87], v138 offset:38040
	s_waitcnt lgkmcnt(15)
	v_pk_fma_f32 v[22:23], v[88:89], v[108:109], v[22:23] op_sel_hi:[0,1,1]
	v_pk_fma_f32 v[22:23], v[88:89], v[110:111], v[22:23] op_sel:[1,0,0] op_sel_hi:[1,1,1]
	ds_read_b64 v[88:89], v138 offset:42264
	s_waitcnt lgkmcnt(15)
	v_pk_fma_f32 v[24:25], v[90:91], v[108:109], v[24:25] op_sel_hi:[0,1,1]
	v_pk_fma_f32 v[24:25], v[90:91], v[110:111], v[24:25] op_sel:[1,0,0] op_sel_hi:[1,1,1]
	ds_read_b64 v[90:91], v138 offset:46488
	s_waitcnt lgkmcnt(15)
	v_pk_fma_f32 v[26:27], v[92:93], v[108:109], v[26:27] op_sel_hi:[0,1,1]
	v_pk_fma_f32 v[26:27], v[92:93], v[110:111], v[26:27] op_sel:[1,0,0] op_sel_hi:[1,1,1]
	ds_read_b64 v[92:93], v138 offset:50712
	s_waitcnt lgkmcnt(15)
	v_pk_fma_f32 v[28:29], v[94:95], v[108:109], v[28:29] op_sel_hi:[0,1,1]
	v_pk_fma_f32 v[28:29], v[94:95], v[110:111], v[28:29] op_sel:[1,0,0] op_sel_hi:[1,1,1]
	ds_read_b64 v[94:95], v138 offset:54936
	s_waitcnt lgkmcnt(15)
	v_pk_fma_f32 v[30:31], v[96:97], v[108:109], v[30:31] op_sel_hi:[0,1,1]
	v_pk_fma_f32 v[30:31], v[96:97], v[110:111], v[30:31] op_sel:[1,0,0] op_sel_hi:[1,1,1]
	ds_read_b64 v[96:97], v138 offset:59160
	s_waitcnt lgkmcnt(15)
	v_pk_fma_f32 v[32:33], v[98:99], v[108:109], v[32:33] op_sel_hi:[0,1,1]
	v_pk_fma_f32 v[32:33], v[98:99], v[110:111], v[32:33] op_sel:[1,0,0] op_sel_hi:[1,1,1]
	ds_read_b64 v[98:99], v138 offset:63384
	s_waitcnt vmcnt(10)
	s_waitcnt lgkmcnt(15)
	v_pk_fma_f32 v[2:3], v[34:35], v[112:113], v[2:3] op_sel_hi:[0,1,1]
	v_pk_fma_f32 v[2:3], v[34:35], v[114:115], v[2:3] op_sel:[1,0,0] op_sel_hi:[1,1,1]
	ds_read_b64 v[34:35], v138 offset:32
	s_waitcnt lgkmcnt(15)
	v_pk_fma_f32 v[4:5], v[36:37], v[112:113], v[4:5] op_sel_hi:[0,1,1]
	v_pk_fma_f32 v[4:5], v[36:37], v[114:115], v[4:5] op_sel:[1,0,0] op_sel_hi:[1,1,1]
	ds_read_b64 v[36:37], v138 offset:4256
	s_waitcnt lgkmcnt(15)
; __device__ __forceinline__ float bflo(unsigned w) { return __uint_as_float(w << 16); }
; __device__ __forceinline__ float bfhi(unsigned w) { return __uint_as_float(w & 0xffff0000u); }
; template <int BR>
; __device__ __forceinline__ void sample_unit(const SampP& P, int bs, int h, char* lds, float lam) {
;     ...
;     for (int k5 = 0; k5 < 13; ++k5) { const int keyb = 130 * wid + 10 * k5 + hf;
;       f32x4 v[5];
; #pragma unroll
;       for (int e = 0; e < 5; ++e) { const int key = keyb + 2 * e;
;         if (key < PAST) v[e] = *(const f32x4*)(Vc + (size_t)key * 1024 + 4 * l31);
;         else { const u32x2 w = *(const u32x2*)(Vn + (size_t)(key - PAST) * 1024 + 4 * l31); v[e] = (f32x4){bflo(w.x), bfhi(w.x), bflo(w.y), bfhi(w.y)}; } }
; #pragma unroll
;       for (int e = 0; e < 5; ++e) { const float* sp = S1 + keyb + 2 * e;
; #pragma unroll
;         for (int q = 0; q < 16; ++q) acc[q] += sp[q * SST] * v[e];
;         asm volatile("" ::: "memory"); }
	v_pk_fma_f32 v[6:7], v[38:39], v[112:113], v[6:7] op_sel_hi:[0,1,1]
	v_pk_fma_f32 v[6:7], v[38:39], v[114:115], v[6:7] op_sel:[1,0,0] op_sel_hi:[1,1,1]
	ds_read_b64 v[38:39], v138 offset:8480
	s_waitcnt lgkmcnt(15)
	v_pk_fma_f32 v[8:9], v[40:41], v[112:113], v[8:9] op_sel_hi:[0,1,1]
	v_pk_fma_f32 v[8:9], v[40:41], v[114:115], v[8:9] op_sel:[1,0,0] op_sel_hi:[1,1,1]
	ds_read_b64 v[40:41], v138 offset:12704
	s_waitcnt lgkmcnt(15)
	v_pk_fma_f32 v[10:11], v[42:43], v[112:113], v[10:11] op_sel_hi:[0,1,1]
	v_pk_fma_f32 v[10:11], v[42:43], v[114:115], v[10:11] op_sel:[1,0,0] op_sel_hi:[1,1,1]
	ds_read_b64 v[42:43], v138 offset:16928
	s_waitcnt lgkmcnt(15)
	v_pk_fma_f32 v[12:13], v[44:45], v[112:113], v[12:13] op_sel_hi:[0,1,1]
	v_pk_fma_f32 v[12:13], v[44:45], v[114:115], v[12:13] op_sel:[1,0,0] op_sel_hi:[1,1,1]
	ds_read_b64 v[44:45], v138 offset:21152
	s_waitcnt lgkmcnt(15)
	v_pk_fma_f32 v[14:15], v[46:47], v[112:113], v[14:15] op_sel_hi:[0,1,1]
	v_pk_fma_f32 v[14:15], v[46:47], v[114:115], v[14:15] op_sel:[1,0,0] op_sel_hi:[1,1,1]
	ds_read_b64 v[46:47], v138 offset:25376
	s_waitcnt lgkmcnt(15)
	v_pk_fma_f32 v[16:17], v[48:49], v[112:113], v[16:17] op_sel_hi:[0,1,1]
	v_pk_fma_f32 v[16:17], v[48:49], v[114:115], v[16:17] op_sel:[1,0,0] op_sel_hi:[1,1,1]
	ds_read_b64 v[48:49], v138 offset:29600
	s_waitcnt lgkmcnt(15)
	v_pk_fma_f32 v[18:19], v[84:85], v[112:113], v[18:19] op_sel_hi:[0,1,1]
	v_pk_fma_f32 v[18:19], v[84:85], v[114:115], v[18:19] op_sel:[1,0,0] op_sel_hi:[1,1,1]
	ds_read_b64 v[84:85], v138 offset:33824
	s_waitcnt lgkmcnt(15)
	v_pk_fma_f32 v[20:21], v[86:87], v[112:113], v[20:21] op_sel_hi:[0,1,1]
	v_pk_fma_f32 v[20:21], v[86:87], v[114:115], v[20:21] op_sel:[1,0,0] op_sel_hi:[1,1,1]
	ds_read_b64 v[86:87], v138 offset:38048
	s_waitcnt lgkmcnt(15)
	v_pk_fma_f32 v[22:23], v[88:89], v[112:113], v[22:23] op_sel_hi:[0,1,1]
	v_pk_fma_f32 v[22:23], v[88:89], v[114:115], v[22:23] op_sel:[1,0,0] op_sel_hi:[1,1,1]
	ds_read_b64 v[88:89], v138 offset:42272
	s_waitcnt lgkmcnt(15)
	v_pk_fma_f32 v[24:25], v[90:91], v[112:113], v[24:25] op_sel_hi:[0,1,1]
	v_pk_fma_f32 v[24:25], v[90:91], v[114:115], v[24:25] op_sel:[1,0,0] op_sel_hi:[1,1,1]
	ds_read_b64 v[90:91], v138 offset:46496
	s_waitcnt lgkmcnt(15)
	v_pk_fma_f32 v[26:27], v[92:93], v[112:113], v[26:27] op_sel_hi:[0,1,1]
	v_pk_fma_f32 v[26:27], v[92:93], v[114:115], v[26:27] op_sel:[1,0,0] op_sel_hi:[1,1,1]
	ds_read_b64 v[92:93], v138 offset:50720
	s_waitcnt lgkmcnt(15)
	v_pk_fma_f32 v[28:29], v[94:95], v[112:113], v[28:29] op_sel_hi:[0,1,1]
	v_pk_fma_f32 v[28:29], v[94:95], v[114:115], v[28:29] op_sel:[1,0,0] op_sel_hi:[1,1,1]
	ds_read_b64 v[94:95], v138 offset:54944
	s_waitcnt lgkmcnt(15)
	v_pk_fma_f32 v[30:31], v[96:97], v[112:113], v[30:31] op_sel_hi:[0,1,1]
	v_pk_fma_f32 v[30:31], v[96:97], v[114:115], v[30:31] op_sel:[1,0,0] op_sel_hi:[1,1,1]
	ds_read_b64 v[96:97], v138 offset:59168
	s_waitcnt lgkmcnt(15)
	v_pk_fma_f32 v[32:33], v[98:99], v[112:113], v[32:33] op_sel_hi:[0,1,1]
	v_pk_fma_f32 v[32:33], v[98:99], v[114:115], v[32:33] op_sel:[1,0,0] op_sel_hi:[1,1,1]
	ds_read_b64 v[98:99], v138 offset:63392
	s_waitcnt vmcnt(8)
	s_waitcnt lgkmcnt(15)
	v_pk_fma_f32 v[2:3], v[34:35], v[116:117], v[2:3] op_sel_hi:[0,1,1]
	v_pk_fma_f32 v[2:3], v[34:35], v[118:119], v[2:3] op_sel:[1,0,0] op_sel_hi:[1,1,1]
	ds_read_b64 v[34:35], v138 offset:40
	s_waitcnt lgkmcnt(15)
	v_pk_fma_f32 v[4:5], v[36:37], v[116:117], v[4:5] op_sel_hi:[0,1,1]
	v_pk_fma_f32 v[4:5], v[36:37], v[118:119], v[4:5] op_sel:[1,0,0] op_sel_hi:[1,1,1]
	ds_read_b64 v[36:37], v138 offset:4264
	s_waitcnt lgkmcnt(15)
	v_pk_fma_f32 v[6:7], v[38:39], v[116:117], v[6:7] op_sel_hi:[0,1,1]
	v_pk_fma_f32 v[6:7], v[38:39], v[118:119], v[6:7] op_sel:[1,0,0] op_sel_hi:[1,1,1]
	ds_read_b64 v[38:39], v138 offset:8488
	s_waitcnt lgkmcnt(15)
	v_pk_fma_f32 v[8:9], v[40:41], v[116:117], v[8:9] op_sel_hi:[0,1,1]
	v_pk_fma_f32 v[8:9], v[40:41], v[118:119], v[8:9] op_sel:[1,0,0] op_sel_hi:[1,1,1]
	ds_read_b64 v[40:41], v138 offset:12712
	s_waitcnt lgkmcnt(15)
	v_pk_fma_f32 v[10:11], v[42:43], v[116:117], v[10:11] op_sel_hi:[0,1,1]
	v_pk_fma_f32 v[10:11], v[42:43], v[118:119], v[10:11] op_sel:[1,0,0] op_sel_hi:[1,1,1]
	ds_read_b64 v[42:43], v138 offset:16936
	s_waitcnt lgkmcnt(15)
	v_pk_fma_f32 v[12:13], v[44:45], v[116:117], v[12:13] op_sel_hi:[0,1,1]
	v_pk_fma_f32 v[12:13], v[44:45], v[118:119], v[12:13] op_sel:[1,0,0] op_sel_hi:[1,1,1]
	ds_read_b64 v[44:45], v138 offset:21160
	s_waitcnt lgkmcnt(15)
	v_pk_fma_f32 v[14:15], v[46:47], v[116:117], v[14:15] op_sel_hi:[0,1,1]
	v_pk_fma_f32 v[14:15], v[46:47], v[118:119], v[14:15] op_sel:[1,0,0] op_sel_hi:[1,1,1]
	ds_read_b64 v[46:47], v138 offset:25384
	s_waitcnt lgkmcnt(15)
	v_pk_fma_f32 v[16:17], v[48:49], v[116:117], v[16:17] op_sel_hi:[0,1,1]
	v_pk_fma_f32 v[16:17], v[48:49], v[118:119], v[16:17] op_sel:[1,0,0] op_sel_hi:[1,1,1]
	ds_read_b64 v[48:49], v138 offset:29608
	s_waitcnt lgkmcnt(15)
	v_pk_fma_f32 v[18:19], v[84:85], v[116:117], v[18:19] op_sel_hi:[0,1,1]
	v_pk_fma_f32 v[18:19], v[84:85], v[118:119], v[18:19] op_sel:[1,0,0] op_sel_hi:[1,1,1]
	ds_read_b64 v[84:85], v138 offset:33832
	s_waitcnt lgkmcnt(15)
	v_pk_fma_f32 v[20:21], v[86:87], v[116:117], v[20:21] op_sel_hi:[0,1,1]
	v_pk_fma_f32 v[20:21], v[86:87], v[118:119], v[20:21] op_sel:[1,0,0] op_sel_hi:[1,1,1]
	ds_read_b64 v[86:87], v138 offset:38056
	s_waitcnt lgkmcnt(15)
	v_pk_fma_f32 v[22:23], v[88:89], v[116:117], v[22:23] op_sel_hi:[0,1,1]
	v_pk_fma_f32 v[22:23], v[88:89], v[118:119], v[22:23] op_sel:[1,0,0] op_sel_hi:[1,1,1]
	ds_read_b64 v[88:89], v138 offset:42280
	s_waitcnt lgkmcnt(15)
; __device__ __forceinline__ float bflo(unsigned w) { return __uint_as_float(w << 16); }
; __device__ __forceinline__ float bfhi(unsigned w) { return __uint_as_float(w & 0xffff0000u); }
; template <int BR>
; __device__ __forceinline__ void sample_unit(const SampP& P, int bs, int h, char* lds, float lam) {
;     ...
;     for (int k5 = 0; k5 < 13; ++k5) { const int keyb = 130 * wid + 10 * k5 + hf;
;       f32x4 v[5];
; #pragma unroll
;       for (int e = 0; e < 5; ++e) { const int key = keyb + 2 * e;
;         if (key < PAST) v[e] = *(const f32x4*)(Vc + (size_t)key * 1024 + 4 * l31);
;         else { const u32x2 w = *(const u32x2*)(Vn + (size_t)(key - PAST) * 1024 + 4 * l31); v[e] = (f32x4){bflo(w.x), bfhi(w.x), bflo(w.y), bfhi(w.y)}; } }
; #pragma unroll
;       for (int e = 0; e < 5; ++e) { const float* sp = S1 + keyb + 2 * e;
; #pragma unroll
;         for (int q = 0; q < 16; ++q) acc[q] += sp[q * SST] * v[e];
;         asm volatile("" ::: "memory"); }
	v_pk_fma_f32 v[24:25], v[90:91], v[116:117], v[24:25] op_sel_hi:[0,1,1]
	v_pk_fma_f32 v[24:25], v[90:91], v[118:119], v[24:25] op_sel:[1,0,0] op_sel_hi:[1,1,1]
	ds_read_b64 v[90:91], v138 offset:46504
	s_waitcnt lgkmcnt(15)
	v_pk_fma_f32 v[26:27], v[92:93], v[116:117], v[26:27] op_sel_hi:[0,1,1]
	v_pk_fma_f32 v[26:27], v[92:93], v[118:119], v[26:27] op_sel:[1,0,0] op_sel_hi:[1,1,1]
	ds_read_b64 v[92:93], v138 offset:50728
	s_waitcnt lgkmcnt(15)
	v_pk_fma_f32 v[28:29], v[94:95], v[116:117], v[28:29] op_sel_hi:[0,1,1]
	v_pk_fma_f32 v[28:29], v[94:95], v[118:119], v[28:29] op_sel:[1,0,0] op_sel_hi:[1,1,1]
	ds_read_b64 v[94:95], v138 offset:54952
	s_waitcnt lgkmcnt(15)
	v_pk_fma_f32 v[30:31], v[96:97], v[116:117], v[30:31] op_sel_hi:[0,1,1]
	v_pk_fma_f32 v[30:31], v[96:97], v[118:119], v[30:31] op_sel:[1,0,0] op_sel_hi:[1,1,1]
	ds_read_b64 v[96:97], v138 offset:59176
	s_waitcnt lgkmcnt(15)
	v_pk_fma_f32 v[32:33], v[98:99], v[116:117], v[32:33] op_sel_hi:[0,1,1]
	v_pk_fma_f32 v[32:33], v[98:99], v[118:119], v[32:33] op_sel:[1,0,0] op_sel_hi:[1,1,1]
	ds_read_b64 v[98:99], v138 offset:63400
	s_waitcnt vmcnt(6)
	s_waitcnt lgkmcnt(15)
	v_pk_fma_f32 v[2:3], v[34:35], v[120:121], v[2:3] op_sel_hi:[0,1,1]
	v_pk_fma_f32 v[2:3], v[34:35], v[122:123], v[2:3] op_sel:[1,0,0] op_sel_hi:[1,1,1]
	ds_read_b64 v[34:35], v138 offset:48
	s_waitcnt lgkmcnt(15)
	v_pk_fma_f32 v[4:5], v[36:37], v[120:121], v[4:5] op_sel_hi:[0,1,1]
	v_pk_fma_f32 v[4:5], v[36:37], v[122:123], v[4:5] op_sel:[1,0,0] op_sel_hi:[1,1,1]
	ds_read_b64 v[36:37], v138 offset:4272
	s_waitcnt lgkmcnt(15)
	v_pk_fma_f32 v[6:7], v[38:39], v[120:121], v[6:7] op_sel_hi:[0,1,1]
	v_pk_fma_f32 v[6:7], v[38:39], v[122:123], v[6:7] op_sel:[1,0,0] op_sel_hi:[1,1,1]
	ds_read_b64 v[38:39], v138 offset:8496
	s_waitcnt lgkmcnt(15)
	v_pk_fma_f32 v[8:9], v[40:41], v[120:121], v[8:9] op_sel_hi:[0,1,1]
	v_pk_fma_f32 v[8:9], v[40:41], v[122:123], v[8:9] op_sel:[1,0,0] op_sel_hi:[1,1,1]
	ds_read_b64 v[40:41], v138 offset:12720
	s_waitcnt lgkmcnt(15)
	v_pk_fma_f32 v[10:11], v[42:43], v[120:121], v[10:11] op_sel_hi:[0,1,1]
	v_pk_fma_f32 v[10:11], v[42:43], v[122:123], v[10:11] op_sel:[1,0,0] op_sel_hi:[1,1,1]
	ds_read_b64 v[42:43], v138 offset:16944
	s_waitcnt lgkmcnt(15)
	v_pk_fma_f32 v[12:13], v[44:45], v[120:121], v[12:13] op_sel_hi:[0,1,1]
	v_pk_fma_f32 v[12:13], v[44:45], v[122:123], v[12:13] op_sel:[1,0,0] op_sel_hi:[1,1,1]
	ds_read_b64 v[44:45], v138 offset:21168
	s_waitcnt lgkmcnt(15)
	v_pk_fma_f32 v[14:15], v[46:47], v[120:121], v[14:15] op_sel_hi:[0,1,1]
	v_pk_fma_f32 v[14:15], v[46:47], v[122:123], v[14:15] op_sel:[1,0,0] op_sel_hi:[1,1,1]
	ds_read_b64 v[46:47], v138 offset:25392
	s_waitcnt lgkmcnt(15)
	v_pk_fma_f32 v[16:17], v[48:49], v[120:121], v[16:17] op_sel_hi:[0,1,1]
	v_pk_fma_f32 v[16:17], v[48:49], v[122:123], v[16:17] op_sel:[1,0,0] op_sel_hi:[1,1,1]
	ds_read_b64 v[48:49], v138 offset:29616
	s_waitcnt lgkmcnt(15)
	v_pk_fma_f32 v[18:19], v[84:85], v[120:121], v[18:19] op_sel_hi:[0,1,1]
	v_pk_fma_f32 v[18:19], v[84:85], v[122:123], v[18:19] op_sel:[1,0,0] op_sel_hi:[1,1,1]
	ds_read_b64 v[84:85], v138 offset:33840
	s_waitcnt lgkmcnt(15)
	v_pk_fma_f32 v[20:21], v[86:87], v[120:121], v[20:21] op_sel_hi:[0,1,1]
	v_pk_fma_f32 v[20:21], v[86:87], v[122:123], v[20:21] op_sel:[1,0,0] op_sel_hi:[1,1,1]
	ds_read_b64 v[86:87], v138 offset:38064
	s_waitcnt lgkmcnt(15)
	v_pk_fma_f32 v[22:23], v[88:89], v[120:121], v[22:23] op_sel_hi:[0,1,1]
	v_pk_fma_f32 v[22:23], v[88:89], v[122:123], v[22:23] op_sel:[1,0,0] op_sel_hi:[1,1,1]
	ds_read_b64 v[88:89], v138 offset:42288
	s_waitcnt lgkmcnt(15)
	v_pk_fma_f32 v[24:25], v[90:91], v[120:121], v[24:25] op_sel_hi:[0,1,1]
	v_pk_fma_f32 v[24:25], v[90:91], v[122:123], v[24:25] op_sel:[1,0,0] op_sel_hi:[1,1,1]
	ds_read_b64 v[90:91], v138 offset:46512
	s_waitcnt lgkmcnt(15)
	v_pk_fma_f32 v[26:27], v[92:93], v[120:121], v[26:27] op_sel_hi:[0,1,1]
	v_pk_fma_f32 v[26:27], v[92:93], v[122:123], v[26:27] op_sel:[1,0,0] op_sel_hi:[1,1,1]
	ds_read_b64 v[92:93], v138 offset:50736
	s_waitcnt lgkmcnt(15)
	v_pk_fma_f32 v[28:29], v[94:95], v[120:121], v[28:29] op_sel_hi:[0,1,1]
	v_pk_fma_f32 v[28:29], v[94:95], v[122:123], v[28:29] op_sel:[1,0,0] op_sel_hi:[1,1,1]
	ds_read_b64 v[94:95], v138 offset:54960
	s_waitcnt lgkmcnt(15)
	v_pk_fma_f32 v[30:31], v[96:97], v[120:121], v[30:31] op_sel_hi:[0,1,1]
	v_pk_fma_f32 v[30:31], v[96:97], v[122:123], v[30:31] op_sel:[1,0,0] op_sel_hi:[1,1,1]
	ds_read_b64 v[96:97], v138 offset:59184
	s_waitcnt lgkmcnt(15)
	v_pk_fma_f32 v[32:33], v[98:99], v[120:121], v[32:33] op_sel_hi:[0,1,1]
	v_pk_fma_f32 v[32:33], v[98:99], v[122:123], v[32:33] op_sel:[1,0,0] op_sel_hi:[1,1,1]
	ds_read_b64 v[98:99], v138 offset:63408
	s_waitcnt vmcnt(4)
	s_waitcnt lgkmcnt(15)
	v_pk_fma_f32 v[2:3], v[34:35], v[124:125], v[2:3] op_sel_hi:[0,1,1]
	v_pk_fma_f32 v[2:3], v[34:35], v[126:127], v[2:3] op_sel:[1,0,0] op_sel_hi:[1,1,1]
	ds_read_b64 v[34:35], v138 offset:56
	s_waitcnt lgkmcnt(15)
	v_pk_fma_f32 v[4:5], v[36:37], v[124:125], v[4:5] op_sel_hi:[0,1,1]
	v_pk_fma_f32 v[4:5], v[36:37], v[126:127], v[4:5] op_sel:[1,0,0] op_sel_hi:[1,1,1]
	ds_read_b64 v[36:37], v138 offset:4280
	s_waitcnt lgkmcnt(15)
	v_pk_fma_f32 v[6:7], v[38:39], v[124:125], v[6:7] op_sel_hi:[0,1,1]
	v_pk_fma_f32 v[6:7], v[38:39], v[126:127], v[6:7] op_sel:[1,0,0] op_sel_hi:[1,1,1]
	ds_read_b64 v[38:39], v138 offset:8504
	s_waitcnt lgkmcnt(15)
	v_pk_fma_f32 v[8:9], v[40:41], v[124:125], v[8:9] op_sel_hi:[0,1,1]
	v_pk_fma_f32 v[8:9], v[40:41], v[126:127], v[8:9] op_sel:[1,0,0] op_sel_hi:[1,1,1]
	ds_read_b64 v[40:41], v138 offset:12728
	s_waitcnt lgkmcnt(15)
; __device__ __forceinline__ float bflo(unsigned w) { return __uint_as_float(w << 16); }
; __device__ __forceinline__ float bfhi(unsigned w) { return __uint_as_float(w & 0xffff0000u); }
; template <int BR>
; __device__ __forceinline__ void sample_unit(const SampP& P, int bs, int h, char* lds, float lam) {
;     ...
;     for (int k5 = 0; k5 < 13; ++k5) { const int keyb = 130 * wid + 10 * k5 + hf;
;       f32x4 v[5];
; #pragma unroll
;       for (int e = 0; e < 5; ++e) { const int key = keyb + 2 * e;
;         if (key < PAST) v[e] = *(const f32x4*)(Vc + (size_t)key * 1024 + 4 * l31);
;         else { const u32x2 w = *(const u32x2*)(Vn + (size_t)(key - PAST) * 1024 + 4 * l31); v[e] = (f32x4){bflo(w.x), bfhi(w.x), bflo(w.y), bfhi(w.y)}; } }
; #pragma unroll
;       for (int e = 0; e < 5; ++e) { const float* sp = S1 + keyb + 2 * e;
; #pragma unroll
;         for (int q = 0; q < 16; ++q) acc[q] += sp[q * SST] * v[e];
;         asm volatile("" ::: "memory"); }
	v_pk_fma_f32 v[10:11], v[42:43], v[124:125], v[10:11] op_sel_hi:[0,1,1]
	v_pk_fma_f32 v[10:11], v[42:43], v[126:127], v[10:11] op_sel:[1,0,0] op_sel_hi:[1,1,1]
	ds_read_b64 v[42:43], v138 offset:16952
	s_waitcnt lgkmcnt(15)
	v_pk_fma_f32 v[12:13], v[44:45], v[124:125], v[12:13] op_sel_hi:[0,1,1]
	v_pk_fma_f32 v[12:13], v[44:45], v[126:127], v[12:13] op_sel:[1,0,0] op_sel_hi:[1,1,1]
	ds_read_b64 v[44:45], v138 offset:21176
	s_waitcnt lgkmcnt(15)
	v_pk_fma_f32 v[14:15], v[46:47], v[124:125], v[14:15] op_sel_hi:[0,1,1]
	v_pk_fma_f32 v[14:15], v[46:47], v[126:127], v[14:15] op_sel:[1,0,0] op_sel_hi:[1,1,1]
	ds_read_b64 v[46:47], v138 offset:25400
	s_waitcnt lgkmcnt(15)
	v_pk_fma_f32 v[16:17], v[48:49], v[124:125], v[16:17] op_sel_hi:[0,1,1]
	v_pk_fma_f32 v[16:17], v[48:49], v[126:127], v[16:17] op_sel:[1,0,0] op_sel_hi:[1,1,1]
	ds_read_b64 v[48:49], v138 offset:29624
	s_waitcnt lgkmcnt(15)
	v_pk_fma_f32 v[18:19], v[84:85], v[124:125], v[18:19] op_sel_hi:[0,1,1]
	v_pk_fma_f32 v[18:19], v[84:85], v[126:127], v[18:19] op_sel:[1,0,0] op_sel_hi:[1,1,1]
	ds_read_b64 v[84:85], v138 offset:33848
	s_waitcnt lgkmcnt(15)
	v_pk_fma_f32 v[20:21], v[86:87], v[124:125], v[20:21] op_sel_hi:[0,1,1]
	v_pk_fma_f32 v[20:21], v[86:87], v[126:127], v[20:21] op_sel:[1,0,0] op_sel_hi:[1,1,1]
	ds_read_b64 v[86:87], v138 offset:38072
	s_waitcnt lgkmcnt(15)
	v_pk_fma_f32 v[22:23], v[88:89], v[124:125], v[22:23] op_sel_hi:[0,1,1]
	v_pk_fma_f32 v[22:23], v[88:89], v[126:127], v[22:23] op_sel:[1,0,0] op_sel_hi:[1,1,1]
	ds_read_b64 v[88:89], v138 offset:42296
	s_waitcnt lgkmcnt(15)
	v_pk_fma_f32 v[24:25], v[90:91], v[124:125], v[24:25] op_sel_hi:[0,1,1]
	v_pk_fma_f32 v[24:25], v[90:91], v[126:127], v[24:25] op_sel:[1,0,0] op_sel_hi:[1,1,1]
	ds_read_b64 v[90:91], v138 offset:46520
	s_waitcnt lgkmcnt(15)
	v_pk_fma_f32 v[26:27], v[92:93], v[124:125], v[26:27] op_sel_hi:[0,1,1]
	v_pk_fma_f32 v[26:27], v[92:93], v[126:127], v[26:27] op_sel:[1,0,0] op_sel_hi:[1,1,1]
	ds_read_b64 v[92:93], v138 offset:50744
	s_waitcnt lgkmcnt(15)
	v_pk_fma_f32 v[28:29], v[94:95], v[124:125], v[28:29] op_sel_hi:[0,1,1]
	v_pk_fma_f32 v[28:29], v[94:95], v[126:127], v[28:29] op_sel:[1,0,0] op_sel_hi:[1,1,1]
	ds_read_b64 v[94:95], v138 offset:54968
	s_waitcnt lgkmcnt(15)
	v_pk_fma_f32 v[30:31], v[96:97], v[124:125], v[30:31] op_sel_hi:[0,1,1]
	v_pk_fma_f32 v[30:31], v[96:97], v[126:127], v[30:31] op_sel:[1,0,0] op_sel_hi:[1,1,1]
	ds_read_b64 v[96:97], v138 offset:59192
	s_waitcnt lgkmcnt(15)
	v_pk_fma_f32 v[32:33], v[98:99], v[124:125], v[32:33] op_sel_hi:[0,1,1]
	v_pk_fma_f32 v[32:33], v[98:99], v[126:127], v[32:33] op_sel:[1,0,0] op_sel_hi:[1,1,1]
	ds_read_b64 v[98:99], v138 offset:63416
	s_waitcnt vmcnt(2)
	s_waitcnt lgkmcnt(15)
	v_pk_fma_f32 v[2:3], v[34:35], v[128:129], v[2:3] op_sel_hi:[0,1,1]
	v_pk_fma_f32 v[2:3], v[34:35], v[130:131], v[2:3] op_sel:[1,0,0] op_sel_hi:[1,1,1]
	ds_read_b64 v[34:35], v139 offset:0
	s_waitcnt lgkmcnt(15)
	v_pk_fma_f32 v[4:5], v[36:37], v[128:129], v[4:5] op_sel_hi:[0,1,1]
	v_pk_fma_f32 v[4:5], v[36:37], v[130:131], v[4:5] op_sel:[1,0,0] op_sel_hi:[1,1,1]
	ds_read_b64 v[36:37], v139 offset:4224
	s_waitcnt lgkmcnt(15)
	v_pk_fma_f32 v[6:7], v[38:39], v[128:129], v[6:7] op_sel_hi:[0,1,1]
	v_pk_fma_f32 v[6:7], v[38:39], v[130:131], v[6:7] op_sel:[1,0,0] op_sel_hi:[1,1,1]
	ds_read_b64 v[38:39], v139 offset:8448
	s_waitcnt lgkmcnt(15)
	v_pk_fma_f32 v[8:9], v[40:41], v[128:129], v[8:9] op_sel_hi:[0,1,1]
	v_pk_fma_f32 v[8:9], v[40:41], v[130:131], v[8:9] op_sel:[1,0,0] op_sel_hi:[1,1,1]
	ds_read_b64 v[40:41], v139 offset:12672
	s_waitcnt lgkmcnt(15)
	v_pk_fma_f32 v[10:11], v[42:43], v[128:129], v[10:11] op_sel_hi:[0,1,1]
	v_pk_fma_f32 v[10:11], v[42:43], v[130:131], v[10:11] op_sel:[1,0,0] op_sel_hi:[1,1,1]
	ds_read_b64 v[42:43], v139 offset:16896
	s_waitcnt lgkmcnt(15)
	v_pk_fma_f32 v[12:13], v[44:45], v[128:129], v[12:13] op_sel_hi:[0,1,1]
	v_pk_fma_f32 v[12:13], v[44:45], v[130:131], v[12:13] op_sel:[1,0,0] op_sel_hi:[1,1,1]
	ds_read_b64 v[44:45], v139 offset:21120
	s_waitcnt lgkmcnt(15)
	v_pk_fma_f32 v[14:15], v[46:47], v[128:129], v[14:15] op_sel_hi:[0,1,1]
	v_pk_fma_f32 v[14:15], v[46:47], v[130:131], v[14:15] op_sel:[1,0,0] op_sel_hi:[1,1,1]
	ds_read_b64 v[46:47], v139 offset:25344
	s_waitcnt lgkmcnt(15)
	v_pk_fma_f32 v[16:17], v[48:49], v[128:129], v[16:17] op_sel_hi:[0,1,1]
	v_pk_fma_f32 v[16:17], v[48:49], v[130:131], v[16:17] op_sel:[1,0,0] op_sel_hi:[1,1,1]
	ds_read_b64 v[48:49], v139 offset:29568
	s_waitcnt lgkmcnt(15)
	v_pk_fma_f32 v[18:19], v[84:85], v[128:129], v[18:19] op_sel_hi:[0,1,1]
	v_pk_fma_f32 v[18:19], v[84:85], v[130:131], v[18:19] op_sel:[1,0,0] op_sel_hi:[1,1,1]
	ds_read_b64 v[84:85], v139 offset:33792
	s_waitcnt lgkmcnt(15)
	v_pk_fma_f32 v[20:21], v[86:87], v[128:129], v[20:21] op_sel_hi:[0,1,1]
	v_pk_fma_f32 v[20:21], v[86:87], v[130:131], v[20:21] op_sel:[1,0,0] op_sel_hi:[1,1,1]
	ds_read_b64 v[86:87], v139 offset:38016
	s_waitcnt lgkmcnt(15)
; template <int BR>
; __device__ __forceinline__ void sample_unit(const SampP& P, int bs, int h, char* lds, float lam) {
;     ...
;       for (int e = 0; e < 5; ++e) { const float* sp = S1 + keyb + 2 * e;
; #pragma unroll
;         for (int q = 0; q < 16; ++q) acc[q] += sp[q * SST] * v[e];
;         asm volatile("" ::: "memory"); }
;     }
; #pragma unroll
;     for (int q = 0; q < 16; ++q) {
; #pragma unroll
;       for (int i = 0; i < 4; ++i) acc[q][i] += __shfl_xor(acc[q][i], 32); }
;     __syncthreads();
;     if (hf == 0) {
; #pragma unroll
;       for (int q = 0; q < 16; ++q) *(f32x4*)(red + (wid * 16 + q) * 128 + 4 * l31) = acc[q]; }
	v_pk_fma_f32 v[22:23], v[88:89], v[128:129], v[22:23] op_sel_hi:[0,1,1]
	v_pk_fma_f32 v[22:23], v[88:89], v[130:131], v[22:23] op_sel:[1,0,0] op_sel_hi:[1,1,1]
	ds_read_b64 v[88:89], v139 offset:42240
	s_waitcnt lgkmcnt(15)
	v_pk_fma_f32 v[24:25], v[90:91], v[128:129], v[24:25] op_sel_hi:[0,1,1]
	v_pk_fma_f32 v[24:25], v[90:91], v[130:131], v[24:25] op_sel:[1,0,0] op_sel_hi:[1,1,1]
	ds_read_b64 v[90:91], v139 offset:46464
	s_waitcnt lgkmcnt(15)
	v_pk_fma_f32 v[26:27], v[92:93], v[128:129], v[26:27] op_sel_hi:[0,1,1]
	v_pk_fma_f32 v[26:27], v[92:93], v[130:131], v[26:27] op_sel:[1,0,0] op_sel_hi:[1,1,1]
	ds_read_b64 v[92:93], v139 offset:50688
	s_waitcnt lgkmcnt(15)
	v_pk_fma_f32 v[28:29], v[94:95], v[128:129], v[28:29] op_sel_hi:[0,1,1]
	v_pk_fma_f32 v[28:29], v[94:95], v[130:131], v[28:29] op_sel:[1,0,0] op_sel_hi:[1,1,1]
	ds_read_b64 v[94:95], v139 offset:54912
	s_waitcnt lgkmcnt(15)
	v_pk_fma_f32 v[30:31], v[96:97], v[128:129], v[30:31] op_sel_hi:[0,1,1]
	v_pk_fma_f32 v[30:31], v[96:97], v[130:131], v[30:31] op_sel:[1,0,0] op_sel_hi:[1,1,1]
	ds_read_b64 v[96:97], v139 offset:59136
	s_waitcnt lgkmcnt(15)
	v_pk_fma_f32 v[32:33], v[98:99], v[128:129], v[32:33] op_sel_hi:[0,1,1]
	v_pk_fma_f32 v[32:33], v[98:99], v[130:131], v[32:33] op_sel:[1,0,0] op_sel_hi:[1,1,1]
	ds_read_b64 v[98:99], v139 offset:63360
	s_waitcnt vmcnt(0)
	v_lshlrev_b32_e32 v144, 16, v141
	v_and_b32_e32 v145, 0xffff0000, v141
	v_lshlrev_b32_e32 v146, 16, v142
	v_and_b32_e32 v147, 0xffff0000, v142
	s_waitcnt lgkmcnt(15)
	v_pk_fma_f32 v[2:3], v[34:35], v[144:145], v[2:3] op_sel_hi:[0,1,1]
	v_pk_fma_f32 v[2:3], v[34:35], v[146:147], v[2:3] op_sel:[1,0,0] op_sel_hi:[1,1,1]
	s_waitcnt lgkmcnt(14)
	v_pk_fma_f32 v[4:5], v[36:37], v[144:145], v[4:5] op_sel_hi:[0,1,1]
	v_pk_fma_f32 v[4:5], v[36:37], v[146:147], v[4:5] op_sel:[1,0,0] op_sel_hi:[1,1,1]
	s_waitcnt lgkmcnt(13)
	v_pk_fma_f32 v[6:7], v[38:39], v[144:145], v[6:7] op_sel_hi:[0,1,1]
	v_pk_fma_f32 v[6:7], v[38:39], v[146:147], v[6:7] op_sel:[1,0,0] op_sel_hi:[1,1,1]
	s_waitcnt lgkmcnt(12)
	v_pk_fma_f32 v[8:9], v[40:41], v[144:145], v[8:9] op_sel_hi:[0,1,1]
	v_pk_fma_f32 v[8:9], v[40:41], v[146:147], v[8:9] op_sel:[1,0,0] op_sel_hi:[1,1,1]
	s_waitcnt lgkmcnt(11)
	v_pk_fma_f32 v[10:11], v[42:43], v[144:145], v[10:11] op_sel_hi:[0,1,1]
	v_pk_fma_f32 v[10:11], v[42:43], v[146:147], v[10:11] op_sel:[1,0,0] op_sel_hi:[1,1,1]
	s_waitcnt lgkmcnt(10)
	v_pk_fma_f32 v[12:13], v[44:45], v[144:145], v[12:13] op_sel_hi:[0,1,1]
	v_pk_fma_f32 v[12:13], v[44:45], v[146:147], v[12:13] op_sel:[1,0,0] op_sel_hi:[1,1,1]
	s_waitcnt lgkmcnt(9)
	v_pk_fma_f32 v[14:15], v[46:47], v[144:145], v[14:15] op_sel_hi:[0,1,1]
	v_pk_fma_f32 v[14:15], v[46:47], v[146:147], v[14:15] op_sel:[1,0,0] op_sel_hi:[1,1,1]
	s_waitcnt lgkmcnt(8)
	v_pk_fma_f32 v[16:17], v[48:49], v[144:145], v[16:17] op_sel_hi:[0,1,1]
	v_pk_fma_f32 v[16:17], v[48:49], v[146:147], v[16:17] op_sel:[1,0,0] op_sel_hi:[1,1,1]
	s_waitcnt lgkmcnt(7)
	v_pk_fma_f32 v[18:19], v[84:85], v[144:145], v[18:19] op_sel_hi:[0,1,1]
	v_pk_fma_f32 v[18:19], v[84:85], v[146:147], v[18:19] op_sel:[1,0,0] op_sel_hi:[1,1,1]
	s_waitcnt lgkmcnt(6)
	v_pk_fma_f32 v[20:21], v[86:87], v[144:145], v[20:21] op_sel_hi:[0,1,1]
	v_pk_fma_f32 v[20:21], v[86:87], v[146:147], v[20:21] op_sel:[1,0,0] op_sel_hi:[1,1,1]
	s_waitcnt lgkmcnt(5)
	v_pk_fma_f32 v[22:23], v[88:89], v[144:145], v[22:23] op_sel_hi:[0,1,1]
	v_pk_fma_f32 v[22:23], v[88:89], v[146:147], v[22:23] op_sel:[1,0,0] op_sel_hi:[1,1,1]
	s_waitcnt lgkmcnt(4)
	v_pk_fma_f32 v[24:25], v[90:91], v[144:145], v[24:25] op_sel_hi:[0,1,1]
	v_pk_fma_f32 v[24:25], v[90:91], v[146:147], v[24:25] op_sel:[1,0,0] op_sel_hi:[1,1,1]
	s_waitcnt lgkmcnt(3)
	v_pk_fma_f32 v[26:27], v[92:93], v[144:145], v[26:27] op_sel_hi:[0,1,1]
	v_pk_fma_f32 v[26:27], v[92:93], v[146:147], v[26:27] op_sel:[1,0,0] op_sel_hi:[1,1,1]
	s_waitcnt lgkmcnt(2)
	v_pk_fma_f32 v[28:29], v[94:95], v[144:145], v[28:29] op_sel_hi:[0,1,1]
	v_pk_fma_f32 v[28:29], v[94:95], v[146:147], v[28:29] op_sel:[1,0,0] op_sel_hi:[1,1,1]
	s_waitcnt lgkmcnt(1)
	v_pk_fma_f32 v[30:31], v[96:97], v[144:145], v[30:31] op_sel_hi:[0,1,1]
	v_pk_fma_f32 v[30:31], v[96:97], v[146:147], v[30:31] op_sel:[1,0,0] op_sel_hi:[1,1,1]
	s_waitcnt lgkmcnt(0)
	v_pk_fma_f32 v[32:33], v[98:99], v[144:145], v[32:33] op_sel_hi:[0,1,1]
	v_pk_fma_f32 v[32:33], v[98:99], v[146:147], v[32:33] op_sel:[1,0,0] op_sel_hi:[1,1,1]
	ds_write_b64 v140, v[2:3] offset:0
	ds_write_b64 v140, v[4:5] offset:512
	ds_write_b64 v140, v[6:7] offset:1024
	ds_write_b64 v140, v[8:9] offset:1536
	ds_write_b64 v140, v[10:11] offset:2048
	ds_write_b64 v140, v[12:13] offset:2560
	ds_write_b64 v140, v[14:15] offset:3072
	ds_write_b64 v140, v[16:17] offset:3584
	ds_write_b64 v140, v[18:19] offset:4096
	ds_write_b64 v140, v[20:21] offset:4608
	ds_write_b64 v140, v[22:23] offset:5120
	ds_write_b64 v140, v[24:25] offset:5632
	ds_write_b64 v140, v[26:27] offset:6144
	ds_write_b64 v140, v[28:29] offset:6656
	ds_write_b64 v140, v[30:31] offset:7168
	ds_write_b64 v140, v[32:33] offset:7680
	s_branch .LBB0_409
